# v40 + every K-loop MFMA run 8-byte aligned, K-loop heads 64B aligned
# speedup vs baseline: 1.0026x; 1.0026x over previous
.LBB0_393:
	s_ashr_i32 s19, s18, 31
	s_lshl_b64 s[0:1], s[18:19], 20
	s_add_u32 s20, s42, s0
	s_addc_u32 s21, s43, s1
	s_and_b64 s[0:1], s[4:5], exec
	s_cselect_b32 s7, s21, s25
	s_cselect_b32 s19, s20, s24
	s_ashr_i32 s17, s16, 31
	s_lshl_b64 s[0:1], s[16:17], 20
	s_add_u32 s22, s30, s0
	s_addc_u32 s23, s31, s1
	s_and_b64 s[0:1], s[4:5], exec
	s_cselect_b32 s17, s23, s27
	s_cselect_b32 s49, s22, s26
	s_add_u32 s24, s24, 0x80080
	s_addc_u32 s25, s25, 0
	s_add_u32 s58, s26, 0x100
	v_mov_b32_e32 v2, 0
	s_addc_u32 s59, s27, 0
	s_mov_b32 s60, -2
	v_mov_b32_e32 v3, v2
	s_waitcnt lgkmcnt(0)
	v_pk_mov_b32 v[4:5], v[2:3], v[2:3] op_sel:[0,1]
	v_pk_mov_b32 v[6:7], v[2:3], v[2:3] op_sel:[0,1]
	v_pk_mov_b32 v[8:9], v[2:3], v[2:3] op_sel:[0,1]
	v_pk_mov_b32 v[18:19], v[2:3], v[2:3] op_sel:[0,1]
	v_pk_mov_b32 v[20:21], v[2:3], v[2:3] op_sel:[0,1]
	v_pk_mov_b32 v[22:23], v[2:3], v[2:3] op_sel:[0,1]
	v_pk_mov_b32 v[24:25], v[2:3], v[2:3] op_sel:[0,1]
	v_pk_mov_b32 v[34:35], v[2:3], v[2:3] op_sel:[0,1]
	v_pk_mov_b32 v[36:37], v[2:3], v[2:3] op_sel:[0,1]
	v_pk_mov_b32 v[38:39], v[2:3], v[2:3] op_sel:[0,1]
	v_pk_mov_b32 v[40:41], v[2:3], v[2:3] op_sel:[0,1]
	v_pk_mov_b32 v[50:51], v[2:3], v[2:3] op_sel:[0,1]
	v_pk_mov_b32 v[52:53], v[2:3], v[2:3] op_sel:[0,1]
	v_pk_mov_b32 v[54:55], v[2:3], v[2:3] op_sel:[0,1]
	v_pk_mov_b32 v[56:57], v[2:3], v[2:3] op_sel:[0,1]
	v_pk_mov_b32 v[10:11], v[2:3], v[2:3] op_sel:[0,1]
	v_pk_mov_b32 v[12:13], v[2:3], v[2:3] op_sel:[0,1]
	v_pk_mov_b32 v[14:15], v[2:3], v[2:3] op_sel:[0,1]
	v_pk_mov_b32 v[16:17], v[2:3], v[2:3] op_sel:[0,1]
	v_pk_mov_b32 v[26:27], v[2:3], v[2:3] op_sel:[0,1]
	v_pk_mov_b32 v[28:29], v[2:3], v[2:3] op_sel:[0,1]
	v_pk_mov_b32 v[30:31], v[2:3], v[2:3] op_sel:[0,1]
	v_pk_mov_b32 v[32:33], v[2:3], v[2:3] op_sel:[0,1]
	v_pk_mov_b32 v[42:43], v[2:3], v[2:3] op_sel:[0,1]
	v_pk_mov_b32 v[44:45], v[2:3], v[2:3] op_sel:[0,1]
	v_pk_mov_b32 v[46:47], v[2:3], v[2:3] op_sel:[0,1]
	v_pk_mov_b32 v[48:49], v[2:3], v[2:3] op_sel:[0,1]
	v_pk_mov_b32 v[58:59], v[2:3], v[2:3] op_sel:[0,1]
	v_pk_mov_b32 v[60:61], v[2:3], v[2:3] op_sel:[0,1]
	v_pk_mov_b32 v[62:63], v[2:3], v[2:3] op_sel:[0,1]
	v_pk_mov_b32 v[64:65], v[2:3], v[2:3] op_sel:[0,1]
	v_pk_mov_b32 v[66:67], v[2:3], v[2:3] op_sel:[0,1]
	v_pk_mov_b32 v[68:69], v[2:3], v[2:3] op_sel:[0,1]
	v_pk_mov_b32 v[70:71], v[2:3], v[2:3] op_sel:[0,1]
	v_pk_mov_b32 v[72:73], v[2:3], v[2:3] op_sel:[0,1]
	v_pk_mov_b32 v[82:83], v[2:3], v[2:3] op_sel:[0,1]
	v_pk_mov_b32 v[84:85], v[2:3], v[2:3] op_sel:[0,1]
	v_pk_mov_b32 v[86:87], v[2:3], v[2:3] op_sel:[0,1]
	v_pk_mov_b32 v[88:89], v[2:3], v[2:3] op_sel:[0,1]
	v_pk_mov_b32 v[98:99], v[2:3], v[2:3] op_sel:[0,1]
	v_pk_mov_b32 v[100:101], v[2:3], v[2:3] op_sel:[0,1]
	v_pk_mov_b32 v[102:103], v[2:3], v[2:3] op_sel:[0,1]
	v_pk_mov_b32 v[104:105], v[2:3], v[2:3] op_sel:[0,1]
	v_pk_mov_b32 v[114:115], v[2:3], v[2:3] op_sel:[0,1]
	v_pk_mov_b32 v[116:117], v[2:3], v[2:3] op_sel:[0,1]
	v_pk_mov_b32 v[118:119], v[2:3], v[2:3] op_sel:[0,1]
	v_pk_mov_b32 v[120:121], v[2:3], v[2:3] op_sel:[0,1]
	v_pk_mov_b32 v[74:75], v[2:3], v[2:3] op_sel:[0,1]
	v_pk_mov_b32 v[76:77], v[2:3], v[2:3] op_sel:[0,1]
	v_pk_mov_b32 v[78:79], v[2:3], v[2:3] op_sel:[0,1]
	v_pk_mov_b32 v[80:81], v[2:3], v[2:3] op_sel:[0,1]
	v_pk_mov_b32 v[90:91], v[2:3], v[2:3] op_sel:[0,1]
	v_pk_mov_b32 v[92:93], v[2:3], v[2:3] op_sel:[0,1]
	v_pk_mov_b32 v[94:95], v[2:3], v[2:3] op_sel:[0,1]
	v_pk_mov_b32 v[96:97], v[2:3], v[2:3] op_sel:[0,1]
	v_pk_mov_b32 v[106:107], v[2:3], v[2:3] op_sel:[0,1]
	v_pk_mov_b32 v[108:109], v[2:3], v[2:3] op_sel:[0,1]
	v_pk_mov_b32 v[110:111], v[2:3], v[2:3] op_sel:[0,1]
	v_pk_mov_b32 v[112:113], v[2:3], v[2:3] op_sel:[0,1]
	v_pk_mov_b32 v[122:123], v[2:3], v[2:3] op_sel:[0,1]
	v_pk_mov_b32 v[124:125], v[2:3], v[2:3] op_sel:[0,1]
	v_pk_mov_b32 v[126:127], v[2:3], v[2:3] op_sel:[0,1]
	v_pk_mov_b32 v[128:129], v[2:3], v[2:3] op_sel:[0,1]
	.p2align 6
.LBB0_394:
	s_add_u32 s0, s24, 0xfff80080
	s_addc_u32 s1, s25, -1
	s_add_i32 s33, 0, 0x10000
	s_cmp_eq_u32 s60, 28
	s_cselect_b32 s29, s7, s1
	s_cselect_b32 s28, s19, s0
	s_cselect_b32 s27, s17, s59
	s_cselect_b32 s26, s49, s58
	s_add_i32 s55, 0, 0x14000
	ds_read_b128 v[142:145], v151
	ds_read_b128 v[146:149], v151 offset:1024
	ds_read_b128 v[154:157], v151 offset:2048
	ds_read_b128 v[158:161], v151 offset:3072
	ds_read_b128 v[162:165], v151 offset:16384
	ds_read_b128 v[166:169], v151 offset:17408
	ds_read_b128 v[170:173], v151 offset:18432
	ds_read_b128 v[174:177], v151 offset:19456
	s_add_i32 m0, s9, 0xc000
	ds_read_b128 v[178:181], v153
	ds_read_b128 v[182:185], v153 offset:1024
	ds_read_b128 v[186:189], v153 offset:2048
	ds_read_b128 v[190:193], v153 offset:3072
	ds_read_b128 v[194:197], v153 offset:4096
	ds_read_b128 v[198:201], v153 offset:5120
	ds_read_b128 v[208:211], v153 offset:6144
	ds_read_b128 v[212:215], v153 offset:7168
	global_load_lds_dwordx4 v138, s[24:25]
	s_add_i32 m0, s9, 0xe000
	s_nop 0
	global_load_lds_dwordx4 v140, s[24:25]
	.p2align 3
	s_waitcnt vmcnt(8)
	s_waitcnt lgkmcnt(0)
	s_setprio 1
	s_barrier
	v_mfma_f32_16x16x32_bf16 v[126:129], v[142:145], v[178:181], v[126:129]
	v_mfma_f32_16x16x32_bf16 v[122:125], v[154:157], v[178:181], v[122:125]
	v_mfma_f32_16x16x32_bf16 v[110:113], v[142:145], v[186:189], v[110:113]
	v_mfma_f32_16x16x32_bf16 v[106:109], v[154:157], v[186:189], v[106:109]
	v_mfma_f32_16x16x32_bf16 v[94:97], v[142:145], v[194:197], v[94:97]
	v_mfma_f32_16x16x32_bf16 v[90:93], v[154:157], v[194:197], v[90:93]
	v_mfma_f32_16x16x32_bf16 v[78:81], v[142:145], v[208:211], v[78:81]
	v_mfma_f32_16x16x32_bf16 v[74:77], v[154:157], v[208:211], v[74:77]
	v_mfma_f32_16x16x32_bf16 v[126:129], v[146:149], v[182:185], v[126:129]
	v_mfma_f32_16x16x32_bf16 v[122:125], v[158:161], v[182:185], v[122:125]
	v_mfma_f32_16x16x32_bf16 v[110:113], v[146:149], v[190:193], v[110:113]
	v_mfma_f32_16x16x32_bf16 v[106:109], v[158:161], v[190:193], v[106:109]
	v_mfma_f32_16x16x32_bf16 v[94:97], v[146:149], v[198:201], v[94:97]
	v_mfma_f32_16x16x32_bf16 v[90:93], v[158:161], v[198:201], v[90:93]
	v_mfma_f32_16x16x32_bf16 v[78:81], v[146:149], v[212:215], v[78:81]
	v_mfma_f32_16x16x32_bf16 v[74:77], v[158:161], v[212:215], v[74:77]
	v_mfma_f32_16x16x32_bf16 v[118:121], v[162:165], v[178:181], v[118:121]
	v_mfma_f32_16x16x32_bf16 v[114:117], v[170:173], v[178:181], v[114:117]
	v_mfma_f32_16x16x32_bf16 v[102:105], v[162:165], v[186:189], v[102:105]
	v_mfma_f32_16x16x32_bf16 v[98:101], v[170:173], v[186:189], v[98:101]
	v_mfma_f32_16x16x32_bf16 v[86:89], v[162:165], v[194:197], v[86:89]
	v_mfma_f32_16x16x32_bf16 v[82:85], v[170:173], v[194:197], v[82:85]
	v_mfma_f32_16x16x32_bf16 v[70:73], v[162:165], v[208:211], v[70:73]
	v_mfma_f32_16x16x32_bf16 v[66:69], v[170:173], v[208:211], v[66:69]
	v_mfma_f32_16x16x32_bf16 v[118:121], v[166:169], v[182:185], v[118:121]
	v_mfma_f32_16x16x32_bf16 v[114:117], v[174:177], v[182:185], v[114:117]
	v_mfma_f32_16x16x32_bf16 v[102:105], v[166:169], v[190:193], v[102:105]
	v_mfma_f32_16x16x32_bf16 v[98:101], v[174:177], v[190:193], v[98:101]
	v_mfma_f32_16x16x32_bf16 v[86:89], v[166:169], v[198:201], v[86:89]
	v_mfma_f32_16x16x32_bf16 v[82:85], v[174:177], v[198:201], v[82:85]
	v_mfma_f32_16x16x32_bf16 v[70:73], v[166:169], v[212:215], v[70:73]
	v_mfma_f32_16x16x32_bf16 v[66:69], v[174:177], v[212:215], v[66:69]
	s_barrier
	s_setprio 0
	s_add_i32 s0, s33, s34
	s_mov_b32 m0, s0
	ds_read_b128 v[178:181], v153 offset:16384
	ds_read_b128 v[182:185], v153 offset:17408
	ds_read_b128 v[186:189], v153 offset:18432
	ds_read_b128 v[190:193], v153 offset:19456
	ds_read_b128 v[194:197], v153 offset:20480
	ds_read_b128 v[198:201], v153 offset:21504
	ds_read_b128 v[208:211], v153 offset:22528
	ds_read_b128 v[212:215], v153 offset:23552
	global_load_lds_dwordx4 v132, s[26:27]
	s_add_i32 m0, s0, 0x2000
	s_add_u32 s0, s26, 0x80000
	s_addc_u32 s1, s27, 0
	s_add_i32 s33, s55, s34
	global_load_lds_dwordx4 v136, s[26:27]
	s_mov_b32 m0, s33
	s_nop 0
	global_load_lds_dwordx4 v132, s[0:1]
	s_add_i32 m0, s33, 0x2000
	s_nop 0
	global_load_lds_dwordx4 v136, s[0:1]
	s_mov_b32 m0, s9
	s_nop 0
	global_load_lds_dwordx4 v130, s[28:29]
	s_mov_b32 m0, s35
	s_nop 0
	global_load_lds_dwordx4 v134, s[28:29]
	.p2align 3
	s_waitcnt vmcnt(8)
	s_waitcnt lgkmcnt(0)
	s_setprio 1
	s_barrier
	v_mfma_f32_16x16x32_bf16 v[62:65], v[142:145], v[178:181], v[62:65]
	v_mfma_f32_16x16x32_bf16 v[58:61], v[154:157], v[178:181], v[58:61]
	v_mfma_f32_16x16x32_bf16 v[46:49], v[142:145], v[186:189], v[46:49]
	v_mfma_f32_16x16x32_bf16 v[42:45], v[154:157], v[186:189], v[42:45]
	v_mfma_f32_16x16x32_bf16 v[30:33], v[142:145], v[194:197], v[30:33]
	v_mfma_f32_16x16x32_bf16 v[26:29], v[154:157], v[194:197], v[26:29]
	v_mfma_f32_16x16x32_bf16 v[14:17], v[142:145], v[208:211], v[14:17]
	v_mfma_f32_16x16x32_bf16 v[10:13], v[154:157], v[208:211], v[10:13]
	v_mfma_f32_16x16x32_bf16 v[62:65], v[146:149], v[182:185], v[62:65]
	v_mfma_f32_16x16x32_bf16 v[58:61], v[158:161], v[182:185], v[58:61]
	v_mfma_f32_16x16x32_bf16 v[46:49], v[146:149], v[190:193], v[46:49]
	v_mfma_f32_16x16x32_bf16 v[42:45], v[158:161], v[190:193], v[42:45]
	v_mfma_f32_16x16x32_bf16 v[30:33], v[146:149], v[198:201], v[30:33]
	v_mfma_f32_16x16x32_bf16 v[26:29], v[158:161], v[198:201], v[26:29]
	v_mfma_f32_16x16x32_bf16 v[14:17], v[146:149], v[212:215], v[14:17]
	v_mfma_f32_16x16x32_bf16 v[10:13], v[158:161], v[212:215], v[10:13]
	v_mfma_f32_16x16x32_bf16 v[54:57], v[162:165], v[178:181], v[54:57]
	v_mfma_f32_16x16x32_bf16 v[50:53], v[170:173], v[178:181], v[50:53]
	v_mfma_f32_16x16x32_bf16 v[38:41], v[162:165], v[186:189], v[38:41]
	v_mfma_f32_16x16x32_bf16 v[34:37], v[170:173], v[186:189], v[34:37]
	v_mfma_f32_16x16x32_bf16 v[22:25], v[162:165], v[194:197], v[22:25]
	v_mfma_f32_16x16x32_bf16 v[18:21], v[170:173], v[194:197], v[18:21]
	v_mfma_f32_16x16x32_bf16 v[6:9], v[162:165], v[208:211], v[6:9]
	v_mfma_f32_16x16x32_bf16 v[2:5], v[170:173], v[208:211], v[2:5]
	v_mfma_f32_16x16x32_bf16 v[54:57], v[166:169], v[182:185], v[54:57]
	v_mfma_f32_16x16x32_bf16 v[50:53], v[174:177], v[182:185], v[50:53]
	v_mfma_f32_16x16x32_bf16 v[38:41], v[166:169], v[190:193], v[38:41]
	v_mfma_f32_16x16x32_bf16 v[34:37], v[174:177], v[190:193], v[34:37]
	v_mfma_f32_16x16x32_bf16 v[22:25], v[166:169], v[198:201], v[22:25]
	v_mfma_f32_16x16x32_bf16 v[18:21], v[174:177], v[198:201], v[18:21]
	v_mfma_f32_16x16x32_bf16 v[6:9], v[166:169], v[212:215], v[6:9]
	v_mfma_f32_16x16x32_bf16 v[2:5], v[174:177], v[212:215], v[2:5]
	s_barrier
	s_setprio 0
	s_add_i32 s33, 0, 0x18000
	s_add_i32 s55, 0, 0x1c000
	ds_read_b128 v[142:145], v151 offset:32768
	ds_read_b128 v[146:149], v151 offset:33792
	ds_read_b128 v[154:157], v151 offset:34816
	ds_read_b128 v[158:161], v151 offset:35840
	ds_read_b128 v[162:165], v151 offset:49152
	ds_read_b128 v[166:169], v151 offset:50176
	ds_read_b128 v[170:173], v151 offset:51200
	ds_read_b128 v[174:177], v151 offset:52224
	s_add_u32 s0, s28, 0x80000
	s_addc_u32 s1, s29, 0
	s_mov_b32 m0, s36
	ds_read_b128 v[178:181], v153 offset:32768
	ds_read_b128 v[182:185], v153 offset:33792
	ds_read_b128 v[186:189], v153 offset:34816
	ds_read_b128 v[190:193], v153 offset:35840
	ds_read_b128 v[194:197], v153 offset:36864
	ds_read_b128 v[198:201], v153 offset:37888
	ds_read_b128 v[208:211], v153 offset:38912
	ds_read_b128 v[212:215], v153 offset:39936
	global_load_lds_dwordx4 v130, s[0:1]
	s_mov_b32 m0, s37
	s_nop 0
	global_load_lds_dwordx4 v134, s[0:1]
	.p2align 3
	s_waitcnt vmcnt(8)
	s_waitcnt lgkmcnt(0)
	s_setprio 1
	s_barrier
	v_mfma_f32_16x16x32_bf16 v[126:129], v[142:145], v[178:181], v[126:129]
	v_mfma_f32_16x16x32_bf16 v[122:125], v[154:157], v[178:181], v[122:125]
	v_mfma_f32_16x16x32_bf16 v[110:113], v[142:145], v[186:189], v[110:113]
	v_mfma_f32_16x16x32_bf16 v[106:109], v[154:157], v[186:189], v[106:109]
	v_mfma_f32_16x16x32_bf16 v[94:97], v[142:145], v[194:197], v[94:97]
	v_mfma_f32_16x16x32_bf16 v[90:93], v[154:157], v[194:197], v[90:93]
	v_mfma_f32_16x16x32_bf16 v[78:81], v[142:145], v[208:211], v[78:81]
	v_mfma_f32_16x16x32_bf16 v[74:77], v[154:157], v[208:211], v[74:77]
	v_mfma_f32_16x16x32_bf16 v[126:129], v[146:149], v[182:185], v[126:129]
	v_mfma_f32_16x16x32_bf16 v[122:125], v[158:161], v[182:185], v[122:125]
	v_mfma_f32_16x16x32_bf16 v[110:113], v[146:149], v[190:193], v[110:113]
	v_mfma_f32_16x16x32_bf16 v[106:109], v[158:161], v[190:193], v[106:109]
	v_mfma_f32_16x16x32_bf16 v[94:97], v[146:149], v[198:201], v[94:97]
	v_mfma_f32_16x16x32_bf16 v[90:93], v[158:161], v[198:201], v[90:93]
	v_mfma_f32_16x16x32_bf16 v[78:81], v[146:149], v[212:215], v[78:81]
	v_mfma_f32_16x16x32_bf16 v[74:77], v[158:161], v[212:215], v[74:77]
	v_mfma_f32_16x16x32_bf16 v[118:121], v[162:165], v[178:181], v[118:121]
	v_mfma_f32_16x16x32_bf16 v[114:117], v[170:173], v[178:181], v[114:117]
	v_mfma_f32_16x16x32_bf16 v[102:105], v[162:165], v[186:189], v[102:105]
	v_mfma_f32_16x16x32_bf16 v[98:101], v[170:173], v[186:189], v[98:101]
	v_mfma_f32_16x16x32_bf16 v[86:89], v[162:165], v[194:197], v[86:89]
	v_mfma_f32_16x16x32_bf16 v[82:85], v[170:173], v[194:197], v[82:85]
	v_mfma_f32_16x16x32_bf16 v[70:73], v[162:165], v[208:211], v[70:73]
	v_mfma_f32_16x16x32_bf16 v[66:69], v[170:173], v[208:211], v[66:69]
	v_mfma_f32_16x16x32_bf16 v[118:121], v[166:169], v[182:185], v[118:121]
	v_mfma_f32_16x16x32_bf16 v[114:117], v[174:177], v[182:185], v[114:117]
	v_mfma_f32_16x16x32_bf16 v[102:105], v[166:169], v[190:193], v[102:105]
	v_mfma_f32_16x16x32_bf16 v[98:101], v[174:177], v[190:193], v[98:101]
	v_mfma_f32_16x16x32_bf16 v[86:89], v[166:169], v[198:201], v[86:89]
	v_mfma_f32_16x16x32_bf16 v[82:85], v[174:177], v[198:201], v[82:85]
	v_mfma_f32_16x16x32_bf16 v[70:73], v[166:169], v[212:215], v[70:73]
	v_mfma_f32_16x16x32_bf16 v[66:69], v[174:177], v[212:215], v[66:69]
	s_barrier
	s_setprio 0
	s_add_i32 s0, s33, s34
	s_add_u32 s100, s26, 0x80
	s_addc_u32 s101, s27, 0
	s_mov_b32 m0, s0
	ds_read_b128 v[178:181], v153 offset:49152
	ds_read_b128 v[182:185], v153 offset:50176
	ds_read_b128 v[186:189], v153 offset:51200
	ds_read_b128 v[190:193], v153 offset:52224
	ds_read_b128 v[194:197], v153 offset:53248
	ds_read_b128 v[198:201], v153 offset:54272
	ds_read_b128 v[208:211], v153 offset:55296
	ds_read_b128 v[212:215], v153 offset:56320
	global_load_lds_dwordx4 v132, s[100:101]
	s_add_i32 m0, s0, 0x2000
	s_add_u32 s100, s26, 0x80
	s_addc_u32 s101, s27, 0
	s_add_u32 s0, s26, 0x80080
	s_addc_u32 s1, s27, 0
	s_add_i32 s26, s55, s34
	global_load_lds_dwordx4 v136, s[100:101]
	s_mov_b32 m0, s26
	s_nop 0
	global_load_lds_dwordx4 v132, s[0:1]
	s_add_i32 m0, s26, 0x2000
	s_nop 0
	global_load_lds_dwordx4 v136, s[0:1]
	s_add_u32 s100, s28, 0x80
	s_addc_u32 s101, s29, 0
	s_mov_b32 m0, s39
	s_nop 0
	global_load_lds_dwordx4 v130, s[100:101]
	s_add_u32 s100, s28, 0x80
	s_addc_u32 s101, s29, 0
	s_mov_b32 m0, s40
	s_nop 0
	global_load_lds_dwordx4 v134, s[100:101]
	.p2align 3
	s_waitcnt vmcnt(8)
	s_waitcnt lgkmcnt(0)
	s_setprio 1
	s_barrier
	v_mfma_f32_16x16x32_bf16 v[62:65], v[142:145], v[178:181], v[62:65]
	v_mfma_f32_16x16x32_bf16 v[58:61], v[154:157], v[178:181], v[58:61]
	v_mfma_f32_16x16x32_bf16 v[46:49], v[142:145], v[186:189], v[46:49]
	v_mfma_f32_16x16x32_bf16 v[42:45], v[154:157], v[186:189], v[42:45]
	v_mfma_f32_16x16x32_bf16 v[30:33], v[142:145], v[194:197], v[30:33]
	v_mfma_f32_16x16x32_bf16 v[26:29], v[154:157], v[194:197], v[26:29]
	v_mfma_f32_16x16x32_bf16 v[14:17], v[142:145], v[208:211], v[14:17]
	v_mfma_f32_16x16x32_bf16 v[10:13], v[154:157], v[208:211], v[10:13]
	v_mfma_f32_16x16x32_bf16 v[62:65], v[146:149], v[182:185], v[62:65]
	v_mfma_f32_16x16x32_bf16 v[58:61], v[158:161], v[182:185], v[58:61]
	v_mfma_f32_16x16x32_bf16 v[46:49], v[146:149], v[190:193], v[46:49]
	v_mfma_f32_16x16x32_bf16 v[42:45], v[158:161], v[190:193], v[42:45]
	v_mfma_f32_16x16x32_bf16 v[30:33], v[146:149], v[198:201], v[30:33]
	v_mfma_f32_16x16x32_bf16 v[26:29], v[158:161], v[198:201], v[26:29]
	v_mfma_f32_16x16x32_bf16 v[14:17], v[146:149], v[212:215], v[14:17]
	v_mfma_f32_16x16x32_bf16 v[10:13], v[158:161], v[212:215], v[10:13]
	v_mfma_f32_16x16x32_bf16 v[54:57], v[162:165], v[178:181], v[54:57]
	v_mfma_f32_16x16x32_bf16 v[50:53], v[170:173], v[178:181], v[50:53]
	v_mfma_f32_16x16x32_bf16 v[38:41], v[162:165], v[186:189], v[38:41]
	v_mfma_f32_16x16x32_bf16 v[34:37], v[170:173], v[186:189], v[34:37]
	v_mfma_f32_16x16x32_bf16 v[22:25], v[162:165], v[194:197], v[22:25]
	v_mfma_f32_16x16x32_bf16 v[18:21], v[170:173], v[194:197], v[18:21]
	v_mfma_f32_16x16x32_bf16 v[6:9], v[162:165], v[208:211], v[6:9]
	v_mfma_f32_16x16x32_bf16 v[2:5], v[170:173], v[208:211], v[2:5]
	v_mfma_f32_16x16x32_bf16 v[54:57], v[166:169], v[182:185], v[54:57]
	v_mfma_f32_16x16x32_bf16 v[50:53], v[174:177], v[182:185], v[50:53]
	v_mfma_f32_16x16x32_bf16 v[38:41], v[166:169], v[190:193], v[38:41]
	v_mfma_f32_16x16x32_bf16 v[34:37], v[174:177], v[190:193], v[34:37]
	v_mfma_f32_16x16x32_bf16 v[22:25], v[166:169], v[198:201], v[22:25]
	v_mfma_f32_16x16x32_bf16 v[18:21], v[174:177], v[198:201], v[18:21]
	v_mfma_f32_16x16x32_bf16 v[6:9], v[166:169], v[212:215], v[6:9]
	v_mfma_f32_16x16x32_bf16 v[2:5], v[174:177], v[212:215], v[2:5]
	s_barrier
	s_setprio 0
	s_add_i32 s60, s60, 2
	s_add_u32 s24, s24, 0x100
	s_addc_u32 s25, s25, 0
	s_add_u32 s58, s58, 0x100
	s_addc_u32 s59, s59, 0
	s_cmp_gt_u32 s60, 29
	s_cbranch_scc0 .LBB0_394
	s_and_b64 vcc, exec, s[14:15]
	s_cbranch_vccz .LBB0_397
	s_barrier

.LBB0_691:
	s_ashr_i32 s11, s10, 31
	s_lshl_b64 s[0:1], s[10:11], 21
	s_add_u32 s14, s78, s0
	s_addc_u32 s15, s79, s1
	s_and_b64 s[0:1], s[2:3], exec
	s_cselect_b32 s11, s15, s19
	s_cselect_b32 s49, s14, s18
	s_ashr_i32 s9, s8, 31
	s_lshl_b64 s[0:1], s[8:9], 21
	s_add_u32 s16, s24, s0
	s_addc_u32 s17, s25, s1
	s_and_b64 s[0:1], s[2:3], exec
	s_cselect_b32 s9, s17, s21
	s_cselect_b32 s58, s16, s20
	s_add_u32 s18, s18, 0x100080
	s_addc_u32 s19, s19, 0
	s_add_u32 s59, s20, 0x100
	v_mov_b32_e32 v2, 0
	s_addc_u32 s60, s21, 0
	s_mov_b32 s61, -2
	v_mov_b32_e32 v3, v2
	v_pk_mov_b32 v[4:5], v[2:3], v[2:3] op_sel:[0,1]
	v_pk_mov_b32 v[6:7], v[2:3], v[2:3] op_sel:[0,1]
	v_pk_mov_b32 v[8:9], v[2:3], v[2:3] op_sel:[0,1]
	v_pk_mov_b32 v[18:19], v[2:3], v[2:3] op_sel:[0,1]
	v_pk_mov_b32 v[20:21], v[2:3], v[2:3] op_sel:[0,1]
	v_pk_mov_b32 v[22:23], v[2:3], v[2:3] op_sel:[0,1]
	v_pk_mov_b32 v[24:25], v[2:3], v[2:3] op_sel:[0,1]
	v_pk_mov_b32 v[34:35], v[2:3], v[2:3] op_sel:[0,1]
	v_pk_mov_b32 v[36:37], v[2:3], v[2:3] op_sel:[0,1]
	v_pk_mov_b32 v[38:39], v[2:3], v[2:3] op_sel:[0,1]
	v_pk_mov_b32 v[40:41], v[2:3], v[2:3] op_sel:[0,1]
	v_pk_mov_b32 v[50:51], v[2:3], v[2:3] op_sel:[0,1]
	v_pk_mov_b32 v[52:53], v[2:3], v[2:3] op_sel:[0,1]
	v_pk_mov_b32 v[54:55], v[2:3], v[2:3] op_sel:[0,1]
	v_pk_mov_b32 v[56:57], v[2:3], v[2:3] op_sel:[0,1]
	v_pk_mov_b32 v[10:11], v[2:3], v[2:3] op_sel:[0,1]
	v_pk_mov_b32 v[12:13], v[2:3], v[2:3] op_sel:[0,1]
	v_pk_mov_b32 v[14:15], v[2:3], v[2:3] op_sel:[0,1]
	v_pk_mov_b32 v[16:17], v[2:3], v[2:3] op_sel:[0,1]
	v_pk_mov_b32 v[26:27], v[2:3], v[2:3] op_sel:[0,1]
	v_pk_mov_b32 v[28:29], v[2:3], v[2:3] op_sel:[0,1]
	v_pk_mov_b32 v[30:31], v[2:3], v[2:3] op_sel:[0,1]
	v_pk_mov_b32 v[32:33], v[2:3], v[2:3] op_sel:[0,1]
	v_pk_mov_b32 v[42:43], v[2:3], v[2:3] op_sel:[0,1]
	v_pk_mov_b32 v[44:45], v[2:3], v[2:3] op_sel:[0,1]
	v_pk_mov_b32 v[46:47], v[2:3], v[2:3] op_sel:[0,1]
	v_pk_mov_b32 v[48:49], v[2:3], v[2:3] op_sel:[0,1]
	v_pk_mov_b32 v[58:59], v[2:3], v[2:3] op_sel:[0,1]
	v_pk_mov_b32 v[60:61], v[2:3], v[2:3] op_sel:[0,1]
	v_pk_mov_b32 v[62:63], v[2:3], v[2:3] op_sel:[0,1]
	v_pk_mov_b32 v[64:65], v[2:3], v[2:3] op_sel:[0,1]
	v_pk_mov_b32 v[66:67], v[2:3], v[2:3] op_sel:[0,1]
	v_pk_mov_b32 v[68:69], v[2:3], v[2:3] op_sel:[0,1]
	v_pk_mov_b32 v[70:71], v[2:3], v[2:3] op_sel:[0,1]
	v_pk_mov_b32 v[72:73], v[2:3], v[2:3] op_sel:[0,1]
	v_pk_mov_b32 v[90:91], v[2:3], v[2:3] op_sel:[0,1]
	v_pk_mov_b32 v[92:93], v[2:3], v[2:3] op_sel:[0,1]
	v_pk_mov_b32 v[102:103], v[2:3], v[2:3] op_sel:[0,1]
	v_pk_mov_b32 v[104:105], v[2:3], v[2:3] op_sel:[0,1]
	v_pk_mov_b32 v[122:123], v[2:3], v[2:3] op_sel:[0,1]
	v_pk_mov_b32 v[124:125], v[2:3], v[2:3] op_sel:[0,1]
	v_pk_mov_b32 v[130:131], v[2:3], v[2:3] op_sel:[0,1]
	v_pk_mov_b32 v[132:133], v[2:3], v[2:3] op_sel:[0,1]
	v_pk_mov_b32 v[150:151], v[2:3], v[2:3] op_sel:[0,1]
	v_pk_mov_b32 v[152:153], v[2:3], v[2:3] op_sel:[0,1]
	v_pk_mov_b32 v[154:155], v[2:3], v[2:3] op_sel:[0,1]
	v_pk_mov_b32 v[156:157], v[2:3], v[2:3] op_sel:[0,1]
	v_pk_mov_b32 v[74:75], v[2:3], v[2:3] op_sel:[0,1]
	v_pk_mov_b32 v[76:77], v[2:3], v[2:3] op_sel:[0,1]
	v_pk_mov_b32 v[82:83], v[2:3], v[2:3] op_sel:[0,1]
	v_pk_mov_b32 v[84:85], v[2:3], v[2:3] op_sel:[0,1]
	v_pk_mov_b32 v[114:115], v[2:3], v[2:3] op_sel:[0,1]
	v_pk_mov_b32 v[116:117], v[2:3], v[2:3] op_sel:[0,1]
	v_pk_mov_b32 v[118:119], v[2:3], v[2:3] op_sel:[0,1]
	v_pk_mov_b32 v[120:121], v[2:3], v[2:3] op_sel:[0,1]
	v_pk_mov_b32 v[138:139], v[2:3], v[2:3] op_sel:[0,1]
	v_pk_mov_b32 v[140:141], v[2:3], v[2:3] op_sel:[0,1]
	v_pk_mov_b32 v[142:143], v[2:3], v[2:3] op_sel:[0,1]
	v_pk_mov_b32 v[144:145], v[2:3], v[2:3] op_sel:[0,1]
	v_pk_mov_b32 v[162:163], v[2:3], v[2:3] op_sel:[0,1]
	v_pk_mov_b32 v[164:165], v[2:3], v[2:3] op_sel:[0,1]
	v_pk_mov_b32 v[170:171], v[2:3], v[2:3] op_sel:[0,1]
	v_pk_mov_b32 v[172:173], v[2:3], v[2:3] op_sel:[0,1]
	.p2align 6
.LBB0_692:
	s_add_u32 s0, s18, 0xfff00080
	s_addc_u32 s1, s19, -1
	s_add_i32 s33, 0, 0x10000
	s_cmp_eq_u32 s61, 60
	s_cselect_b32 s23, s11, s1
	s_cselect_b32 s22, s49, s0
	s_cselect_b32 s21, s9, s60
	s_cselect_b32 s20, s58, s59
	s_add_i32 s55, 0, 0x14000
	ds_read_b128 v[78:81], v205
	ds_read_b128 v[86:89], v205 offset:1024
	ds_read_b128 v[94:97], v205 offset:2048
	ds_read_b128 v[98:101], v205 offset:3072
	ds_read_b128 v[106:109], v205 offset:16384
	ds_read_b128 v[110:113], v205 offset:17408
	ds_read_b128 v[126:129], v205 offset:18432
	ds_read_b128 v[134:137], v205 offset:19456
	s_add_i32 m0, s27, 0xc000
	ds_read_b128 v[146:149], v239
	ds_read_b128 v[158:161], v239 offset:1024
	ds_read_b128 v[166:169], v239 offset:2048
	ds_read_b128 v[174:177], v239 offset:3072
	ds_read_b128 v[178:181], v239 offset:4096
	ds_read_b128 v[182:185], v239 offset:5120
	ds_read_b128 v[186:189], v239 offset:6144
	ds_read_b128 v[190:193], v239 offset:7168
	global_load_lds_dwordx4 v214, s[18:19]
	s_add_i32 m0, s27, 0xe000
	s_nop 0
	global_load_lds_dwordx4 v216, s[18:19]
	.p2align 3
	s_waitcnt vmcnt(8)
	s_waitcnt lgkmcnt(0)
	s_setprio 1
	s_barrier
	v_mfma_f32_16x16x32_bf16 v[170:173], v[78:81], v[146:149], v[170:173]
	v_mfma_f32_16x16x32_bf16 v[162:165], v[94:97], v[146:149], v[162:165]
	v_mfma_f32_16x16x32_bf16 v[142:145], v[78:81], v[166:169], v[142:145]
	v_mfma_f32_16x16x32_bf16 v[138:141], v[94:97], v[166:169], v[138:141]
	v_mfma_f32_16x16x32_bf16 v[118:121], v[78:81], v[178:181], v[118:121]
	v_mfma_f32_16x16x32_bf16 v[114:117], v[94:97], v[178:181], v[114:117]
	v_mfma_f32_16x16x32_bf16 v[82:85], v[78:81], v[186:189], v[82:85]
	v_mfma_f32_16x16x32_bf16 v[74:77], v[94:97], v[186:189], v[74:77]
	v_mfma_f32_16x16x32_bf16 v[170:173], v[86:89], v[158:161], v[170:173]
	v_mfma_f32_16x16x32_bf16 v[162:165], v[98:101], v[158:161], v[162:165]
	v_mfma_f32_16x16x32_bf16 v[142:145], v[86:89], v[174:177], v[142:145]
	v_mfma_f32_16x16x32_bf16 v[138:141], v[98:101], v[174:177], v[138:141]
	v_mfma_f32_16x16x32_bf16 v[118:121], v[86:89], v[182:185], v[118:121]
	v_mfma_f32_16x16x32_bf16 v[114:117], v[98:101], v[182:185], v[114:117]
	v_mfma_f32_16x16x32_bf16 v[82:85], v[86:89], v[190:193], v[82:85]
	v_mfma_f32_16x16x32_bf16 v[74:77], v[98:101], v[190:193], v[74:77]
	v_mfma_f32_16x16x32_bf16 v[154:157], v[106:109], v[146:149], v[154:157]
	v_mfma_f32_16x16x32_bf16 v[130:133], v[106:109], v[166:169], v[130:133]
	v_mfma_f32_16x16x32_bf16 v[122:125], v[126:129], v[166:169], v[122:125]
	v_mfma_f32_16x16x32_bf16 v[102:105], v[106:109], v[178:181], v[102:105]
	v_mfma_f32_16x16x32_bf16 v[90:93], v[126:129], v[178:181], v[90:93]
	v_mfma_f32_16x16x32_bf16 v[70:73], v[106:109], v[186:189], v[70:73]
	v_mfma_f32_16x16x32_bf16 v[66:69], v[126:129], v[186:189], v[66:69]
	v_mfma_f32_16x16x32_bf16 v[154:157], v[110:113], v[158:161], v[154:157]
	v_mfma_f32_16x16x32_bf16 v[146:149], v[126:129], v[146:149], v[150:153]
	v_mfma_f32_16x16x32_bf16 v[130:133], v[110:113], v[174:177], v[130:133]
	v_mfma_f32_16x16x32_bf16 v[122:125], v[134:137], v[174:177], v[122:125]
	v_mfma_f32_16x16x32_bf16 v[102:105], v[110:113], v[182:185], v[102:105]
	v_mfma_f32_16x16x32_bf16 v[90:93], v[134:137], v[182:185], v[90:93]
	v_mfma_f32_16x16x32_bf16 v[70:73], v[110:113], v[190:193], v[70:73]
	v_mfma_f32_16x16x32_bf16 v[66:69], v[134:137], v[190:193], v[66:69]
	v_mfma_f32_16x16x32_bf16 v[146:149], v[134:137], v[158:161], v[146:149]
	s_barrier
	s_setprio 0
	s_add_i32 s0, s33, s26
	s_mov_b32 m0, s0
	ds_read_b128 v[150:153], v239 offset:16384
	ds_read_b128 v[158:161], v239 offset:17408
	ds_read_b128 v[166:169], v239 offset:18432
	ds_read_b128 v[174:177], v239 offset:19456
	ds_read_b128 v[178:181], v239 offset:20480
	ds_read_b128 v[182:185], v239 offset:21504
	ds_read_b128 v[186:189], v239 offset:22528
	ds_read_b128 v[190:193], v239 offset:23552
	global_load_lds_dwordx4 v202, s[20:21]
	s_add_i32 m0, s0, 0x2000
	s_add_u32 s0, s20, 0x100000
	s_addc_u32 s1, s21, 0
	s_add_i32 s33, s55, s26
	global_load_lds_dwordx4 v208, s[20:21]
	s_mov_b32 m0, s33
	s_nop 0
	global_load_lds_dwordx4 v202, s[0:1]
	s_add_i32 m0, s33, 0x2000
	s_nop 0
	global_load_lds_dwordx4 v208, s[0:1]
	s_mov_b32 m0, s27
	s_nop 0
	global_load_lds_dwordx4 v212, s[22:23]
	s_mov_b32 m0, s28
	s_nop 0
	global_load_lds_dwordx4 v210, s[22:23]
	.p2align 3
	s_waitcnt vmcnt(8)
	s_waitcnt lgkmcnt(0)
	s_setprio 1
	s_barrier
	v_mfma_f32_16x16x32_bf16 v[62:65], v[78:81], v[150:153], v[62:65]
	v_mfma_f32_16x16x32_bf16 v[58:61], v[94:97], v[150:153], v[58:61]
	v_mfma_f32_16x16x32_bf16 v[46:49], v[78:81], v[166:169], v[46:49]
	v_mfma_f32_16x16x32_bf16 v[42:45], v[94:97], v[166:169], v[42:45]
	v_mfma_f32_16x16x32_bf16 v[30:33], v[78:81], v[178:181], v[30:33]
	v_mfma_f32_16x16x32_bf16 v[26:29], v[94:97], v[178:181], v[26:29]
	v_mfma_f32_16x16x32_bf16 v[14:17], v[78:81], v[186:189], v[14:17]
	v_mfma_f32_16x16x32_bf16 v[10:13], v[94:97], v[186:189], v[10:13]
	v_mfma_f32_16x16x32_bf16 v[62:65], v[86:89], v[158:161], v[62:65]
	v_mfma_f32_16x16x32_bf16 v[58:61], v[98:101], v[158:161], v[58:61]
	v_mfma_f32_16x16x32_bf16 v[46:49], v[86:89], v[174:177], v[46:49]
	v_mfma_f32_16x16x32_bf16 v[42:45], v[98:101], v[174:177], v[42:45]
	v_mfma_f32_16x16x32_bf16 v[30:33], v[86:89], v[182:185], v[30:33]
	v_mfma_f32_16x16x32_bf16 v[26:29], v[98:101], v[182:185], v[26:29]
	v_mfma_f32_16x16x32_bf16 v[14:17], v[86:89], v[190:193], v[14:17]
	v_mfma_f32_16x16x32_bf16 v[10:13], v[98:101], v[190:193], v[10:13]
	v_mfma_f32_16x16x32_bf16 v[54:57], v[106:109], v[150:153], v[54:57]
	v_mfma_f32_16x16x32_bf16 v[50:53], v[126:129], v[150:153], v[50:53]
	v_mfma_f32_16x16x32_bf16 v[38:41], v[106:109], v[166:169], v[38:41]
	v_mfma_f32_16x16x32_bf16 v[34:37], v[126:129], v[166:169], v[34:37]
	v_mfma_f32_16x16x32_bf16 v[22:25], v[106:109], v[178:181], v[22:25]
	v_mfma_f32_16x16x32_bf16 v[18:21], v[126:129], v[178:181], v[18:21]
	v_mfma_f32_16x16x32_bf16 v[6:9], v[106:109], v[186:189], v[6:9]
	v_mfma_f32_16x16x32_bf16 v[2:5], v[126:129], v[186:189], v[2:5]
	v_mfma_f32_16x16x32_bf16 v[54:57], v[110:113], v[158:161], v[54:57]
	v_mfma_f32_16x16x32_bf16 v[50:53], v[134:137], v[158:161], v[50:53]
	v_mfma_f32_16x16x32_bf16 v[38:41], v[110:113], v[174:177], v[38:41]
	v_mfma_f32_16x16x32_bf16 v[34:37], v[134:137], v[174:177], v[34:37]
	v_mfma_f32_16x16x32_bf16 v[22:25], v[110:113], v[182:185], v[22:25]
	v_mfma_f32_16x16x32_bf16 v[18:21], v[134:137], v[182:185], v[18:21]
	v_mfma_f32_16x16x32_bf16 v[6:9], v[110:113], v[190:193], v[6:9]
	v_mfma_f32_16x16x32_bf16 v[2:5], v[134:137], v[190:193], v[2:5]
	s_barrier
	s_setprio 0
	s_add_i32 s33, 0, 0x18000
	s_add_i32 s55, 0, 0x1c000
	ds_read_b128 v[78:81], v205 offset:32768
	ds_read_b128 v[86:89], v205 offset:33792
	ds_read_b128 v[94:97], v205 offset:34816
	ds_read_b128 v[98:101], v205 offset:35840
	ds_read_b128 v[106:109], v205 offset:49152
	ds_read_b128 v[110:113], v205 offset:50176
	ds_read_b128 v[126:129], v205 offset:51200
	ds_read_b128 v[134:137], v205 offset:52224
	s_add_u32 s0, s22, 0x100000
	s_addc_u32 s1, s23, 0
	s_mov_b32 m0, s29
	ds_read_b128 v[150:153], v239 offset:32768
	ds_read_b128 v[158:161], v239 offset:33792
	ds_read_b128 v[166:169], v239 offset:34816
	ds_read_b128 v[174:177], v239 offset:35840
	ds_read_b128 v[178:181], v239 offset:36864
	ds_read_b128 v[182:185], v239 offset:37888
	ds_read_b128 v[186:189], v239 offset:38912
	ds_read_b128 v[190:193], v239 offset:39936
	global_load_lds_dwordx4 v212, s[0:1]
	s_mov_b32 m0, s30
	s_nop 0
	global_load_lds_dwordx4 v210, s[0:1]
	.p2align 3
	s_waitcnt vmcnt(8)
	s_waitcnt lgkmcnt(0)
	s_setprio 1
	s_barrier
	v_mfma_f32_16x16x32_bf16 v[170:173], v[78:81], v[150:153], v[170:173]
	v_mfma_f32_16x16x32_bf16 v[162:165], v[94:97], v[150:153], v[162:165]
	v_mfma_f32_16x16x32_bf16 v[142:145], v[78:81], v[166:169], v[142:145]
	v_mfma_f32_16x16x32_bf16 v[138:141], v[94:97], v[166:169], v[138:141]
	v_mfma_f32_16x16x32_bf16 v[118:121], v[78:81], v[178:181], v[118:121]
	v_mfma_f32_16x16x32_bf16 v[114:117], v[94:97], v[178:181], v[114:117]
	v_mfma_f32_16x16x32_bf16 v[82:85], v[78:81], v[186:189], v[82:85]
	v_mfma_f32_16x16x32_bf16 v[74:77], v[94:97], v[186:189], v[74:77]
	v_mfma_f32_16x16x32_bf16 v[170:173], v[86:89], v[158:161], v[170:173]
	v_mfma_f32_16x16x32_bf16 v[162:165], v[98:101], v[158:161], v[162:165]
	v_mfma_f32_16x16x32_bf16 v[142:145], v[86:89], v[174:177], v[142:145]
	v_mfma_f32_16x16x32_bf16 v[138:141], v[98:101], v[174:177], v[138:141]
	v_mfma_f32_16x16x32_bf16 v[118:121], v[86:89], v[182:185], v[118:121]
	v_mfma_f32_16x16x32_bf16 v[114:117], v[98:101], v[182:185], v[114:117]
	v_mfma_f32_16x16x32_bf16 v[82:85], v[86:89], v[190:193], v[82:85]
	v_mfma_f32_16x16x32_bf16 v[74:77], v[98:101], v[190:193], v[74:77]
	v_mfma_f32_16x16x32_bf16 v[154:157], v[106:109], v[150:153], v[154:157]
	v_mfma_f32_16x16x32_bf16 v[146:149], v[126:129], v[150:153], v[146:149]
	v_mfma_f32_16x16x32_bf16 v[130:133], v[106:109], v[166:169], v[130:133]
	v_mfma_f32_16x16x32_bf16 v[122:125], v[126:129], v[166:169], v[122:125]
	v_mfma_f32_16x16x32_bf16 v[102:105], v[106:109], v[178:181], v[102:105]
	v_mfma_f32_16x16x32_bf16 v[90:93], v[126:129], v[178:181], v[90:93]
	v_mfma_f32_16x16x32_bf16 v[70:73], v[106:109], v[186:189], v[70:73]
	v_mfma_f32_16x16x32_bf16 v[66:69], v[126:129], v[186:189], v[66:69]
	v_mfma_f32_16x16x32_bf16 v[154:157], v[110:113], v[158:161], v[154:157]
	v_mfma_f32_16x16x32_bf16 v[150:153], v[134:137], v[158:161], v[146:149]
	v_mfma_f32_16x16x32_bf16 v[130:133], v[110:113], v[174:177], v[130:133]
	v_mfma_f32_16x16x32_bf16 v[122:125], v[134:137], v[174:177], v[122:125]
	v_mfma_f32_16x16x32_bf16 v[102:105], v[110:113], v[182:185], v[102:105]
	v_mfma_f32_16x16x32_bf16 v[90:93], v[134:137], v[182:185], v[90:93]
	v_mfma_f32_16x16x32_bf16 v[70:73], v[110:113], v[190:193], v[70:73]
	v_mfma_f32_16x16x32_bf16 v[66:69], v[134:137], v[190:193], v[66:69]
	s_barrier
	s_setprio 0
	s_add_i32 s0, s33, s26
	s_add_u32 s100, s20, 0x80
	s_addc_u32 s101, s21, 0
	s_mov_b32 m0, s0
	ds_read_b128 v[146:149], v239 offset:49152
	ds_read_b128 v[158:161], v239 offset:50176
	ds_read_b128 v[166:169], v239 offset:51200
	ds_read_b128 v[174:177], v239 offset:52224
	ds_read_b128 v[178:181], v239 offset:53248
	ds_read_b128 v[182:185], v239 offset:54272
	ds_read_b128 v[186:189], v239 offset:55296
	ds_read_b128 v[190:193], v239 offset:56320
	global_load_lds_dwordx4 v202, s[100:101]
	s_add_i32 m0, s0, 0x2000
	s_add_u32 s100, s20, 0x80
	s_addc_u32 s101, s21, 0
	s_add_u32 s0, s20, 0x100080
	s_addc_u32 s1, s21, 0
	s_add_i32 s20, s55, s26
	global_load_lds_dwordx4 v208, s[100:101]
	s_mov_b32 m0, s20
	s_nop 0
	global_load_lds_dwordx4 v202, s[0:1]
	s_add_i32 m0, s20, 0x2000
	s_nop 0
	global_load_lds_dwordx4 v208, s[0:1]
	s_add_u32 s100, s22, 0x80
	s_addc_u32 s101, s23, 0
	s_mov_b32 m0, s35
	s_nop 0
	global_load_lds_dwordx4 v212, s[100:101]
	s_add_u32 s100, s22, 0x80
	s_addc_u32 s101, s23, 0
	s_mov_b32 m0, s36
	s_nop 0
	global_load_lds_dwordx4 v210, s[100:101]
	.p2align 3
	s_waitcnt vmcnt(8)
	s_waitcnt lgkmcnt(0)
	s_setprio 1
	s_barrier
	v_mfma_f32_16x16x32_bf16 v[62:65], v[78:81], v[146:149], v[62:65]
	v_mfma_f32_16x16x32_bf16 v[58:61], v[94:97], v[146:149], v[58:61]
	v_mfma_f32_16x16x32_bf16 v[46:49], v[78:81], v[166:169], v[46:49]
	v_mfma_f32_16x16x32_bf16 v[42:45], v[94:97], v[166:169], v[42:45]
	v_mfma_f32_16x16x32_bf16 v[30:33], v[78:81], v[178:181], v[30:33]
	v_mfma_f32_16x16x32_bf16 v[26:29], v[94:97], v[178:181], v[26:29]
	v_mfma_f32_16x16x32_bf16 v[14:17], v[78:81], v[186:189], v[14:17]
	v_mfma_f32_16x16x32_bf16 v[10:13], v[94:97], v[186:189], v[10:13]
	v_mfma_f32_16x16x32_bf16 v[62:65], v[86:89], v[158:161], v[62:65]
	v_mfma_f32_16x16x32_bf16 v[58:61], v[98:101], v[158:161], v[58:61]
	v_mfma_f32_16x16x32_bf16 v[46:49], v[86:89], v[174:177], v[46:49]
	v_mfma_f32_16x16x32_bf16 v[42:45], v[98:101], v[174:177], v[42:45]
	v_mfma_f32_16x16x32_bf16 v[30:33], v[86:89], v[182:185], v[30:33]
	v_mfma_f32_16x16x32_bf16 v[26:29], v[98:101], v[182:185], v[26:29]
	v_mfma_f32_16x16x32_bf16 v[14:17], v[86:89], v[190:193], v[14:17]
	v_mfma_f32_16x16x32_bf16 v[10:13], v[98:101], v[190:193], v[10:13]
	v_mfma_f32_16x16x32_bf16 v[54:57], v[106:109], v[146:149], v[54:57]
	v_mfma_f32_16x16x32_bf16 v[50:53], v[126:129], v[146:149], v[50:53]
	v_mfma_f32_16x16x32_bf16 v[38:41], v[106:109], v[166:169], v[38:41]
	v_mfma_f32_16x16x32_bf16 v[34:37], v[126:129], v[166:169], v[34:37]
	v_mfma_f32_16x16x32_bf16 v[22:25], v[106:109], v[178:181], v[22:25]
	v_mfma_f32_16x16x32_bf16 v[18:21], v[126:129], v[178:181], v[18:21]
	v_mfma_f32_16x16x32_bf16 v[6:9], v[106:109], v[186:189], v[6:9]
	v_mfma_f32_16x16x32_bf16 v[2:5], v[126:129], v[186:189], v[2:5]
	v_mfma_f32_16x16x32_bf16 v[54:57], v[110:113], v[158:161], v[54:57]
	v_mfma_f32_16x16x32_bf16 v[50:53], v[134:137], v[158:161], v[50:53]
	v_mfma_f32_16x16x32_bf16 v[38:41], v[110:113], v[174:177], v[38:41]
	v_mfma_f32_16x16x32_bf16 v[34:37], v[134:137], v[174:177], v[34:37]
	v_mfma_f32_16x16x32_bf16 v[22:25], v[110:113], v[182:185], v[22:25]
	v_mfma_f32_16x16x32_bf16 v[18:21], v[134:137], v[182:185], v[18:21]
	v_mfma_f32_16x16x32_bf16 v[6:9], v[110:113], v[190:193], v[6:9]
	v_mfma_f32_16x16x32_bf16 v[2:5], v[134:137], v[190:193], v[2:5]
	s_barrier
	s_setprio 0
	s_add_i32 s61, s61, 2
	s_add_u32 s18, s18, 0x100
	s_addc_u32 s19, s19, 0
	s_add_u32 s59, s59, 0x100
	s_addc_u32 s60, s60, 0
	s_cmp_gt_u32 s61, 61
	s_cbranch_scc0 .LBB0_692
	s_and_b64 vcc, exec, s[6:7]
	s_cbranch_vccz .LBB0_695
	s_barrier

.LBB0_711:
	s_add_u32 s18, s18, 0x100080
	s_addc_u32 s19, s19, 0
	s_add_u32 s9, s20, 0x100
	v_mov_b32_e32 v2, 0
	s_addc_u32 s11, s21, 0
	s_mov_b32 s49, -2
	v_mov_b32_e32 v3, v2
	v_pk_mov_b32 v[4:5], v[2:3], v[2:3] op_sel:[0,1]
	v_pk_mov_b32 v[6:7], v[2:3], v[2:3] op_sel:[0,1]
	v_pk_mov_b32 v[8:9], v[2:3], v[2:3] op_sel:[0,1]
	v_pk_mov_b32 v[10:11], v[2:3], v[2:3] op_sel:[0,1]
	v_pk_mov_b32 v[12:13], v[2:3], v[2:3] op_sel:[0,1]
	v_pk_mov_b32 v[14:15], v[2:3], v[2:3] op_sel:[0,1]
	v_pk_mov_b32 v[16:17], v[2:3], v[2:3] op_sel:[0,1]
	v_pk_mov_b32 v[26:27], v[2:3], v[2:3] op_sel:[0,1]
	v_pk_mov_b32 v[28:29], v[2:3], v[2:3] op_sel:[0,1]
	v_pk_mov_b32 v[30:31], v[2:3], v[2:3] op_sel:[0,1]
	v_pk_mov_b32 v[32:33], v[2:3], v[2:3] op_sel:[0,1]
	v_pk_mov_b32 v[42:43], v[2:3], v[2:3] op_sel:[0,1]
	v_pk_mov_b32 v[44:45], v[2:3], v[2:3] op_sel:[0,1]
	v_pk_mov_b32 v[46:47], v[2:3], v[2:3] op_sel:[0,1]
	v_pk_mov_b32 v[48:49], v[2:3], v[2:3] op_sel:[0,1]
	v_pk_mov_b32 v[18:19], v[2:3], v[2:3] op_sel:[0,1]
	v_pk_mov_b32 v[20:21], v[2:3], v[2:3] op_sel:[0,1]
	v_pk_mov_b32 v[22:23], v[2:3], v[2:3] op_sel:[0,1]
	v_pk_mov_b32 v[24:25], v[2:3], v[2:3] op_sel:[0,1]
	v_pk_mov_b32 v[34:35], v[2:3], v[2:3] op_sel:[0,1]
	v_pk_mov_b32 v[36:37], v[2:3], v[2:3] op_sel:[0,1]
	v_pk_mov_b32 v[38:39], v[2:3], v[2:3] op_sel:[0,1]
	v_pk_mov_b32 v[40:41], v[2:3], v[2:3] op_sel:[0,1]
	v_pk_mov_b32 v[50:51], v[2:3], v[2:3] op_sel:[0,1]
	v_pk_mov_b32 v[52:53], v[2:3], v[2:3] op_sel:[0,1]
	v_pk_mov_b32 v[54:55], v[2:3], v[2:3] op_sel:[0,1]
	v_pk_mov_b32 v[56:57], v[2:3], v[2:3] op_sel:[0,1]
	v_pk_mov_b32 v[58:59], v[2:3], v[2:3] op_sel:[0,1]
	v_pk_mov_b32 v[60:61], v[2:3], v[2:3] op_sel:[0,1]
	v_pk_mov_b32 v[62:63], v[2:3], v[2:3] op_sel:[0,1]
	v_pk_mov_b32 v[64:65], v[2:3], v[2:3] op_sel:[0,1]
	v_pk_mov_b32 v[66:67], v[2:3], v[2:3] op_sel:[0,1]
	v_pk_mov_b32 v[68:69], v[2:3], v[2:3] op_sel:[0,1]
	v_pk_mov_b32 v[70:71], v[2:3], v[2:3] op_sel:[0,1]
	v_pk_mov_b32 v[72:73], v[2:3], v[2:3] op_sel:[0,1]
	v_pk_mov_b32 v[74:75], v[2:3], v[2:3] op_sel:[0,1]
	v_pk_mov_b32 v[76:77], v[2:3], v[2:3] op_sel:[0,1]
	v_pk_mov_b32 v[78:79], v[2:3], v[2:3] op_sel:[0,1]
	v_pk_mov_b32 v[80:81], v[2:3], v[2:3] op_sel:[0,1]
	v_pk_mov_b32 v[86:87], v[2:3], v[2:3] op_sel:[0,1]
	v_pk_mov_b32 v[88:89], v[2:3], v[2:3] op_sel:[0,1]
	v_pk_mov_b32 v[94:95], v[2:3], v[2:3] op_sel:[0,1]
	v_pk_mov_b32 v[96:97], v[2:3], v[2:3] op_sel:[0,1]
	v_pk_mov_b32 v[102:103], v[2:3], v[2:3] op_sel:[0,1]
	v_pk_mov_b32 v[104:105], v[2:3], v[2:3] op_sel:[0,1]
	v_pk_mov_b32 v[110:111], v[2:3], v[2:3] op_sel:[0,1]
	v_pk_mov_b32 v[112:113], v[2:3], v[2:3] op_sel:[0,1]
	v_pk_mov_b32 v[82:83], v[2:3], v[2:3] op_sel:[0,1]
	v_pk_mov_b32 v[84:85], v[2:3], v[2:3] op_sel:[0,1]
	v_pk_mov_b32 v[90:91], v[2:3], v[2:3] op_sel:[0,1]
	v_pk_mov_b32 v[92:93], v[2:3], v[2:3] op_sel:[0,1]
	v_pk_mov_b32 v[98:99], v[2:3], v[2:3] op_sel:[0,1]
	v_pk_mov_b32 v[100:101], v[2:3], v[2:3] op_sel:[0,1]
	v_pk_mov_b32 v[106:107], v[2:3], v[2:3] op_sel:[0,1]
	v_pk_mov_b32 v[108:109], v[2:3], v[2:3] op_sel:[0,1]
	v_pk_mov_b32 v[114:115], v[2:3], v[2:3] op_sel:[0,1]
	v_pk_mov_b32 v[116:117], v[2:3], v[2:3] op_sel:[0,1]
	v_pk_mov_b32 v[118:119], v[2:3], v[2:3] op_sel:[0,1]
	v_pk_mov_b32 v[120:121], v[2:3], v[2:3] op_sel:[0,1]
	v_pk_mov_b32 v[122:123], v[2:3], v[2:3] op_sel:[0,1]
	v_pk_mov_b32 v[124:125], v[2:3], v[2:3] op_sel:[0,1]
	v_pk_mov_b32 v[126:127], v[2:3], v[2:3] op_sel:[0,1]
	v_pk_mov_b32 v[128:129], v[2:3], v[2:3] op_sel:[0,1]
	.p2align 6
.LBB0_712:
	s_add_u32 s0, s18, 0xfff00080
	s_addc_u32 s1, s19, -1
	s_add_i32 s33, 0, 0x10000
	s_cmp_eq_u32 s49, 4
	s_cselect_b32 s23, s15, s1
	s_cselect_b32 s22, s14, s0
	s_cselect_b32 s21, s17, s11
	s_cselect_b32 s20, s16, s9
	s_add_i32 s55, 0, 0x14000
	ds_read_b128 v[140:143], v136
	ds_read_b128 v[144:147], v136 offset:1024
	ds_read_b128 v[148:151], v136 offset:2048
	ds_read_b128 v[152:155], v136 offset:3072
	ds_read_b128 v[156:159], v136 offset:16384
	ds_read_b128 v[160:163], v136 offset:17408
	ds_read_b128 v[164:167], v136 offset:18432
	ds_read_b128 v[168:171], v136 offset:19456
	s_add_i32 m0, s27, 0xc000
	ds_read_b128 v[172:175], v139
	ds_read_b128 v[176:179], v139 offset:1024
	ds_read_b128 v[180:183], v139 offset:2048
	ds_read_b128 v[184:187], v139 offset:3072
	ds_read_b128 v[188:191], v139 offset:4096
	ds_read_b128 v[192:195], v139 offset:5120
	ds_read_b128 v[196:199], v139 offset:6144
	ds_read_b128 v[208:211], v139 offset:7168
	global_load_lds_dwordx4 v132, s[18:19]
	s_add_i32 m0, s27, 0xe000
	s_nop 0
	global_load_lds_dwordx4 v134, s[18:19]
	.p2align 3
	s_waitcnt vmcnt(8)
	s_waitcnt lgkmcnt(0)
	s_setprio 1
	s_barrier
	v_mfma_f32_16x16x32_bf16 v[126:129], v[140:143], v[172:175], v[126:129]
	v_mfma_f32_16x16x32_bf16 v[122:125], v[148:151], v[172:175], v[122:125]
	v_mfma_f32_16x16x32_bf16 v[118:121], v[140:143], v[180:183], v[118:121]
	v_mfma_f32_16x16x32_bf16 v[114:117], v[148:151], v[180:183], v[114:117]
	v_mfma_f32_16x16x32_bf16 v[106:109], v[140:143], v[188:191], v[106:109]
	v_mfma_f32_16x16x32_bf16 v[98:101], v[148:151], v[188:191], v[98:101]
	v_mfma_f32_16x16x32_bf16 v[90:93], v[140:143], v[196:199], v[90:93]
	v_mfma_f32_16x16x32_bf16 v[82:85], v[148:151], v[196:199], v[82:85]
	v_mfma_f32_16x16x32_bf16 v[126:129], v[144:147], v[176:179], v[126:129]
	v_mfma_f32_16x16x32_bf16 v[122:125], v[152:155], v[176:179], v[122:125]
	v_mfma_f32_16x16x32_bf16 v[118:121], v[144:147], v[184:187], v[118:121]
	v_mfma_f32_16x16x32_bf16 v[114:117], v[152:155], v[184:187], v[114:117]
	v_mfma_f32_16x16x32_bf16 v[106:109], v[144:147], v[192:195], v[106:109]
	v_mfma_f32_16x16x32_bf16 v[98:101], v[152:155], v[192:195], v[98:101]
	v_mfma_f32_16x16x32_bf16 v[90:93], v[144:147], v[208:211], v[90:93]
	v_mfma_f32_16x16x32_bf16 v[82:85], v[152:155], v[208:211], v[82:85]
	v_mfma_f32_16x16x32_bf16 v[110:113], v[156:159], v[172:175], v[110:113]
	v_mfma_f32_16x16x32_bf16 v[102:105], v[164:167], v[172:175], v[102:105]
	v_mfma_f32_16x16x32_bf16 v[94:97], v[156:159], v[180:183], v[94:97]
	v_mfma_f32_16x16x32_bf16 v[86:89], v[164:167], v[180:183], v[86:89]
	v_mfma_f32_16x16x32_bf16 v[78:81], v[156:159], v[188:191], v[78:81]
	v_mfma_f32_16x16x32_bf16 v[74:77], v[164:167], v[188:191], v[74:77]
	v_mfma_f32_16x16x32_bf16 v[70:73], v[156:159], v[196:199], v[70:73]
	v_mfma_f32_16x16x32_bf16 v[66:69], v[164:167], v[196:199], v[66:69]
	v_mfma_f32_16x16x32_bf16 v[110:113], v[160:163], v[176:179], v[110:113]
	v_mfma_f32_16x16x32_bf16 v[102:105], v[168:171], v[176:179], v[102:105]
	v_mfma_f32_16x16x32_bf16 v[94:97], v[160:163], v[184:187], v[94:97]
	v_mfma_f32_16x16x32_bf16 v[86:89], v[168:171], v[184:187], v[86:89]
	v_mfma_f32_16x16x32_bf16 v[78:81], v[160:163], v[192:195], v[78:81]
	v_mfma_f32_16x16x32_bf16 v[74:77], v[168:171], v[192:195], v[74:77]
	v_mfma_f32_16x16x32_bf16 v[70:73], v[160:163], v[208:211], v[70:73]
	v_mfma_f32_16x16x32_bf16 v[66:69], v[168:171], v[208:211], v[66:69]
	s_barrier
	s_setprio 0
	s_add_i32 s0, s33, s26
	s_mov_b32 m0, s0
	ds_read_b128 v[172:175], v139 offset:16384
	ds_read_b128 v[176:179], v139 offset:17408
	ds_read_b128 v[180:183], v139 offset:18432
	ds_read_b128 v[184:187], v139 offset:19456
	ds_read_b128 v[188:191], v139 offset:20480
	ds_read_b128 v[192:195], v139 offset:21504
	ds_read_b128 v[196:199], v139 offset:22528
	ds_read_b128 v[208:211], v139 offset:23552
	global_load_lds_dwordx4 v202, s[20:21]
	s_add_i32 m0, s0, 0x2000
	s_add_u32 s0, s20, 0x100000
	s_addc_u32 s1, s21, 0
	s_add_i32 s33, s55, s26
	global_load_lds_dwordx4 v130, s[20:21]
	s_mov_b32 m0, s33
	s_nop 0
	global_load_lds_dwordx4 v202, s[0:1]
	s_add_i32 m0, s33, 0x2000
	s_nop 0
	global_load_lds_dwordx4 v130, s[0:1]
	s_mov_b32 m0, s27
	s_nop 0
	global_load_lds_dwordx4 v202, s[22:23]
	s_mov_b32 m0, s28
	s_nop 0
	global_load_lds_dwordx4 v130, s[22:23]
	.p2align 3
	s_waitcnt vmcnt(8)
	s_waitcnt lgkmcnt(0)
	s_setprio 1
	s_barrier
	v_mfma_f32_16x16x32_bf16 v[62:65], v[140:143], v[172:175], v[62:65]
	v_mfma_f32_16x16x32_bf16 v[58:61], v[148:151], v[172:175], v[58:61]
	v_mfma_f32_16x16x32_bf16 v[54:57], v[140:143], v[180:183], v[54:57]
	v_mfma_f32_16x16x32_bf16 v[50:53], v[148:151], v[180:183], v[50:53]
	v_mfma_f32_16x16x32_bf16 v[38:41], v[140:143], v[188:191], v[38:41]
	v_mfma_f32_16x16x32_bf16 v[34:37], v[148:151], v[188:191], v[34:37]
	v_mfma_f32_16x16x32_bf16 v[22:25], v[140:143], v[196:199], v[22:25]
	v_mfma_f32_16x16x32_bf16 v[18:21], v[148:151], v[196:199], v[18:21]
	v_mfma_f32_16x16x32_bf16 v[62:65], v[144:147], v[176:179], v[62:65]
	v_mfma_f32_16x16x32_bf16 v[58:61], v[152:155], v[176:179], v[58:61]
	v_mfma_f32_16x16x32_bf16 v[54:57], v[144:147], v[184:187], v[54:57]
	v_mfma_f32_16x16x32_bf16 v[50:53], v[152:155], v[184:187], v[50:53]
	v_mfma_f32_16x16x32_bf16 v[38:41], v[144:147], v[192:195], v[38:41]
	v_mfma_f32_16x16x32_bf16 v[34:37], v[152:155], v[192:195], v[34:37]
	v_mfma_f32_16x16x32_bf16 v[22:25], v[144:147], v[208:211], v[22:25]
	v_mfma_f32_16x16x32_bf16 v[18:21], v[152:155], v[208:211], v[18:21]
	v_mfma_f32_16x16x32_bf16 v[46:49], v[156:159], v[172:175], v[46:49]
	v_mfma_f32_16x16x32_bf16 v[42:45], v[164:167], v[172:175], v[42:45]
	v_mfma_f32_16x16x32_bf16 v[30:33], v[156:159], v[180:183], v[30:33]
	v_mfma_f32_16x16x32_bf16 v[26:29], v[164:167], v[180:183], v[26:29]
	v_mfma_f32_16x16x32_bf16 v[14:17], v[156:159], v[188:191], v[14:17]
	v_mfma_f32_16x16x32_bf16 v[10:13], v[164:167], v[188:191], v[10:13]
	v_mfma_f32_16x16x32_bf16 v[6:9], v[156:159], v[196:199], v[6:9]
	v_mfma_f32_16x16x32_bf16 v[2:5], v[164:167], v[196:199], v[2:5]
	v_mfma_f32_16x16x32_bf16 v[46:49], v[160:163], v[176:179], v[46:49]
	v_mfma_f32_16x16x32_bf16 v[42:45], v[168:171], v[176:179], v[42:45]
	v_mfma_f32_16x16x32_bf16 v[30:33], v[160:163], v[184:187], v[30:33]
	v_mfma_f32_16x16x32_bf16 v[26:29], v[168:171], v[184:187], v[26:29]
	v_mfma_f32_16x16x32_bf16 v[14:17], v[160:163], v[192:195], v[14:17]
	v_mfma_f32_16x16x32_bf16 v[10:13], v[168:171], v[192:195], v[10:13]
	v_mfma_f32_16x16x32_bf16 v[6:9], v[160:163], v[208:211], v[6:9]
	v_mfma_f32_16x16x32_bf16 v[2:5], v[168:171], v[208:211], v[2:5]
	s_barrier
	s_setprio 0
	s_add_i32 s33, 0, 0x18000
	s_add_i32 s55, 0, 0x1c000
	ds_read_b128 v[140:143], v136 offset:32768
	ds_read_b128 v[144:147], v136 offset:33792
	ds_read_b128 v[148:151], v136 offset:34816
	ds_read_b128 v[152:155], v136 offset:35840
	ds_read_b128 v[156:159], v136 offset:49152
	ds_read_b128 v[160:163], v136 offset:50176
	ds_read_b128 v[164:167], v136 offset:51200
	ds_read_b128 v[168:171], v136 offset:52224
	s_add_u32 s0, s22, 0x100000
	s_addc_u32 s1, s23, 0
	s_mov_b32 m0, s29
	ds_read_b128 v[172:175], v139 offset:32768
	ds_read_b128 v[176:179], v139 offset:33792
	ds_read_b128 v[180:183], v139 offset:34816
	ds_read_b128 v[184:187], v139 offset:35840
	ds_read_b128 v[188:191], v139 offset:36864
	ds_read_b128 v[192:195], v139 offset:37888
	ds_read_b128 v[196:199], v139 offset:38912
	ds_read_b128 v[208:211], v139 offset:39936
	global_load_lds_dwordx4 v202, s[0:1]
	s_mov_b32 m0, s30
	s_nop 0
	global_load_lds_dwordx4 v130, s[0:1]
	.p2align 3
	s_waitcnt vmcnt(8)
	s_waitcnt lgkmcnt(0)
	s_setprio 1
	s_barrier
	v_mfma_f32_16x16x32_bf16 v[126:129], v[140:143], v[172:175], v[126:129]
	v_mfma_f32_16x16x32_bf16 v[122:125], v[148:151], v[172:175], v[122:125]
	v_mfma_f32_16x16x32_bf16 v[118:121], v[140:143], v[180:183], v[118:121]
	v_mfma_f32_16x16x32_bf16 v[114:117], v[148:151], v[180:183], v[114:117]
	v_mfma_f32_16x16x32_bf16 v[106:109], v[140:143], v[188:191], v[106:109]
	v_mfma_f32_16x16x32_bf16 v[98:101], v[148:151], v[188:191], v[98:101]
	v_mfma_f32_16x16x32_bf16 v[90:93], v[140:143], v[196:199], v[90:93]
	v_mfma_f32_16x16x32_bf16 v[82:85], v[148:151], v[196:199], v[82:85]
	v_mfma_f32_16x16x32_bf16 v[126:129], v[144:147], v[176:179], v[126:129]
	v_mfma_f32_16x16x32_bf16 v[122:125], v[152:155], v[176:179], v[122:125]
	v_mfma_f32_16x16x32_bf16 v[118:121], v[144:147], v[184:187], v[118:121]
	v_mfma_f32_16x16x32_bf16 v[114:117], v[152:155], v[184:187], v[114:117]
	v_mfma_f32_16x16x32_bf16 v[106:109], v[144:147], v[192:195], v[106:109]
	v_mfma_f32_16x16x32_bf16 v[98:101], v[152:155], v[192:195], v[98:101]
	v_mfma_f32_16x16x32_bf16 v[90:93], v[144:147], v[208:211], v[90:93]
	v_mfma_f32_16x16x32_bf16 v[82:85], v[152:155], v[208:211], v[82:85]
	v_mfma_f32_16x16x32_bf16 v[110:113], v[156:159], v[172:175], v[110:113]
	v_mfma_f32_16x16x32_bf16 v[102:105], v[164:167], v[172:175], v[102:105]
	v_mfma_f32_16x16x32_bf16 v[94:97], v[156:159], v[180:183], v[94:97]
	v_mfma_f32_16x16x32_bf16 v[86:89], v[164:167], v[180:183], v[86:89]
	v_mfma_f32_16x16x32_bf16 v[78:81], v[156:159], v[188:191], v[78:81]
	v_mfma_f32_16x16x32_bf16 v[74:77], v[164:167], v[188:191], v[74:77]
	v_mfma_f32_16x16x32_bf16 v[70:73], v[156:159], v[196:199], v[70:73]
	v_mfma_f32_16x16x32_bf16 v[66:69], v[164:167], v[196:199], v[66:69]
	v_mfma_f32_16x16x32_bf16 v[110:113], v[160:163], v[176:179], v[110:113]
	v_mfma_f32_16x16x32_bf16 v[102:105], v[168:171], v[176:179], v[102:105]
	v_mfma_f32_16x16x32_bf16 v[94:97], v[160:163], v[184:187], v[94:97]
	v_mfma_f32_16x16x32_bf16 v[86:89], v[168:171], v[184:187], v[86:89]
	v_mfma_f32_16x16x32_bf16 v[78:81], v[160:163], v[192:195], v[78:81]
	v_mfma_f32_16x16x32_bf16 v[74:77], v[168:171], v[192:195], v[74:77]
	v_mfma_f32_16x16x32_bf16 v[70:73], v[160:163], v[208:211], v[70:73]
	v_mfma_f32_16x16x32_bf16 v[66:69], v[168:171], v[208:211], v[66:69]
	s_barrier
	s_setprio 0
	s_add_i32 s0, s33, s26
	s_add_u32 s100, s20, 0x80
	s_addc_u32 s101, s21, 0
	s_mov_b32 m0, s0
	ds_read_b128 v[172:175], v139 offset:49152
	ds_read_b128 v[176:179], v139 offset:50176
	ds_read_b128 v[180:183], v139 offset:51200
	ds_read_b128 v[184:187], v139 offset:52224
	ds_read_b128 v[188:191], v139 offset:53248
	ds_read_b128 v[192:195], v139 offset:54272
	ds_read_b128 v[196:199], v139 offset:55296
	ds_read_b128 v[208:211], v139 offset:56320
	global_load_lds_dwordx4 v202, s[100:101]
	s_add_i32 m0, s0, 0x2000
	s_add_u32 s100, s20, 0x80
	s_addc_u32 s101, s21, 0
	s_add_u32 s0, s20, 0x100080
	s_addc_u32 s1, s21, 0
	s_add_i32 s20, s55, s26
	global_load_lds_dwordx4 v130, s[100:101]
	s_mov_b32 m0, s20
	s_nop 0
	global_load_lds_dwordx4 v202, s[0:1]
	s_add_i32 m0, s20, 0x2000
	s_nop 0
	global_load_lds_dwordx4 v130, s[0:1]
	s_add_u32 s100, s22, 0x80
	s_addc_u32 s101, s23, 0
	s_mov_b32 m0, s31
	s_nop 0
	global_load_lds_dwordx4 v202, s[100:101]
	s_add_u32 s100, s22, 0x80
	s_addc_u32 s101, s23, 0
	s_mov_b32 m0, s34
	s_nop 0
	global_load_lds_dwordx4 v130, s[100:101]
	.p2align 3
	s_waitcnt vmcnt(8)
	s_waitcnt lgkmcnt(0)
	s_setprio 1
	s_barrier
	v_mfma_f32_16x16x32_bf16 v[62:65], v[140:143], v[172:175], v[62:65]
	v_mfma_f32_16x16x32_bf16 v[58:61], v[148:151], v[172:175], v[58:61]
	v_mfma_f32_16x16x32_bf16 v[54:57], v[140:143], v[180:183], v[54:57]
	v_mfma_f32_16x16x32_bf16 v[50:53], v[148:151], v[180:183], v[50:53]
	v_mfma_f32_16x16x32_bf16 v[38:41], v[140:143], v[188:191], v[38:41]
	v_mfma_f32_16x16x32_bf16 v[34:37], v[148:151], v[188:191], v[34:37]
	v_mfma_f32_16x16x32_bf16 v[22:25], v[140:143], v[196:199], v[22:25]
	v_mfma_f32_16x16x32_bf16 v[18:21], v[148:151], v[196:199], v[18:21]
	v_mfma_f32_16x16x32_bf16 v[62:65], v[144:147], v[176:179], v[62:65]
	v_mfma_f32_16x16x32_bf16 v[58:61], v[152:155], v[176:179], v[58:61]
	v_mfma_f32_16x16x32_bf16 v[54:57], v[144:147], v[184:187], v[54:57]
	v_mfma_f32_16x16x32_bf16 v[50:53], v[152:155], v[184:187], v[50:53]
	v_mfma_f32_16x16x32_bf16 v[38:41], v[144:147], v[192:195], v[38:41]
	v_mfma_f32_16x16x32_bf16 v[34:37], v[152:155], v[192:195], v[34:37]
	v_mfma_f32_16x16x32_bf16 v[22:25], v[144:147], v[208:211], v[22:25]
	v_mfma_f32_16x16x32_bf16 v[18:21], v[152:155], v[208:211], v[18:21]
	v_mfma_f32_16x16x32_bf16 v[46:49], v[156:159], v[172:175], v[46:49]
	v_mfma_f32_16x16x32_bf16 v[42:45], v[164:167], v[172:175], v[42:45]
	v_mfma_f32_16x16x32_bf16 v[30:33], v[156:159], v[180:183], v[30:33]
	v_mfma_f32_16x16x32_bf16 v[26:29], v[164:167], v[180:183], v[26:29]
	v_mfma_f32_16x16x32_bf16 v[14:17], v[156:159], v[188:191], v[14:17]
	v_mfma_f32_16x16x32_bf16 v[10:13], v[164:167], v[188:191], v[10:13]
	v_mfma_f32_16x16x32_bf16 v[6:9], v[156:159], v[196:199], v[6:9]
	v_mfma_f32_16x16x32_bf16 v[2:5], v[164:167], v[196:199], v[2:5]
	v_mfma_f32_16x16x32_bf16 v[46:49], v[160:163], v[176:179], v[46:49]
	v_mfma_f32_16x16x32_bf16 v[42:45], v[168:171], v[176:179], v[42:45]
	v_mfma_f32_16x16x32_bf16 v[30:33], v[160:163], v[184:187], v[30:33]
	v_mfma_f32_16x16x32_bf16 v[26:29], v[168:171], v[184:187], v[26:29]
	v_mfma_f32_16x16x32_bf16 v[14:17], v[160:163], v[192:195], v[14:17]
	v_mfma_f32_16x16x32_bf16 v[10:13], v[168:171], v[192:195], v[10:13]
	v_mfma_f32_16x16x32_bf16 v[6:9], v[160:163], v[208:211], v[6:9]
	v_mfma_f32_16x16x32_bf16 v[2:5], v[168:171], v[208:211], v[2:5]
	s_barrier
	s_setprio 0
	s_add_i32 s49, s49, 2
	s_add_u32 s18, s18, 0x100
	s_addc_u32 s19, s19, 0
	s_add_u32 s9, s9, 0x100
	s_addc_u32 s11, s11, 0
	s_cmp_gt_u32 s49, 5
	s_cbranch_scc0 .LBB0_712
	s_and_b64 vcc, exec, s[6:7]
	s_cbranch_vccz .LBB0_715
	s_barrier

.LBB0_836:
	s_ashr_i32 s11, s10, 31
	s_lshl_b64 s[0:1], s[10:11], 20
	s_add_u32 s14, s42, s0
	s_addc_u32 s15, s43, s1
	s_and_b64 s[0:1], s[2:3], exec
	s_cselect_b32 s11, s15, s19
	s_cselect_b32 s38, s14, s18
	s_ashr_i32 s9, s8, 31
	s_lshl_b64 s[0:1], s[8:9], 20
	s_add_u32 s16, s24, s0
	s_addc_u32 s17, s25, s1
	s_and_b64 s[0:1], s[2:3], exec
	s_cselect_b32 s9, s17, s21
	s_cselect_b32 s39, s16, s20
	s_add_u32 s18, s18, 0x80080
	s_addc_u32 s19, s19, 0
	s_add_u32 s49, s20, 0x100
	v_mov_b32_e32 v2, 0
	s_addc_u32 s58, s21, 0
	s_mov_b32 s59, -2
	v_mov_b32_e32 v3, v2
	v_pk_mov_b32 v[4:5], v[2:3], v[2:3] op_sel:[0,1]
	v_pk_mov_b32 v[10:11], v[2:3], v[2:3] op_sel:[0,1]
	v_pk_mov_b32 v[12:13], v[2:3], v[2:3] op_sel:[0,1]
	v_pk_mov_b32 v[18:19], v[2:3], v[2:3] op_sel:[0,1]
	v_pk_mov_b32 v[20:21], v[2:3], v[2:3] op_sel:[0,1]
	v_pk_mov_b32 v[26:27], v[2:3], v[2:3] op_sel:[0,1]
	v_pk_mov_b32 v[28:29], v[2:3], v[2:3] op_sel:[0,1]
	v_pk_mov_b32 v[34:35], v[2:3], v[2:3] op_sel:[0,1]
	v_pk_mov_b32 v[36:37], v[2:3], v[2:3] op_sel:[0,1]
	v_pk_mov_b32 v[42:43], v[2:3], v[2:3] op_sel:[0,1]
	v_pk_mov_b32 v[44:45], v[2:3], v[2:3] op_sel:[0,1]
	v_pk_mov_b32 v[50:51], v[2:3], v[2:3] op_sel:[0,1]
	v_pk_mov_b32 v[52:53], v[2:3], v[2:3] op_sel:[0,1]
	v_pk_mov_b32 v[58:59], v[2:3], v[2:3] op_sel:[0,1]
	v_pk_mov_b32 v[60:61], v[2:3], v[2:3] op_sel:[0,1]
	v_pk_mov_b32 v[6:7], v[2:3], v[2:3] op_sel:[0,1]
	v_pk_mov_b32 v[8:9], v[2:3], v[2:3] op_sel:[0,1]
	v_pk_mov_b32 v[14:15], v[2:3], v[2:3] op_sel:[0,1]
	v_pk_mov_b32 v[16:17], v[2:3], v[2:3] op_sel:[0,1]
	v_pk_mov_b32 v[22:23], v[2:3], v[2:3] op_sel:[0,1]
	v_pk_mov_b32 v[24:25], v[2:3], v[2:3] op_sel:[0,1]
	v_pk_mov_b32 v[30:31], v[2:3], v[2:3] op_sel:[0,1]
	v_pk_mov_b32 v[32:33], v[2:3], v[2:3] op_sel:[0,1]
	v_pk_mov_b32 v[38:39], v[2:3], v[2:3] op_sel:[0,1]
	v_pk_mov_b32 v[40:41], v[2:3], v[2:3] op_sel:[0,1]
	v_pk_mov_b32 v[46:47], v[2:3], v[2:3] op_sel:[0,1]
	v_pk_mov_b32 v[48:49], v[2:3], v[2:3] op_sel:[0,1]
	v_pk_mov_b32 v[54:55], v[2:3], v[2:3] op_sel:[0,1]
	v_pk_mov_b32 v[56:57], v[2:3], v[2:3] op_sel:[0,1]
	v_pk_mov_b32 v[62:63], v[2:3], v[2:3] op_sel:[0,1]
	v_pk_mov_b32 v[64:65], v[2:3], v[2:3] op_sel:[0,1]
	v_pk_mov_b32 v[66:67], v[2:3], v[2:3] op_sel:[0,1]
	v_pk_mov_b32 v[68:69], v[2:3], v[2:3] op_sel:[0,1]
	v_pk_mov_b32 v[74:75], v[2:3], v[2:3] op_sel:[0,1]
	v_pk_mov_b32 v[76:77], v[2:3], v[2:3] op_sel:[0,1]
	v_pk_mov_b32 v[82:83], v[2:3], v[2:3] op_sel:[0,1]
	v_pk_mov_b32 v[84:85], v[2:3], v[2:3] op_sel:[0,1]
	v_pk_mov_b32 v[90:91], v[2:3], v[2:3] op_sel:[0,1]
	v_pk_mov_b32 v[92:93], v[2:3], v[2:3] op_sel:[0,1]
	v_pk_mov_b32 v[98:99], v[2:3], v[2:3] op_sel:[0,1]
	v_pk_mov_b32 v[100:101], v[2:3], v[2:3] op_sel:[0,1]
	v_pk_mov_b32 v[106:107], v[2:3], v[2:3] op_sel:[0,1]
	v_pk_mov_b32 v[108:109], v[2:3], v[2:3] op_sel:[0,1]
	v_pk_mov_b32 v[114:115], v[2:3], v[2:3] op_sel:[0,1]
	v_pk_mov_b32 v[116:117], v[2:3], v[2:3] op_sel:[0,1]
	v_pk_mov_b32 v[122:123], v[2:3], v[2:3] op_sel:[0,1]
	v_pk_mov_b32 v[124:125], v[2:3], v[2:3] op_sel:[0,1]
	v_pk_mov_b32 v[70:71], v[2:3], v[2:3] op_sel:[0,1]
	v_pk_mov_b32 v[72:73], v[2:3], v[2:3] op_sel:[0,1]
	v_pk_mov_b32 v[78:79], v[2:3], v[2:3] op_sel:[0,1]
	v_pk_mov_b32 v[80:81], v[2:3], v[2:3] op_sel:[0,1]
	v_pk_mov_b32 v[86:87], v[2:3], v[2:3] op_sel:[0,1]
	v_pk_mov_b32 v[88:89], v[2:3], v[2:3] op_sel:[0,1]
	v_pk_mov_b32 v[94:95], v[2:3], v[2:3] op_sel:[0,1]
	v_pk_mov_b32 v[96:97], v[2:3], v[2:3] op_sel:[0,1]
	v_pk_mov_b32 v[102:103], v[2:3], v[2:3] op_sel:[0,1]
	v_pk_mov_b32 v[104:105], v[2:3], v[2:3] op_sel:[0,1]
	v_pk_mov_b32 v[110:111], v[2:3], v[2:3] op_sel:[0,1]
	v_pk_mov_b32 v[112:113], v[2:3], v[2:3] op_sel:[0,1]
	v_pk_mov_b32 v[118:119], v[2:3], v[2:3] op_sel:[0,1]
	v_pk_mov_b32 v[120:121], v[2:3], v[2:3] op_sel:[0,1]
	v_pk_mov_b32 v[126:127], v[2:3], v[2:3] op_sel:[0,1]
	v_pk_mov_b32 v[128:129], v[2:3], v[2:3] op_sel:[0,1]
	.p2align 6
.LBB0_837:
	s_add_u32 s0, s18, 0xfff80080
	s_addc_u32 s1, s19, -1
	s_add_i32 s33, 0, 0x10000
	s_cmp_eq_u32 s59, 28
	s_cselect_b32 s23, s11, s1
	s_cselect_b32 s22, s38, s0
	s_cselect_b32 s21, s9, s58
	s_cselect_b32 s20, s39, s49
	s_add_i32 s55, 0, 0x14000
	ds_read_b128 v[146:149], v143
	ds_read_b128 v[150:153], v143 offset:1024
	ds_read_b128 v[154:157], v143 offset:2048
	ds_read_b128 v[158:161], v143 offset:3072
	ds_read_b128 v[162:165], v143 offset:16384
	ds_read_b128 v[166:169], v143 offset:17408
	ds_read_b128 v[170:173], v143 offset:18432
	ds_read_b128 v[174:177], v143 offset:19456
	s_add_i32 m0, s27, 0xc000
	ds_read_b128 v[178:181], v145
	ds_read_b128 v[182:185], v145 offset:1024
	ds_read_b128 v[186:189], v145 offset:2048
	ds_read_b128 v[190:193], v145 offset:3072
	ds_read_b128 v[194:197], v145 offset:4096
	ds_read_b128 v[198:201], v145 offset:5120
	ds_read_b128 v[208:211], v145 offset:6144
	ds_read_b128 v[212:215], v145 offset:7168
	global_load_lds_dwordx4 v136, s[18:19]
	s_add_i32 m0, s27, 0xe000
	s_nop 0
	global_load_lds_dwordx4 v138, s[18:19]
	.p2align 3
	s_waitcnt vmcnt(8)
	s_waitcnt lgkmcnt(0)
	s_setprio 1
	s_barrier
	v_mfma_f32_16x16x32_bf16 v[126:129], v[146:149], v[178:181], v[126:129]
	v_mfma_f32_16x16x32_bf16 v[118:121], v[154:157], v[178:181], v[118:121]
	v_mfma_f32_16x16x32_bf16 v[110:113], v[146:149], v[186:189], v[110:113]
	v_mfma_f32_16x16x32_bf16 v[102:105], v[154:157], v[186:189], v[102:105]
	v_mfma_f32_16x16x32_bf16 v[94:97], v[146:149], v[194:197], v[94:97]
	v_mfma_f32_16x16x32_bf16 v[86:89], v[154:157], v[194:197], v[86:89]
	v_mfma_f32_16x16x32_bf16 v[78:81], v[146:149], v[208:211], v[78:81]
	v_mfma_f32_16x16x32_bf16 v[70:73], v[154:157], v[208:211], v[70:73]
	v_mfma_f32_16x16x32_bf16 v[126:129], v[150:153], v[182:185], v[126:129]
	v_mfma_f32_16x16x32_bf16 v[118:121], v[158:161], v[182:185], v[118:121]
	v_mfma_f32_16x16x32_bf16 v[110:113], v[150:153], v[190:193], v[110:113]
	v_mfma_f32_16x16x32_bf16 v[102:105], v[158:161], v[190:193], v[102:105]
	v_mfma_f32_16x16x32_bf16 v[94:97], v[150:153], v[198:201], v[94:97]
	v_mfma_f32_16x16x32_bf16 v[86:89], v[158:161], v[198:201], v[86:89]
	v_mfma_f32_16x16x32_bf16 v[78:81], v[150:153], v[212:215], v[78:81]
	v_mfma_f32_16x16x32_bf16 v[70:73], v[158:161], v[212:215], v[70:73]
	v_mfma_f32_16x16x32_bf16 v[122:125], v[162:165], v[178:181], v[122:125]
	v_mfma_f32_16x16x32_bf16 v[114:117], v[170:173], v[178:181], v[114:117]
	v_mfma_f32_16x16x32_bf16 v[106:109], v[162:165], v[186:189], v[106:109]
	v_mfma_f32_16x16x32_bf16 v[98:101], v[170:173], v[186:189], v[98:101]
	v_mfma_f32_16x16x32_bf16 v[90:93], v[162:165], v[194:197], v[90:93]
	v_mfma_f32_16x16x32_bf16 v[82:85], v[170:173], v[194:197], v[82:85]
	v_mfma_f32_16x16x32_bf16 v[74:77], v[162:165], v[208:211], v[74:77]
	v_mfma_f32_16x16x32_bf16 v[66:69], v[170:173], v[208:211], v[66:69]
	v_mfma_f32_16x16x32_bf16 v[122:125], v[166:169], v[182:185], v[122:125]
	v_mfma_f32_16x16x32_bf16 v[114:117], v[174:177], v[182:185], v[114:117]
	v_mfma_f32_16x16x32_bf16 v[106:109], v[166:169], v[190:193], v[106:109]
	v_mfma_f32_16x16x32_bf16 v[98:101], v[174:177], v[190:193], v[98:101]
	v_mfma_f32_16x16x32_bf16 v[90:93], v[166:169], v[198:201], v[90:93]
	v_mfma_f32_16x16x32_bf16 v[82:85], v[174:177], v[198:201], v[82:85]
	v_mfma_f32_16x16x32_bf16 v[74:77], v[166:169], v[212:215], v[74:77]
	v_mfma_f32_16x16x32_bf16 v[66:69], v[174:177], v[212:215], v[66:69]
	s_barrier
	s_setprio 0
	s_add_i32 s0, s33, s26
	s_mov_b32 m0, s0
	ds_read_b128 v[178:181], v145 offset:16384
	ds_read_b128 v[182:185], v145 offset:17408
	ds_read_b128 v[186:189], v145 offset:18432
	ds_read_b128 v[190:193], v145 offset:19456
	ds_read_b128 v[194:197], v145 offset:20480
	ds_read_b128 v[198:201], v145 offset:21504
	ds_read_b128 v[208:211], v145 offset:22528
	ds_read_b128 v[212:215], v145 offset:23552
	global_load_lds_dwordx4 v202, s[20:21]
	s_add_i32 m0, s0, 0x2000
	s_add_u32 s0, s20, 0x80000
	s_addc_u32 s1, s21, 0
	s_add_i32 s33, s55, s26
	global_load_lds_dwordx4 v130, s[20:21]
	s_mov_b32 m0, s33
	s_nop 0
	global_load_lds_dwordx4 v202, s[0:1]
	s_add_i32 m0, s33, 0x2000
	s_nop 0
	global_load_lds_dwordx4 v130, s[0:1]
	s_mov_b32 m0, s27
	s_nop 0
	global_load_lds_dwordx4 v134, s[22:23]
	s_mov_b32 m0, s28
	s_nop 0
	global_load_lds_dwordx4 v132, s[22:23]
	.p2align 3
	s_waitcnt vmcnt(8)
	s_waitcnt lgkmcnt(0)
	s_setprio 1
	s_barrier
	v_mfma_f32_16x16x32_bf16 v[62:65], v[146:149], v[178:181], v[62:65]
	v_mfma_f32_16x16x32_bf16 v[54:57], v[154:157], v[178:181], v[54:57]
	v_mfma_f32_16x16x32_bf16 v[46:49], v[146:149], v[186:189], v[46:49]
	v_mfma_f32_16x16x32_bf16 v[38:41], v[154:157], v[186:189], v[38:41]
	v_mfma_f32_16x16x32_bf16 v[30:33], v[146:149], v[194:197], v[30:33]
	v_mfma_f32_16x16x32_bf16 v[22:25], v[154:157], v[194:197], v[22:25]
	v_mfma_f32_16x16x32_bf16 v[14:17], v[146:149], v[208:211], v[14:17]
	v_mfma_f32_16x16x32_bf16 v[6:9], v[154:157], v[208:211], v[6:9]
	v_mfma_f32_16x16x32_bf16 v[62:65], v[150:153], v[182:185], v[62:65]
	v_mfma_f32_16x16x32_bf16 v[54:57], v[158:161], v[182:185], v[54:57]
	v_mfma_f32_16x16x32_bf16 v[46:49], v[150:153], v[190:193], v[46:49]
	v_mfma_f32_16x16x32_bf16 v[38:41], v[158:161], v[190:193], v[38:41]
	v_mfma_f32_16x16x32_bf16 v[30:33], v[150:153], v[198:201], v[30:33]
	v_mfma_f32_16x16x32_bf16 v[22:25], v[158:161], v[198:201], v[22:25]
	v_mfma_f32_16x16x32_bf16 v[14:17], v[150:153], v[212:215], v[14:17]
	v_mfma_f32_16x16x32_bf16 v[6:9], v[158:161], v[212:215], v[6:9]
	v_mfma_f32_16x16x32_bf16 v[58:61], v[162:165], v[178:181], v[58:61]
	v_mfma_f32_16x16x32_bf16 v[50:53], v[170:173], v[178:181], v[50:53]
	v_mfma_f32_16x16x32_bf16 v[42:45], v[162:165], v[186:189], v[42:45]
	v_mfma_f32_16x16x32_bf16 v[34:37], v[170:173], v[186:189], v[34:37]
	v_mfma_f32_16x16x32_bf16 v[26:29], v[162:165], v[194:197], v[26:29]
	v_mfma_f32_16x16x32_bf16 v[18:21], v[170:173], v[194:197], v[18:21]
	v_mfma_f32_16x16x32_bf16 v[10:13], v[162:165], v[208:211], v[10:13]
	v_mfma_f32_16x16x32_bf16 v[2:5], v[170:173], v[208:211], v[2:5]
	v_mfma_f32_16x16x32_bf16 v[58:61], v[166:169], v[182:185], v[58:61]
	v_mfma_f32_16x16x32_bf16 v[50:53], v[174:177], v[182:185], v[50:53]
	v_mfma_f32_16x16x32_bf16 v[42:45], v[166:169], v[190:193], v[42:45]
	v_mfma_f32_16x16x32_bf16 v[34:37], v[174:177], v[190:193], v[34:37]
	v_mfma_f32_16x16x32_bf16 v[26:29], v[166:169], v[198:201], v[26:29]
	v_mfma_f32_16x16x32_bf16 v[18:21], v[174:177], v[198:201], v[18:21]
	v_mfma_f32_16x16x32_bf16 v[10:13], v[166:169], v[212:215], v[10:13]
	v_mfma_f32_16x16x32_bf16 v[2:5], v[174:177], v[212:215], v[2:5]
	s_barrier
	s_setprio 0
	s_add_i32 s33, 0, 0x18000
	s_add_i32 s55, 0, 0x1c000
	ds_read_b128 v[146:149], v143 offset:32768
	ds_read_b128 v[150:153], v143 offset:33792
	ds_read_b128 v[154:157], v143 offset:34816
	ds_read_b128 v[158:161], v143 offset:35840
	ds_read_b128 v[162:165], v143 offset:49152
	ds_read_b128 v[166:169], v143 offset:50176
	ds_read_b128 v[170:173], v143 offset:51200
	ds_read_b128 v[174:177], v143 offset:52224
	s_add_u32 s0, s22, 0x80000
	s_addc_u32 s1, s23, 0
	s_mov_b32 m0, s29
	ds_read_b128 v[178:181], v145 offset:32768
	ds_read_b128 v[182:185], v145 offset:33792
	ds_read_b128 v[186:189], v145 offset:34816
	ds_read_b128 v[190:193], v145 offset:35840
	ds_read_b128 v[194:197], v145 offset:36864
	ds_read_b128 v[198:201], v145 offset:37888
	ds_read_b128 v[208:211], v145 offset:38912
	ds_read_b128 v[212:215], v145 offset:39936
	global_load_lds_dwordx4 v134, s[0:1]
	s_mov_b32 m0, s30
	s_nop 0
	global_load_lds_dwordx4 v132, s[0:1]
	.p2align 3
	s_waitcnt vmcnt(8)
	s_waitcnt lgkmcnt(0)
	s_setprio 1
	s_barrier
	v_mfma_f32_16x16x32_bf16 v[126:129], v[146:149], v[178:181], v[126:129]
	v_mfma_f32_16x16x32_bf16 v[118:121], v[154:157], v[178:181], v[118:121]
	v_mfma_f32_16x16x32_bf16 v[110:113], v[146:149], v[186:189], v[110:113]
	v_mfma_f32_16x16x32_bf16 v[102:105], v[154:157], v[186:189], v[102:105]
	v_mfma_f32_16x16x32_bf16 v[94:97], v[146:149], v[194:197], v[94:97]
	v_mfma_f32_16x16x32_bf16 v[86:89], v[154:157], v[194:197], v[86:89]
	v_mfma_f32_16x16x32_bf16 v[78:81], v[146:149], v[208:211], v[78:81]
	v_mfma_f32_16x16x32_bf16 v[70:73], v[154:157], v[208:211], v[70:73]
	v_mfma_f32_16x16x32_bf16 v[126:129], v[150:153], v[182:185], v[126:129]
	v_mfma_f32_16x16x32_bf16 v[118:121], v[158:161], v[182:185], v[118:121]
	v_mfma_f32_16x16x32_bf16 v[110:113], v[150:153], v[190:193], v[110:113]
	v_mfma_f32_16x16x32_bf16 v[102:105], v[158:161], v[190:193], v[102:105]
	v_mfma_f32_16x16x32_bf16 v[94:97], v[150:153], v[198:201], v[94:97]
	v_mfma_f32_16x16x32_bf16 v[86:89], v[158:161], v[198:201], v[86:89]
	v_mfma_f32_16x16x32_bf16 v[78:81], v[150:153], v[212:215], v[78:81]
	v_mfma_f32_16x16x32_bf16 v[70:73], v[158:161], v[212:215], v[70:73]
	v_mfma_f32_16x16x32_bf16 v[122:125], v[162:165], v[178:181], v[122:125]
	v_mfma_f32_16x16x32_bf16 v[114:117], v[170:173], v[178:181], v[114:117]
	v_mfma_f32_16x16x32_bf16 v[106:109], v[162:165], v[186:189], v[106:109]
	v_mfma_f32_16x16x32_bf16 v[98:101], v[170:173], v[186:189], v[98:101]
	v_mfma_f32_16x16x32_bf16 v[90:93], v[162:165], v[194:197], v[90:93]
	v_mfma_f32_16x16x32_bf16 v[82:85], v[170:173], v[194:197], v[82:85]
	v_mfma_f32_16x16x32_bf16 v[74:77], v[162:165], v[208:211], v[74:77]
	v_mfma_f32_16x16x32_bf16 v[66:69], v[170:173], v[208:211], v[66:69]
	v_mfma_f32_16x16x32_bf16 v[122:125], v[166:169], v[182:185], v[122:125]
	v_mfma_f32_16x16x32_bf16 v[114:117], v[174:177], v[182:185], v[114:117]
	v_mfma_f32_16x16x32_bf16 v[106:109], v[166:169], v[190:193], v[106:109]
	v_mfma_f32_16x16x32_bf16 v[98:101], v[174:177], v[190:193], v[98:101]
	v_mfma_f32_16x16x32_bf16 v[90:93], v[166:169], v[198:201], v[90:93]
	v_mfma_f32_16x16x32_bf16 v[82:85], v[174:177], v[198:201], v[82:85]
	v_mfma_f32_16x16x32_bf16 v[74:77], v[166:169], v[212:215], v[74:77]
	v_mfma_f32_16x16x32_bf16 v[66:69], v[174:177], v[212:215], v[66:69]
	s_barrier
	s_setprio 0
	s_add_i32 s0, s33, s26
	s_add_u32 s100, s20, 0x80
	s_addc_u32 s101, s21, 0
	s_mov_b32 m0, s0
	ds_read_b128 v[178:181], v145 offset:49152
	ds_read_b128 v[182:185], v145 offset:50176
	ds_read_b128 v[186:189], v145 offset:51200
	ds_read_b128 v[190:193], v145 offset:52224
	ds_read_b128 v[194:197], v145 offset:53248
	ds_read_b128 v[198:201], v145 offset:54272
	ds_read_b128 v[208:211], v145 offset:55296
	ds_read_b128 v[212:215], v145 offset:56320
	global_load_lds_dwordx4 v202, s[100:101]
	s_add_i32 m0, s0, 0x2000
	s_add_u32 s100, s20, 0x80
	s_addc_u32 s101, s21, 0
	s_add_u32 s0, s20, 0x80080
	s_addc_u32 s1, s21, 0
	s_add_i32 s20, s55, s26
	global_load_lds_dwordx4 v130, s[100:101]
	s_mov_b32 m0, s20
	s_nop 0
	global_load_lds_dwordx4 v202, s[0:1]
	s_add_i32 m0, s20, 0x2000
	s_nop 0
	global_load_lds_dwordx4 v130, s[0:1]
	s_add_u32 s100, s22, 0x80
	s_addc_u32 s101, s23, 0
	s_mov_b32 m0, s31
	s_nop 0
	global_load_lds_dwordx4 v134, s[100:101]
	s_add_u32 s100, s22, 0x80
	s_addc_u32 s101, s23, 0
	s_mov_b32 m0, s34
	s_nop 0
	global_load_lds_dwordx4 v132, s[100:101]
	.p2align 3
	s_waitcnt vmcnt(8)
	s_waitcnt lgkmcnt(0)
	s_setprio 1
	s_barrier
	v_mfma_f32_16x16x32_bf16 v[62:65], v[146:149], v[178:181], v[62:65]
	v_mfma_f32_16x16x32_bf16 v[54:57], v[154:157], v[178:181], v[54:57]
	v_mfma_f32_16x16x32_bf16 v[46:49], v[146:149], v[186:189], v[46:49]
	v_mfma_f32_16x16x32_bf16 v[38:41], v[154:157], v[186:189], v[38:41]
	v_mfma_f32_16x16x32_bf16 v[30:33], v[146:149], v[194:197], v[30:33]
	v_mfma_f32_16x16x32_bf16 v[22:25], v[154:157], v[194:197], v[22:25]
	v_mfma_f32_16x16x32_bf16 v[14:17], v[146:149], v[208:211], v[14:17]
	v_mfma_f32_16x16x32_bf16 v[6:9], v[154:157], v[208:211], v[6:9]
	v_mfma_f32_16x16x32_bf16 v[62:65], v[150:153], v[182:185], v[62:65]
	v_mfma_f32_16x16x32_bf16 v[54:57], v[158:161], v[182:185], v[54:57]
	v_mfma_f32_16x16x32_bf16 v[46:49], v[150:153], v[190:193], v[46:49]
	v_mfma_f32_16x16x32_bf16 v[38:41], v[158:161], v[190:193], v[38:41]
	v_mfma_f32_16x16x32_bf16 v[30:33], v[150:153], v[198:201], v[30:33]
	v_mfma_f32_16x16x32_bf16 v[22:25], v[158:161], v[198:201], v[22:25]
	v_mfma_f32_16x16x32_bf16 v[14:17], v[150:153], v[212:215], v[14:17]
	v_mfma_f32_16x16x32_bf16 v[6:9], v[158:161], v[212:215], v[6:9]
	v_mfma_f32_16x16x32_bf16 v[58:61], v[162:165], v[178:181], v[58:61]
	v_mfma_f32_16x16x32_bf16 v[50:53], v[170:173], v[178:181], v[50:53]
	v_mfma_f32_16x16x32_bf16 v[42:45], v[162:165], v[186:189], v[42:45]
	v_mfma_f32_16x16x32_bf16 v[34:37], v[170:173], v[186:189], v[34:37]
	v_mfma_f32_16x16x32_bf16 v[26:29], v[162:165], v[194:197], v[26:29]
	v_mfma_f32_16x16x32_bf16 v[18:21], v[170:173], v[194:197], v[18:21]
	v_mfma_f32_16x16x32_bf16 v[10:13], v[162:165], v[208:211], v[10:13]
	v_mfma_f32_16x16x32_bf16 v[2:5], v[170:173], v[208:211], v[2:5]
	v_mfma_f32_16x16x32_bf16 v[58:61], v[166:169], v[182:185], v[58:61]
	v_mfma_f32_16x16x32_bf16 v[50:53], v[174:177], v[182:185], v[50:53]
	v_mfma_f32_16x16x32_bf16 v[42:45], v[166:169], v[190:193], v[42:45]
	v_mfma_f32_16x16x32_bf16 v[34:37], v[174:177], v[190:193], v[34:37]
	v_mfma_f32_16x16x32_bf16 v[26:29], v[166:169], v[198:201], v[26:29]
	v_mfma_f32_16x16x32_bf16 v[18:21], v[174:177], v[198:201], v[18:21]
	v_mfma_f32_16x16x32_bf16 v[10:13], v[166:169], v[212:215], v[10:13]
	v_mfma_f32_16x16x32_bf16 v[2:5], v[174:177], v[212:215], v[2:5]
	s_barrier
	s_setprio 0
	s_add_i32 s59, s59, 2
	s_add_u32 s18, s18, 0x100
	s_addc_u32 s19, s19, 0
	s_add_u32 s49, s49, 0x100
	s_addc_u32 s58, s58, 0
	s_cmp_gt_u32 s59, 29
	s_cbranch_scc0 .LBB0_837
	s_and_b64 vcc, exec, s[6:7]
	s_cbranch_vccz .LBB0_840
	s_barrier

.LBB0_969:
	s_add_u32 s49, s16, 0x100
	v_mov_b32_e32 v2, 0
	s_addc_u32 s58, s17, 0
	s_mov_b32 s59, -2
	v_mov_b32_e32 v3, v2
	v_pk_mov_b32 v[4:5], v[2:3], v[2:3] op_sel:[0,1]
	v_pk_mov_b32 v[6:7], v[2:3], v[2:3] op_sel:[0,1]
	v_pk_mov_b32 v[8:9], v[2:3], v[2:3] op_sel:[0,1]
	v_pk_mov_b32 v[18:19], v[2:3], v[2:3] op_sel:[0,1]
	v_pk_mov_b32 v[20:21], v[2:3], v[2:3] op_sel:[0,1]
	v_pk_mov_b32 v[22:23], v[2:3], v[2:3] op_sel:[0,1]
	v_pk_mov_b32 v[24:25], v[2:3], v[2:3] op_sel:[0,1]
	v_pk_mov_b32 v[34:35], v[2:3], v[2:3] op_sel:[0,1]
	v_pk_mov_b32 v[36:37], v[2:3], v[2:3] op_sel:[0,1]
	v_pk_mov_b32 v[38:39], v[2:3], v[2:3] op_sel:[0,1]
	v_pk_mov_b32 v[40:41], v[2:3], v[2:3] op_sel:[0,1]
	v_pk_mov_b32 v[50:51], v[2:3], v[2:3] op_sel:[0,1]
	v_pk_mov_b32 v[52:53], v[2:3], v[2:3] op_sel:[0,1]
	v_pk_mov_b32 v[54:55], v[2:3], v[2:3] op_sel:[0,1]
	v_pk_mov_b32 v[56:57], v[2:3], v[2:3] op_sel:[0,1]
	v_pk_mov_b32 v[10:11], v[2:3], v[2:3] op_sel:[0,1]
	v_pk_mov_b32 v[12:13], v[2:3], v[2:3] op_sel:[0,1]
	v_pk_mov_b32 v[14:15], v[2:3], v[2:3] op_sel:[0,1]
	v_pk_mov_b32 v[16:17], v[2:3], v[2:3] op_sel:[0,1]
	v_pk_mov_b32 v[26:27], v[2:3], v[2:3] op_sel:[0,1]
	v_pk_mov_b32 v[28:29], v[2:3], v[2:3] op_sel:[0,1]
	v_pk_mov_b32 v[30:31], v[2:3], v[2:3] op_sel:[0,1]
	v_pk_mov_b32 v[32:33], v[2:3], v[2:3] op_sel:[0,1]
	v_pk_mov_b32 v[42:43], v[2:3], v[2:3] op_sel:[0,1]
	v_pk_mov_b32 v[44:45], v[2:3], v[2:3] op_sel:[0,1]
	v_pk_mov_b32 v[46:47], v[2:3], v[2:3] op_sel:[0,1]
	v_pk_mov_b32 v[48:49], v[2:3], v[2:3] op_sel:[0,1]
	v_pk_mov_b32 v[58:59], v[2:3], v[2:3] op_sel:[0,1]
	v_pk_mov_b32 v[60:61], v[2:3], v[2:3] op_sel:[0,1]
	v_pk_mov_b32 v[62:63], v[2:3], v[2:3] op_sel:[0,1]
	v_pk_mov_b32 v[64:65], v[2:3], v[2:3] op_sel:[0,1]
	v_pk_mov_b32 v[66:67], v[2:3], v[2:3] op_sel:[0,1]
	v_pk_mov_b32 v[68:69], v[2:3], v[2:3] op_sel:[0,1]
	v_pk_mov_b32 v[70:71], v[2:3], v[2:3] op_sel:[0,1]
	v_pk_mov_b32 v[72:73], v[2:3], v[2:3] op_sel:[0,1]
	v_pk_mov_b32 v[90:91], v[2:3], v[2:3] op_sel:[0,1]
	v_pk_mov_b32 v[92:93], v[2:3], v[2:3] op_sel:[0,1]
	v_pk_mov_b32 v[102:103], v[2:3], v[2:3] op_sel:[0,1]
	v_pk_mov_b32 v[104:105], v[2:3], v[2:3] op_sel:[0,1]
	v_pk_mov_b32 v[122:123], v[2:3], v[2:3] op_sel:[0,1]
	v_pk_mov_b32 v[124:125], v[2:3], v[2:3] op_sel:[0,1]
	v_pk_mov_b32 v[130:131], v[2:3], v[2:3] op_sel:[0,1]
	v_pk_mov_b32 v[132:133], v[2:3], v[2:3] op_sel:[0,1]
	v_pk_mov_b32 v[150:151], v[2:3], v[2:3] op_sel:[0,1]
	v_pk_mov_b32 v[152:153], v[2:3], v[2:3] op_sel:[0,1]
	v_pk_mov_b32 v[154:155], v[2:3], v[2:3] op_sel:[0,1]
	v_pk_mov_b32 v[156:157], v[2:3], v[2:3] op_sel:[0,1]
	v_pk_mov_b32 v[74:75], v[2:3], v[2:3] op_sel:[0,1]
	v_pk_mov_b32 v[76:77], v[2:3], v[2:3] op_sel:[0,1]
	v_pk_mov_b32 v[86:87], v[2:3], v[2:3] op_sel:[0,1]
	v_pk_mov_b32 v[88:89], v[2:3], v[2:3] op_sel:[0,1]
	v_pk_mov_b32 v[114:115], v[2:3], v[2:3] op_sel:[0,1]
	v_pk_mov_b32 v[116:117], v[2:3], v[2:3] op_sel:[0,1]
	v_pk_mov_b32 v[118:119], v[2:3], v[2:3] op_sel:[0,1]
	v_pk_mov_b32 v[120:121], v[2:3], v[2:3] op_sel:[0,1]
	v_pk_mov_b32 v[138:139], v[2:3], v[2:3] op_sel:[0,1]
	v_pk_mov_b32 v[140:141], v[2:3], v[2:3] op_sel:[0,1]
	v_pk_mov_b32 v[142:143], v[2:3], v[2:3] op_sel:[0,1]
	v_pk_mov_b32 v[144:145], v[2:3], v[2:3] op_sel:[0,1]
	v_pk_mov_b32 v[162:163], v[2:3], v[2:3] op_sel:[0,1]
	v_pk_mov_b32 v[164:165], v[2:3], v[2:3] op_sel:[0,1]
	v_pk_mov_b32 v[170:171], v[2:3], v[2:3] op_sel:[0,1]
	v_pk_mov_b32 v[172:173], v[2:3], v[2:3] op_sel:[0,1]
	.p2align 6
.LBB0_970:
	s_add_u32 s16, s2, 0x100
	s_addc_u32 s17, s3, 0
	s_add_i32 s0, 0, 0x10000
	s_cmpk_eq_i32 s59, 0x54
	s_cselect_b32 s21, s7, s17
	s_cselect_b32 s20, s6, s16
	s_cselect_b32 s19, s15, s58
	s_cselect_b32 s18, s14, s49
	s_add_i32 s33, 0, 0x14000
	ds_read_b128 v[78:81], v205
	ds_read_b128 v[82:85], v205 offset:1024
	ds_read_b128 v[94:97], v205 offset:2048
	ds_read_b128 v[98:101], v205 offset:3072
	ds_read_b128 v[106:109], v205 offset:16384
	ds_read_b128 v[110:113], v205 offset:17408
	ds_read_b128 v[126:129], v205 offset:18432
	ds_read_b128 v[134:137], v205 offset:19456
	s_add_i32 m0, s25, 0xc000
	ds_read_b128 v[146:149], v239
	ds_read_b128 v[158:161], v239 offset:1024
	ds_read_b128 v[166:169], v239 offset:2048
	ds_read_b128 v[174:177], v239 offset:3072
	ds_read_b128 v[178:181], v239 offset:4096
	ds_read_b128 v[182:185], v239 offset:5120
	ds_read_b128 v[186:189], v239 offset:6144
	ds_read_b128 v[190:193], v239 offset:7168
	global_load_lds_dwordx4 v214, s[2:3]
	s_add_i32 m0, s25, 0xe000
	s_nop 0
	global_load_lds_dwordx4 v216, s[2:3]
	.p2align 3
	s_waitcnt vmcnt(8)
	s_waitcnt lgkmcnt(0)
	s_setprio 1
	s_barrier
	v_mfma_f32_16x16x32_bf16 v[170:173], v[78:81], v[146:149], v[170:173]
	v_mfma_f32_16x16x32_bf16 v[162:165], v[94:97], v[146:149], v[162:165]
	v_mfma_f32_16x16x32_bf16 v[142:145], v[78:81], v[166:169], v[142:145]
	v_mfma_f32_16x16x32_bf16 v[138:141], v[94:97], v[166:169], v[138:141]
	v_mfma_f32_16x16x32_bf16 v[118:121], v[78:81], v[178:181], v[118:121]
	v_mfma_f32_16x16x32_bf16 v[114:117], v[94:97], v[178:181], v[114:117]
	v_mfma_f32_16x16x32_bf16 v[86:89], v[78:81], v[186:189], v[86:89]
	v_mfma_f32_16x16x32_bf16 v[74:77], v[94:97], v[186:189], v[74:77]
	v_mfma_f32_16x16x32_bf16 v[170:173], v[82:85], v[158:161], v[170:173]
	v_mfma_f32_16x16x32_bf16 v[162:165], v[98:101], v[158:161], v[162:165]
	v_mfma_f32_16x16x32_bf16 v[142:145], v[82:85], v[174:177], v[142:145]
	v_mfma_f32_16x16x32_bf16 v[138:141], v[98:101], v[174:177], v[138:141]
	v_mfma_f32_16x16x32_bf16 v[118:121], v[82:85], v[182:185], v[118:121]
	v_mfma_f32_16x16x32_bf16 v[114:117], v[98:101], v[182:185], v[114:117]
	v_mfma_f32_16x16x32_bf16 v[86:89], v[82:85], v[190:193], v[86:89]
	v_mfma_f32_16x16x32_bf16 v[74:77], v[98:101], v[190:193], v[74:77]
	v_mfma_f32_16x16x32_bf16 v[154:157], v[106:109], v[146:149], v[154:157]
	v_mfma_f32_16x16x32_bf16 v[130:133], v[106:109], v[166:169], v[130:133]
	v_mfma_f32_16x16x32_bf16 v[122:125], v[126:129], v[166:169], v[122:125]
	v_mfma_f32_16x16x32_bf16 v[102:105], v[106:109], v[178:181], v[102:105]
	v_mfma_f32_16x16x32_bf16 v[90:93], v[126:129], v[178:181], v[90:93]
	v_mfma_f32_16x16x32_bf16 v[70:73], v[106:109], v[186:189], v[70:73]
	v_mfma_f32_16x16x32_bf16 v[66:69], v[126:129], v[186:189], v[66:69]
	v_mfma_f32_16x16x32_bf16 v[154:157], v[110:113], v[158:161], v[154:157]
	v_mfma_f32_16x16x32_bf16 v[146:149], v[126:129], v[146:149], v[150:153]
	v_mfma_f32_16x16x32_bf16 v[130:133], v[110:113], v[174:177], v[130:133]
	v_mfma_f32_16x16x32_bf16 v[122:125], v[134:137], v[174:177], v[122:125]
	v_mfma_f32_16x16x32_bf16 v[102:105], v[110:113], v[182:185], v[102:105]
	v_mfma_f32_16x16x32_bf16 v[90:93], v[134:137], v[182:185], v[90:93]
	v_mfma_f32_16x16x32_bf16 v[70:73], v[110:113], v[190:193], v[70:73]
	v_mfma_f32_16x16x32_bf16 v[66:69], v[134:137], v[190:193], v[66:69]
	v_mfma_f32_16x16x32_bf16 v[146:149], v[134:137], v[158:161], v[146:149]
	s_barrier
	s_setprio 0
	s_add_i32 s0, s0, s24
	s_mov_b32 m0, s0
	ds_read_b128 v[150:153], v239 offset:16384
	ds_read_b128 v[158:161], v239 offset:17408
	ds_read_b128 v[166:169], v239 offset:18432
	ds_read_b128 v[174:177], v239 offset:19456
	ds_read_b128 v[178:181], v239 offset:20480
	ds_read_b128 v[182:185], v239 offset:21504
	ds_read_b128 v[186:189], v239 offset:22528
	ds_read_b128 v[190:193], v239 offset:23552
	global_load_lds_dwordx4 v202, s[18:19]
	s_add_i32 m0, s0, 0x2000
	s_add_u32 s0, s18, 0x160000
	s_addc_u32 s1, s19, 0
	s_add_i32 s2, s33, s24
	global_load_lds_dwordx4 v208, s[18:19]
	s_mov_b32 m0, s2
	s_nop 0
	global_load_lds_dwordx4 v202, s[0:1]
	s_add_i32 m0, s2, 0x2000
	s_nop 0
	global_load_lds_dwordx4 v208, s[0:1]
	s_mov_b32 m0, s25
	s_nop 0
	global_load_lds_dwordx4 v212, s[20:21]
	s_mov_b32 m0, s26
	s_nop 0
	global_load_lds_dwordx4 v210, s[20:21]
	.p2align 3
	s_waitcnt vmcnt(8)
	s_waitcnt lgkmcnt(0)
	s_setprio 1
	s_barrier
	v_mfma_f32_16x16x32_bf16 v[62:65], v[78:81], v[150:153], v[62:65]
	v_mfma_f32_16x16x32_bf16 v[58:61], v[94:97], v[150:153], v[58:61]
	v_mfma_f32_16x16x32_bf16 v[46:49], v[78:81], v[166:169], v[46:49]
	v_mfma_f32_16x16x32_bf16 v[42:45], v[94:97], v[166:169], v[42:45]
	v_mfma_f32_16x16x32_bf16 v[30:33], v[78:81], v[178:181], v[30:33]
	v_mfma_f32_16x16x32_bf16 v[26:29], v[94:97], v[178:181], v[26:29]
	v_mfma_f32_16x16x32_bf16 v[14:17], v[78:81], v[186:189], v[14:17]
	v_mfma_f32_16x16x32_bf16 v[10:13], v[94:97], v[186:189], v[10:13]
	v_mfma_f32_16x16x32_bf16 v[62:65], v[82:85], v[158:161], v[62:65]
	v_mfma_f32_16x16x32_bf16 v[58:61], v[98:101], v[158:161], v[58:61]
	v_mfma_f32_16x16x32_bf16 v[46:49], v[82:85], v[174:177], v[46:49]
	v_mfma_f32_16x16x32_bf16 v[42:45], v[98:101], v[174:177], v[42:45]
	v_mfma_f32_16x16x32_bf16 v[30:33], v[82:85], v[182:185], v[30:33]
	v_mfma_f32_16x16x32_bf16 v[26:29], v[98:101], v[182:185], v[26:29]
	v_mfma_f32_16x16x32_bf16 v[14:17], v[82:85], v[190:193], v[14:17]
	v_mfma_f32_16x16x32_bf16 v[10:13], v[98:101], v[190:193], v[10:13]
	v_mfma_f32_16x16x32_bf16 v[54:57], v[106:109], v[150:153], v[54:57]
	v_mfma_f32_16x16x32_bf16 v[50:53], v[126:129], v[150:153], v[50:53]
	v_mfma_f32_16x16x32_bf16 v[38:41], v[106:109], v[166:169], v[38:41]
	v_mfma_f32_16x16x32_bf16 v[34:37], v[126:129], v[166:169], v[34:37]
	v_mfma_f32_16x16x32_bf16 v[22:25], v[106:109], v[178:181], v[22:25]
	v_mfma_f32_16x16x32_bf16 v[18:21], v[126:129], v[178:181], v[18:21]
	v_mfma_f32_16x16x32_bf16 v[6:9], v[106:109], v[186:189], v[6:9]
	v_mfma_f32_16x16x32_bf16 v[2:5], v[126:129], v[186:189], v[2:5]
	v_mfma_f32_16x16x32_bf16 v[54:57], v[110:113], v[158:161], v[54:57]
	v_mfma_f32_16x16x32_bf16 v[50:53], v[134:137], v[158:161], v[50:53]
	v_mfma_f32_16x16x32_bf16 v[38:41], v[110:113], v[174:177], v[38:41]
	v_mfma_f32_16x16x32_bf16 v[34:37], v[134:137], v[174:177], v[34:37]
	v_mfma_f32_16x16x32_bf16 v[22:25], v[110:113], v[182:185], v[22:25]
	v_mfma_f32_16x16x32_bf16 v[18:21], v[134:137], v[182:185], v[18:21]
	v_mfma_f32_16x16x32_bf16 v[6:9], v[110:113], v[190:193], v[6:9]
	v_mfma_f32_16x16x32_bf16 v[2:5], v[134:137], v[190:193], v[2:5]
	s_barrier
	s_setprio 0
	s_add_i32 s2, 0, 0x18000
	s_add_i32 s3, 0, 0x1c000
	ds_read_b128 v[78:81], v205 offset:32768
	ds_read_b128 v[82:85], v205 offset:33792
	ds_read_b128 v[94:97], v205 offset:34816
	ds_read_b128 v[98:101], v205 offset:35840
	ds_read_b128 v[106:109], v205 offset:49152
	ds_read_b128 v[110:113], v205 offset:50176
	ds_read_b128 v[126:129], v205 offset:51200
	ds_read_b128 v[134:137], v205 offset:52224
	s_add_u32 s0, s20, 0x160000
	s_addc_u32 s1, s21, 0
	s_mov_b32 m0, s27
	ds_read_b128 v[150:153], v239 offset:32768
	ds_read_b128 v[158:161], v239 offset:33792
	ds_read_b128 v[166:169], v239 offset:34816
	ds_read_b128 v[174:177], v239 offset:35840
	ds_read_b128 v[178:181], v239 offset:36864
	ds_read_b128 v[182:185], v239 offset:37888
	ds_read_b128 v[186:189], v239 offset:38912
	ds_read_b128 v[190:193], v239 offset:39936
	global_load_lds_dwordx4 v212, s[0:1]
	s_mov_b32 m0, s28
	s_nop 0
	global_load_lds_dwordx4 v210, s[0:1]
	.p2align 3
	s_waitcnt vmcnt(8)
	s_waitcnt lgkmcnt(0)
	s_setprio 1
	s_barrier
	v_mfma_f32_16x16x32_bf16 v[170:173], v[78:81], v[150:153], v[170:173]
	v_mfma_f32_16x16x32_bf16 v[162:165], v[94:97], v[150:153], v[162:165]
	v_mfma_f32_16x16x32_bf16 v[142:145], v[78:81], v[166:169], v[142:145]
	v_mfma_f32_16x16x32_bf16 v[138:141], v[94:97], v[166:169], v[138:141]
	v_mfma_f32_16x16x32_bf16 v[118:121], v[78:81], v[178:181], v[118:121]
	v_mfma_f32_16x16x32_bf16 v[114:117], v[94:97], v[178:181], v[114:117]
	v_mfma_f32_16x16x32_bf16 v[86:89], v[78:81], v[186:189], v[86:89]
	v_mfma_f32_16x16x32_bf16 v[74:77], v[94:97], v[186:189], v[74:77]
	v_mfma_f32_16x16x32_bf16 v[170:173], v[82:85], v[158:161], v[170:173]
	v_mfma_f32_16x16x32_bf16 v[162:165], v[98:101], v[158:161], v[162:165]
	v_mfma_f32_16x16x32_bf16 v[142:145], v[82:85], v[174:177], v[142:145]
	v_mfma_f32_16x16x32_bf16 v[138:141], v[98:101], v[174:177], v[138:141]
	v_mfma_f32_16x16x32_bf16 v[118:121], v[82:85], v[182:185], v[118:121]
	v_mfma_f32_16x16x32_bf16 v[114:117], v[98:101], v[182:185], v[114:117]
	v_mfma_f32_16x16x32_bf16 v[86:89], v[82:85], v[190:193], v[86:89]
	v_mfma_f32_16x16x32_bf16 v[74:77], v[98:101], v[190:193], v[74:77]
	v_mfma_f32_16x16x32_bf16 v[154:157], v[106:109], v[150:153], v[154:157]
	v_mfma_f32_16x16x32_bf16 v[146:149], v[126:129], v[150:153], v[146:149]
	v_mfma_f32_16x16x32_bf16 v[130:133], v[106:109], v[166:169], v[130:133]
	v_mfma_f32_16x16x32_bf16 v[122:125], v[126:129], v[166:169], v[122:125]
	v_mfma_f32_16x16x32_bf16 v[102:105], v[106:109], v[178:181], v[102:105]
	v_mfma_f32_16x16x32_bf16 v[90:93], v[126:129], v[178:181], v[90:93]
	v_mfma_f32_16x16x32_bf16 v[70:73], v[106:109], v[186:189], v[70:73]
	v_mfma_f32_16x16x32_bf16 v[66:69], v[126:129], v[186:189], v[66:69]
	v_mfma_f32_16x16x32_bf16 v[154:157], v[110:113], v[158:161], v[154:157]
	v_mfma_f32_16x16x32_bf16 v[150:153], v[134:137], v[158:161], v[146:149]
	v_mfma_f32_16x16x32_bf16 v[130:133], v[110:113], v[174:177], v[130:133]
	v_mfma_f32_16x16x32_bf16 v[122:125], v[134:137], v[174:177], v[122:125]
	v_mfma_f32_16x16x32_bf16 v[102:105], v[110:113], v[182:185], v[102:105]
	v_mfma_f32_16x16x32_bf16 v[90:93], v[134:137], v[182:185], v[90:93]
	v_mfma_f32_16x16x32_bf16 v[70:73], v[110:113], v[190:193], v[70:73]
	v_mfma_f32_16x16x32_bf16 v[66:69], v[134:137], v[190:193], v[66:69]
	s_barrier
	s_setprio 0
	s_add_i32 s0, s2, s24
	s_add_u32 s100, s18, 0x80
	s_addc_u32 s101, s19, 0
	s_mov_b32 m0, s0
	ds_read_b128 v[146:149], v239 offset:49152
	ds_read_b128 v[158:161], v239 offset:50176
	ds_read_b128 v[166:169], v239 offset:51200
	ds_read_b128 v[174:177], v239 offset:52224
	ds_read_b128 v[178:181], v239 offset:53248
	ds_read_b128 v[182:185], v239 offset:54272
	ds_read_b128 v[186:189], v239 offset:55296
	ds_read_b128 v[190:193], v239 offset:56320
	global_load_lds_dwordx4 v202, s[100:101]
	s_add_i32 m0, s0, 0x2000
	s_add_u32 s100, s18, 0x80
	s_addc_u32 s101, s19, 0
	s_add_u32 s0, s18, 0x160080
	s_addc_u32 s1, s19, 0
	s_add_i32 s2, s3, s24
	global_load_lds_dwordx4 v208, s[100:101]
	s_mov_b32 m0, s2
	s_nop 0
	global_load_lds_dwordx4 v202, s[0:1]
	s_add_i32 m0, s2, 0x2000
	s_nop 0
	global_load_lds_dwordx4 v208, s[0:1]
	s_add_u32 s100, s20, 0x80
	s_addc_u32 s101, s21, 0
	s_mov_b32 m0, s31
	s_nop 0
	global_load_lds_dwordx4 v212, s[100:101]
	s_add_u32 s100, s20, 0x80
	s_addc_u32 s101, s21, 0
	s_mov_b32 m0, s34
	s_nop 0
	global_load_lds_dwordx4 v210, s[100:101]
	.p2align 3
	s_waitcnt vmcnt(8)
	s_waitcnt lgkmcnt(0)
	s_setprio 1
	s_barrier
	v_mfma_f32_16x16x32_bf16 v[62:65], v[78:81], v[146:149], v[62:65]
	v_mfma_f32_16x16x32_bf16 v[58:61], v[94:97], v[146:149], v[58:61]
	v_mfma_f32_16x16x32_bf16 v[46:49], v[78:81], v[166:169], v[46:49]
	v_mfma_f32_16x16x32_bf16 v[42:45], v[94:97], v[166:169], v[42:45]
	v_mfma_f32_16x16x32_bf16 v[30:33], v[78:81], v[178:181], v[30:33]
	v_mfma_f32_16x16x32_bf16 v[26:29], v[94:97], v[178:181], v[26:29]
	v_mfma_f32_16x16x32_bf16 v[14:17], v[78:81], v[186:189], v[14:17]
	v_mfma_f32_16x16x32_bf16 v[10:13], v[94:97], v[186:189], v[10:13]
	v_mfma_f32_16x16x32_bf16 v[62:65], v[82:85], v[158:161], v[62:65]
	v_mfma_f32_16x16x32_bf16 v[58:61], v[98:101], v[158:161], v[58:61]
	v_mfma_f32_16x16x32_bf16 v[46:49], v[82:85], v[174:177], v[46:49]
	v_mfma_f32_16x16x32_bf16 v[42:45], v[98:101], v[174:177], v[42:45]
	v_mfma_f32_16x16x32_bf16 v[30:33], v[82:85], v[182:185], v[30:33]
	v_mfma_f32_16x16x32_bf16 v[26:29], v[98:101], v[182:185], v[26:29]
	v_mfma_f32_16x16x32_bf16 v[14:17], v[82:85], v[190:193], v[14:17]
	v_mfma_f32_16x16x32_bf16 v[10:13], v[98:101], v[190:193], v[10:13]
	v_mfma_f32_16x16x32_bf16 v[54:57], v[106:109], v[146:149], v[54:57]
	v_mfma_f32_16x16x32_bf16 v[50:53], v[126:129], v[146:149], v[50:53]
	v_mfma_f32_16x16x32_bf16 v[38:41], v[106:109], v[166:169], v[38:41]
	v_mfma_f32_16x16x32_bf16 v[34:37], v[126:129], v[166:169], v[34:37]
	v_mfma_f32_16x16x32_bf16 v[22:25], v[106:109], v[178:181], v[22:25]
	v_mfma_f32_16x16x32_bf16 v[18:21], v[126:129], v[178:181], v[18:21]
	v_mfma_f32_16x16x32_bf16 v[6:9], v[106:109], v[186:189], v[6:9]
	v_mfma_f32_16x16x32_bf16 v[2:5], v[126:129], v[186:189], v[2:5]
	v_mfma_f32_16x16x32_bf16 v[54:57], v[110:113], v[158:161], v[54:57]
	v_mfma_f32_16x16x32_bf16 v[50:53], v[134:137], v[158:161], v[50:53]
	v_mfma_f32_16x16x32_bf16 v[38:41], v[110:113], v[174:177], v[38:41]
	v_mfma_f32_16x16x32_bf16 v[34:37], v[134:137], v[174:177], v[34:37]
	v_mfma_f32_16x16x32_bf16 v[22:25], v[110:113], v[182:185], v[22:25]
	v_mfma_f32_16x16x32_bf16 v[18:21], v[134:137], v[182:185], v[18:21]
	v_mfma_f32_16x16x32_bf16 v[6:9], v[110:113], v[190:193], v[6:9]
	v_mfma_f32_16x16x32_bf16 v[2:5], v[134:137], v[190:193], v[2:5]
	s_barrier
	s_setprio 0
	s_add_i32 s59, s59, 2
	s_add_u32 s49, s49, 0x100
	s_addc_u32 s58, s58, 0
	s_cmpk_gt_u32 s59, 0x55
	s_mov_b64 s[2:3], s[16:17]
	s_cbranch_scc0 .LBB0_970
	s_and_b64 vcc, exec, s[10:11]
	s_cbranch_vccz .LBB0_973
	s_barrier

.LBB0_989:
	s_add_u32 s49, s4, 0x100
	v_mov_b32_e32 v2, 0
	s_addc_u32 s58, s5, 0
	s_mov_b32 s59, -2
	v_mov_b32_e32 v3, v2
	v_pk_mov_b32 v[4:5], v[2:3], v[2:3] op_sel:[0,1]
	v_pk_mov_b32 v[6:7], v[2:3], v[2:3] op_sel:[0,1]
	v_pk_mov_b32 v[8:9], v[2:3], v[2:3] op_sel:[0,1]
	v_pk_mov_b32 v[10:11], v[2:3], v[2:3] op_sel:[0,1]
	v_pk_mov_b32 v[12:13], v[2:3], v[2:3] op_sel:[0,1]
	v_pk_mov_b32 v[14:15], v[2:3], v[2:3] op_sel:[0,1]
	v_pk_mov_b32 v[16:17], v[2:3], v[2:3] op_sel:[0,1]
	v_pk_mov_b32 v[26:27], v[2:3], v[2:3] op_sel:[0,1]
	v_pk_mov_b32 v[28:29], v[2:3], v[2:3] op_sel:[0,1]
	v_pk_mov_b32 v[30:31], v[2:3], v[2:3] op_sel:[0,1]
	v_pk_mov_b32 v[32:33], v[2:3], v[2:3] op_sel:[0,1]
	v_pk_mov_b32 v[42:43], v[2:3], v[2:3] op_sel:[0,1]
	v_pk_mov_b32 v[44:45], v[2:3], v[2:3] op_sel:[0,1]
	v_pk_mov_b32 v[46:47], v[2:3], v[2:3] op_sel:[0,1]
	v_pk_mov_b32 v[48:49], v[2:3], v[2:3] op_sel:[0,1]
	v_pk_mov_b32 v[18:19], v[2:3], v[2:3] op_sel:[0,1]
	v_pk_mov_b32 v[20:21], v[2:3], v[2:3] op_sel:[0,1]
	v_pk_mov_b32 v[22:23], v[2:3], v[2:3] op_sel:[0,1]
	v_pk_mov_b32 v[24:25], v[2:3], v[2:3] op_sel:[0,1]
	v_pk_mov_b32 v[34:35], v[2:3], v[2:3] op_sel:[0,1]
	v_pk_mov_b32 v[36:37], v[2:3], v[2:3] op_sel:[0,1]
	v_pk_mov_b32 v[38:39], v[2:3], v[2:3] op_sel:[0,1]
	v_pk_mov_b32 v[40:41], v[2:3], v[2:3] op_sel:[0,1]
	v_pk_mov_b32 v[50:51], v[2:3], v[2:3] op_sel:[0,1]
	v_pk_mov_b32 v[52:53], v[2:3], v[2:3] op_sel:[0,1]
	v_pk_mov_b32 v[54:55], v[2:3], v[2:3] op_sel:[0,1]
	v_pk_mov_b32 v[56:57], v[2:3], v[2:3] op_sel:[0,1]
	v_pk_mov_b32 v[58:59], v[2:3], v[2:3] op_sel:[0,1]
	v_pk_mov_b32 v[60:61], v[2:3], v[2:3] op_sel:[0,1]
	v_pk_mov_b32 v[62:63], v[2:3], v[2:3] op_sel:[0,1]
	v_pk_mov_b32 v[64:65], v[2:3], v[2:3] op_sel:[0,1]
	v_pk_mov_b32 v[66:67], v[2:3], v[2:3] op_sel:[0,1]
	v_pk_mov_b32 v[68:69], v[2:3], v[2:3] op_sel:[0,1]
	v_pk_mov_b32 v[70:71], v[2:3], v[2:3] op_sel:[0,1]
	v_pk_mov_b32 v[72:73], v[2:3], v[2:3] op_sel:[0,1]
	v_pk_mov_b32 v[74:75], v[2:3], v[2:3] op_sel:[0,1]
	v_pk_mov_b32 v[76:77], v[2:3], v[2:3] op_sel:[0,1]
	v_pk_mov_b32 v[78:79], v[2:3], v[2:3] op_sel:[0,1]
	v_pk_mov_b32 v[80:81], v[2:3], v[2:3] op_sel:[0,1]
	v_pk_mov_b32 v[86:87], v[2:3], v[2:3] op_sel:[0,1]
	v_pk_mov_b32 v[88:89], v[2:3], v[2:3] op_sel:[0,1]
	v_pk_mov_b32 v[94:95], v[2:3], v[2:3] op_sel:[0,1]
	v_pk_mov_b32 v[96:97], v[2:3], v[2:3] op_sel:[0,1]
	v_pk_mov_b32 v[102:103], v[2:3], v[2:3] op_sel:[0,1]
	v_pk_mov_b32 v[104:105], v[2:3], v[2:3] op_sel:[0,1]
	v_pk_mov_b32 v[110:111], v[2:3], v[2:3] op_sel:[0,1]
	v_pk_mov_b32 v[112:113], v[2:3], v[2:3] op_sel:[0,1]
	v_pk_mov_b32 v[82:83], v[2:3], v[2:3] op_sel:[0,1]
	v_pk_mov_b32 v[84:85], v[2:3], v[2:3] op_sel:[0,1]
	v_pk_mov_b32 v[90:91], v[2:3], v[2:3] op_sel:[0,1]
	v_pk_mov_b32 v[92:93], v[2:3], v[2:3] op_sel:[0,1]
	v_pk_mov_b32 v[98:99], v[2:3], v[2:3] op_sel:[0,1]
	v_pk_mov_b32 v[100:101], v[2:3], v[2:3] op_sel:[0,1]
	v_pk_mov_b32 v[106:107], v[2:3], v[2:3] op_sel:[0,1]
	v_pk_mov_b32 v[108:109], v[2:3], v[2:3] op_sel:[0,1]
	v_pk_mov_b32 v[114:115], v[2:3], v[2:3] op_sel:[0,1]
	v_pk_mov_b32 v[116:117], v[2:3], v[2:3] op_sel:[0,1]
	v_pk_mov_b32 v[118:119], v[2:3], v[2:3] op_sel:[0,1]
	v_pk_mov_b32 v[120:121], v[2:3], v[2:3] op_sel:[0,1]
	v_pk_mov_b32 v[122:123], v[2:3], v[2:3] op_sel:[0,1]
	v_pk_mov_b32 v[124:125], v[2:3], v[2:3] op_sel:[0,1]
	v_pk_mov_b32 v[126:127], v[2:3], v[2:3] op_sel:[0,1]
	v_pk_mov_b32 v[128:129], v[2:3], v[2:3] op_sel:[0,1]
	.p2align 6
.LBB0_990:
	s_add_u32 s4, s2, 0x100
	s_addc_u32 s5, s3, 0
	s_add_i32 s0, 0, 0x10000
	s_cmp_eq_u32 s59, 4
	s_cselect_b32 s21, s15, s5
	s_cselect_b32 s20, s14, s4
	s_cselect_b32 s19, s17, s58
	s_cselect_b32 s18, s16, s49
	s_add_i32 s33, 0, 0x14000
	ds_read_b128 v[140:143], v136
	ds_read_b128 v[144:147], v136 offset:1024
	ds_read_b128 v[148:151], v136 offset:2048
	ds_read_b128 v[152:155], v136 offset:3072
	ds_read_b128 v[156:159], v136 offset:16384
	ds_read_b128 v[160:163], v136 offset:17408
	ds_read_b128 v[164:167], v136 offset:18432
	ds_read_b128 v[168:171], v136 offset:19456
	s_add_i32 m0, s25, 0xc000
	ds_read_b128 v[172:175], v139
	ds_read_b128 v[176:179], v139 offset:1024
	ds_read_b128 v[180:183], v139 offset:2048
	ds_read_b128 v[184:187], v139 offset:3072
	ds_read_b128 v[188:191], v139 offset:4096
	ds_read_b128 v[192:195], v139 offset:5120
	ds_read_b128 v[196:199], v139 offset:6144
	ds_read_b128 v[208:211], v139 offset:7168
	global_load_lds_dwordx4 v132, s[2:3]
	s_add_i32 m0, s25, 0xe000
	s_nop 0
	global_load_lds_dwordx4 v134, s[2:3]
	.p2align 3
	s_waitcnt vmcnt(8)
	s_waitcnt lgkmcnt(0)
	s_setprio 1
	s_barrier
	v_mfma_f32_16x16x32_bf16 v[126:129], v[140:143], v[172:175], v[126:129]
	v_mfma_f32_16x16x32_bf16 v[122:125], v[148:151], v[172:175], v[122:125]
	v_mfma_f32_16x16x32_bf16 v[118:121], v[140:143], v[180:183], v[118:121]
	v_mfma_f32_16x16x32_bf16 v[114:117], v[148:151], v[180:183], v[114:117]
	v_mfma_f32_16x16x32_bf16 v[106:109], v[140:143], v[188:191], v[106:109]
	v_mfma_f32_16x16x32_bf16 v[98:101], v[148:151], v[188:191], v[98:101]
	v_mfma_f32_16x16x32_bf16 v[90:93], v[140:143], v[196:199], v[90:93]
	v_mfma_f32_16x16x32_bf16 v[82:85], v[148:151], v[196:199], v[82:85]
	v_mfma_f32_16x16x32_bf16 v[126:129], v[144:147], v[176:179], v[126:129]
	v_mfma_f32_16x16x32_bf16 v[122:125], v[152:155], v[176:179], v[122:125]
	v_mfma_f32_16x16x32_bf16 v[118:121], v[144:147], v[184:187], v[118:121]
	v_mfma_f32_16x16x32_bf16 v[114:117], v[152:155], v[184:187], v[114:117]
	v_mfma_f32_16x16x32_bf16 v[106:109], v[144:147], v[192:195], v[106:109]
	v_mfma_f32_16x16x32_bf16 v[98:101], v[152:155], v[192:195], v[98:101]
	v_mfma_f32_16x16x32_bf16 v[90:93], v[144:147], v[208:211], v[90:93]
	v_mfma_f32_16x16x32_bf16 v[82:85], v[152:155], v[208:211], v[82:85]
	v_mfma_f32_16x16x32_bf16 v[110:113], v[156:159], v[172:175], v[110:113]
	v_mfma_f32_16x16x32_bf16 v[102:105], v[164:167], v[172:175], v[102:105]
	v_mfma_f32_16x16x32_bf16 v[94:97], v[156:159], v[180:183], v[94:97]
	v_mfma_f32_16x16x32_bf16 v[86:89], v[164:167], v[180:183], v[86:89]
	v_mfma_f32_16x16x32_bf16 v[78:81], v[156:159], v[188:191], v[78:81]
	v_mfma_f32_16x16x32_bf16 v[74:77], v[164:167], v[188:191], v[74:77]
	v_mfma_f32_16x16x32_bf16 v[70:73], v[156:159], v[196:199], v[70:73]
	v_mfma_f32_16x16x32_bf16 v[66:69], v[164:167], v[196:199], v[66:69]
	v_mfma_f32_16x16x32_bf16 v[110:113], v[160:163], v[176:179], v[110:113]
	v_mfma_f32_16x16x32_bf16 v[102:105], v[168:171], v[176:179], v[102:105]
	v_mfma_f32_16x16x32_bf16 v[94:97], v[160:163], v[184:187], v[94:97]
	v_mfma_f32_16x16x32_bf16 v[86:89], v[168:171], v[184:187], v[86:89]
	v_mfma_f32_16x16x32_bf16 v[78:81], v[160:163], v[192:195], v[78:81]
	v_mfma_f32_16x16x32_bf16 v[74:77], v[168:171], v[192:195], v[74:77]
	v_mfma_f32_16x16x32_bf16 v[70:73], v[160:163], v[208:211], v[70:73]
	v_mfma_f32_16x16x32_bf16 v[66:69], v[168:171], v[208:211], v[66:69]
	s_barrier
	s_setprio 0
	s_add_i32 s0, s0, s24
	s_mov_b32 m0, s0
	ds_read_b128 v[172:175], v139 offset:16384
	ds_read_b128 v[176:179], v139 offset:17408
	ds_read_b128 v[180:183], v139 offset:18432
	ds_read_b128 v[184:187], v139 offset:19456
	ds_read_b128 v[188:191], v139 offset:20480
	ds_read_b128 v[192:195], v139 offset:21504
	ds_read_b128 v[196:199], v139 offset:22528
	ds_read_b128 v[208:211], v139 offset:23552
	global_load_lds_dwordx4 v202, s[18:19]
	s_add_i32 m0, s0, 0x2000
	s_add_u32 s0, s18, 0x160000
	s_addc_u32 s1, s19, 0
	s_add_i32 s2, s33, s24
	global_load_lds_dwordx4 v130, s[18:19]
	s_mov_b32 m0, s2
	s_nop 0
	global_load_lds_dwordx4 v202, s[0:1]
	s_add_i32 m0, s2, 0x2000
	s_nop 0
	global_load_lds_dwordx4 v130, s[0:1]
	s_mov_b32 m0, s25
	s_nop 0
	global_load_lds_dwordx4 v202, s[20:21]
	s_mov_b32 m0, s26
	s_nop 0
	global_load_lds_dwordx4 v130, s[20:21]
	.p2align 3
	s_waitcnt vmcnt(8)
	s_waitcnt lgkmcnt(0)
	s_setprio 1
	s_barrier
	v_mfma_f32_16x16x32_bf16 v[62:65], v[140:143], v[172:175], v[62:65]
	v_mfma_f32_16x16x32_bf16 v[58:61], v[148:151], v[172:175], v[58:61]
	v_mfma_f32_16x16x32_bf16 v[54:57], v[140:143], v[180:183], v[54:57]
	v_mfma_f32_16x16x32_bf16 v[50:53], v[148:151], v[180:183], v[50:53]
	v_mfma_f32_16x16x32_bf16 v[38:41], v[140:143], v[188:191], v[38:41]
	v_mfma_f32_16x16x32_bf16 v[34:37], v[148:151], v[188:191], v[34:37]
	v_mfma_f32_16x16x32_bf16 v[22:25], v[140:143], v[196:199], v[22:25]
	v_mfma_f32_16x16x32_bf16 v[18:21], v[148:151], v[196:199], v[18:21]
	v_mfma_f32_16x16x32_bf16 v[62:65], v[144:147], v[176:179], v[62:65]
	v_mfma_f32_16x16x32_bf16 v[58:61], v[152:155], v[176:179], v[58:61]
	v_mfma_f32_16x16x32_bf16 v[54:57], v[144:147], v[184:187], v[54:57]
	v_mfma_f32_16x16x32_bf16 v[50:53], v[152:155], v[184:187], v[50:53]
	v_mfma_f32_16x16x32_bf16 v[38:41], v[144:147], v[192:195], v[38:41]
	v_mfma_f32_16x16x32_bf16 v[34:37], v[152:155], v[192:195], v[34:37]
	v_mfma_f32_16x16x32_bf16 v[22:25], v[144:147], v[208:211], v[22:25]
	v_mfma_f32_16x16x32_bf16 v[18:21], v[152:155], v[208:211], v[18:21]
	v_mfma_f32_16x16x32_bf16 v[46:49], v[156:159], v[172:175], v[46:49]
	v_mfma_f32_16x16x32_bf16 v[42:45], v[164:167], v[172:175], v[42:45]
	v_mfma_f32_16x16x32_bf16 v[30:33], v[156:159], v[180:183], v[30:33]
	v_mfma_f32_16x16x32_bf16 v[26:29], v[164:167], v[180:183], v[26:29]
	v_mfma_f32_16x16x32_bf16 v[14:17], v[156:159], v[188:191], v[14:17]
	v_mfma_f32_16x16x32_bf16 v[10:13], v[164:167], v[188:191], v[10:13]
	v_mfma_f32_16x16x32_bf16 v[6:9], v[156:159], v[196:199], v[6:9]
	v_mfma_f32_16x16x32_bf16 v[2:5], v[164:167], v[196:199], v[2:5]
	v_mfma_f32_16x16x32_bf16 v[46:49], v[160:163], v[176:179], v[46:49]
	v_mfma_f32_16x16x32_bf16 v[42:45], v[168:171], v[176:179], v[42:45]
	v_mfma_f32_16x16x32_bf16 v[30:33], v[160:163], v[184:187], v[30:33]
	v_mfma_f32_16x16x32_bf16 v[26:29], v[168:171], v[184:187], v[26:29]
	v_mfma_f32_16x16x32_bf16 v[14:17], v[160:163], v[192:195], v[14:17]
	v_mfma_f32_16x16x32_bf16 v[10:13], v[168:171], v[192:195], v[10:13]
	v_mfma_f32_16x16x32_bf16 v[6:9], v[160:163], v[208:211], v[6:9]
	v_mfma_f32_16x16x32_bf16 v[2:5], v[168:171], v[208:211], v[2:5]
	s_barrier
	s_setprio 0
	s_add_i32 s2, 0, 0x18000
	s_add_i32 s3, 0, 0x1c000
	ds_read_b128 v[140:143], v136 offset:32768
	ds_read_b128 v[144:147], v136 offset:33792
	ds_read_b128 v[148:151], v136 offset:34816
	ds_read_b128 v[152:155], v136 offset:35840
	ds_read_b128 v[156:159], v136 offset:49152
	ds_read_b128 v[160:163], v136 offset:50176
	ds_read_b128 v[164:167], v136 offset:51200
	ds_read_b128 v[168:171], v136 offset:52224
	s_add_u32 s0, s20, 0x160000
	s_addc_u32 s1, s21, 0
	s_mov_b32 m0, s27
	ds_read_b128 v[172:175], v139 offset:32768
	ds_read_b128 v[176:179], v139 offset:33792
	ds_read_b128 v[180:183], v139 offset:34816
	ds_read_b128 v[184:187], v139 offset:35840
	ds_read_b128 v[188:191], v139 offset:36864
	ds_read_b128 v[192:195], v139 offset:37888
	ds_read_b128 v[196:199], v139 offset:38912
	ds_read_b128 v[208:211], v139 offset:39936
	global_load_lds_dwordx4 v202, s[0:1]
	s_mov_b32 m0, s28
	s_nop 0
	global_load_lds_dwordx4 v130, s[0:1]
	.p2align 3
	s_waitcnt vmcnt(8)
	s_waitcnt lgkmcnt(0)
	s_setprio 1
	s_barrier
	v_mfma_f32_16x16x32_bf16 v[126:129], v[140:143], v[172:175], v[126:129]
	v_mfma_f32_16x16x32_bf16 v[122:125], v[148:151], v[172:175], v[122:125]
	v_mfma_f32_16x16x32_bf16 v[118:121], v[140:143], v[180:183], v[118:121]
	v_mfma_f32_16x16x32_bf16 v[114:117], v[148:151], v[180:183], v[114:117]
	v_mfma_f32_16x16x32_bf16 v[106:109], v[140:143], v[188:191], v[106:109]
	v_mfma_f32_16x16x32_bf16 v[98:101], v[148:151], v[188:191], v[98:101]
	v_mfma_f32_16x16x32_bf16 v[90:93], v[140:143], v[196:199], v[90:93]
	v_mfma_f32_16x16x32_bf16 v[82:85], v[148:151], v[196:199], v[82:85]
	v_mfma_f32_16x16x32_bf16 v[126:129], v[144:147], v[176:179], v[126:129]
	v_mfma_f32_16x16x32_bf16 v[122:125], v[152:155], v[176:179], v[122:125]
	v_mfma_f32_16x16x32_bf16 v[118:121], v[144:147], v[184:187], v[118:121]
	v_mfma_f32_16x16x32_bf16 v[114:117], v[152:155], v[184:187], v[114:117]
	v_mfma_f32_16x16x32_bf16 v[106:109], v[144:147], v[192:195], v[106:109]
	v_mfma_f32_16x16x32_bf16 v[98:101], v[152:155], v[192:195], v[98:101]
	v_mfma_f32_16x16x32_bf16 v[90:93], v[144:147], v[208:211], v[90:93]
	v_mfma_f32_16x16x32_bf16 v[82:85], v[152:155], v[208:211], v[82:85]
	v_mfma_f32_16x16x32_bf16 v[110:113], v[156:159], v[172:175], v[110:113]
	v_mfma_f32_16x16x32_bf16 v[102:105], v[164:167], v[172:175], v[102:105]
	v_mfma_f32_16x16x32_bf16 v[94:97], v[156:159], v[180:183], v[94:97]
	v_mfma_f32_16x16x32_bf16 v[86:89], v[164:167], v[180:183], v[86:89]
	v_mfma_f32_16x16x32_bf16 v[78:81], v[156:159], v[188:191], v[78:81]
	v_mfma_f32_16x16x32_bf16 v[74:77], v[164:167], v[188:191], v[74:77]
	v_mfma_f32_16x16x32_bf16 v[70:73], v[156:159], v[196:199], v[70:73]
	v_mfma_f32_16x16x32_bf16 v[66:69], v[164:167], v[196:199], v[66:69]
	v_mfma_f32_16x16x32_bf16 v[110:113], v[160:163], v[176:179], v[110:113]
	v_mfma_f32_16x16x32_bf16 v[102:105], v[168:171], v[176:179], v[102:105]
	v_mfma_f32_16x16x32_bf16 v[94:97], v[160:163], v[184:187], v[94:97]
	v_mfma_f32_16x16x32_bf16 v[86:89], v[168:171], v[184:187], v[86:89]
	v_mfma_f32_16x16x32_bf16 v[78:81], v[160:163], v[192:195], v[78:81]
	v_mfma_f32_16x16x32_bf16 v[74:77], v[168:171], v[192:195], v[74:77]
	v_mfma_f32_16x16x32_bf16 v[70:73], v[160:163], v[208:211], v[70:73]
	v_mfma_f32_16x16x32_bf16 v[66:69], v[168:171], v[208:211], v[66:69]
	s_barrier
	s_setprio 0
	s_add_i32 s0, s2, s24
	s_add_u32 s100, s18, 0x80
	s_addc_u32 s101, s19, 0
	s_mov_b32 m0, s0
	ds_read_b128 v[172:175], v139 offset:49152
	ds_read_b128 v[176:179], v139 offset:50176
	ds_read_b128 v[180:183], v139 offset:51200
	ds_read_b128 v[184:187], v139 offset:52224
	ds_read_b128 v[188:191], v139 offset:53248
	ds_read_b128 v[192:195], v139 offset:54272
	ds_read_b128 v[196:199], v139 offset:55296
	ds_read_b128 v[208:211], v139 offset:56320
	global_load_lds_dwordx4 v202, s[100:101]
	s_add_i32 m0, s0, 0x2000
	s_add_u32 s100, s18, 0x80
	s_addc_u32 s101, s19, 0
	s_add_u32 s0, s18, 0x160080
	s_addc_u32 s1, s19, 0
	s_add_i32 s2, s3, s24
	global_load_lds_dwordx4 v130, s[100:101]
	s_mov_b32 m0, s2
	s_nop 0
	global_load_lds_dwordx4 v202, s[0:1]
	s_add_i32 m0, s2, 0x2000
	s_nop 0
	global_load_lds_dwordx4 v130, s[0:1]
	s_add_u32 s100, s20, 0x80
	s_addc_u32 s101, s21, 0
	s_mov_b32 m0, s29
	s_nop 0
	global_load_lds_dwordx4 v202, s[100:101]
	s_add_u32 s100, s20, 0x80
	s_addc_u32 s101, s21, 0
	s_mov_b32 m0, s30
	s_nop 0
	global_load_lds_dwordx4 v130, s[100:101]
	.p2align 3
	s_waitcnt vmcnt(8)
	s_waitcnt lgkmcnt(0)
	s_setprio 1
	s_barrier
	v_mfma_f32_16x16x32_bf16 v[62:65], v[140:143], v[172:175], v[62:65]
	v_mfma_f32_16x16x32_bf16 v[58:61], v[148:151], v[172:175], v[58:61]
	v_mfma_f32_16x16x32_bf16 v[54:57], v[140:143], v[180:183], v[54:57]
	v_mfma_f32_16x16x32_bf16 v[50:53], v[148:151], v[180:183], v[50:53]
	v_mfma_f32_16x16x32_bf16 v[38:41], v[140:143], v[188:191], v[38:41]
	v_mfma_f32_16x16x32_bf16 v[34:37], v[148:151], v[188:191], v[34:37]
	v_mfma_f32_16x16x32_bf16 v[22:25], v[140:143], v[196:199], v[22:25]
	v_mfma_f32_16x16x32_bf16 v[18:21], v[148:151], v[196:199], v[18:21]
	v_mfma_f32_16x16x32_bf16 v[62:65], v[144:147], v[176:179], v[62:65]
	v_mfma_f32_16x16x32_bf16 v[58:61], v[152:155], v[176:179], v[58:61]
	v_mfma_f32_16x16x32_bf16 v[54:57], v[144:147], v[184:187], v[54:57]
	v_mfma_f32_16x16x32_bf16 v[50:53], v[152:155], v[184:187], v[50:53]
	v_mfma_f32_16x16x32_bf16 v[38:41], v[144:147], v[192:195], v[38:41]
	v_mfma_f32_16x16x32_bf16 v[34:37], v[152:155], v[192:195], v[34:37]
	v_mfma_f32_16x16x32_bf16 v[22:25], v[144:147], v[208:211], v[22:25]
	v_mfma_f32_16x16x32_bf16 v[18:21], v[152:155], v[208:211], v[18:21]
	v_mfma_f32_16x16x32_bf16 v[46:49], v[156:159], v[172:175], v[46:49]
	v_mfma_f32_16x16x32_bf16 v[42:45], v[164:167], v[172:175], v[42:45]
	v_mfma_f32_16x16x32_bf16 v[30:33], v[156:159], v[180:183], v[30:33]
	v_mfma_f32_16x16x32_bf16 v[26:29], v[164:167], v[180:183], v[26:29]
	v_mfma_f32_16x16x32_bf16 v[14:17], v[156:159], v[188:191], v[14:17]
	v_mfma_f32_16x16x32_bf16 v[10:13], v[164:167], v[188:191], v[10:13]
	v_mfma_f32_16x16x32_bf16 v[6:9], v[156:159], v[196:199], v[6:9]
	v_mfma_f32_16x16x32_bf16 v[2:5], v[164:167], v[196:199], v[2:5]
	v_mfma_f32_16x16x32_bf16 v[46:49], v[160:163], v[176:179], v[46:49]
	v_mfma_f32_16x16x32_bf16 v[42:45], v[168:171], v[176:179], v[42:45]
	v_mfma_f32_16x16x32_bf16 v[30:33], v[160:163], v[184:187], v[30:33]
	v_mfma_f32_16x16x32_bf16 v[26:29], v[168:171], v[184:187], v[26:29]
	v_mfma_f32_16x16x32_bf16 v[14:17], v[160:163], v[192:195], v[14:17]
	v_mfma_f32_16x16x32_bf16 v[10:13], v[168:171], v[192:195], v[10:13]
	v_mfma_f32_16x16x32_bf16 v[6:9], v[160:163], v[208:211], v[6:9]
	v_mfma_f32_16x16x32_bf16 v[2:5], v[168:171], v[208:211], v[2:5]
	s_barrier
	s_setprio 0
	s_add_i32 s59, s59, 2
	s_add_u32 s49, s49, 0x100
	s_addc_u32 s58, s58, 0
	s_cmp_gt_u32 s59, 5
	s_mov_b64 s[2:3], s[4:5]
	s_cbranch_scc0 .LBB0_990
	s_and_b64 vcc, exec, s[10:11]
	s_cbranch_vccz .LBB0_993
	s_barrier

.LBB0_1114:
	s_ashr_i32 s17, s16, 31
	s_lshl_b64 s[0:1], s[16:17], 20
	s_add_u32 s18, s42, s0
	s_addc_u32 s19, s43, s1
	s_and_b64 s[0:1], s[6:7], exec
	s_cselect_b32 s17, s19, s5
	s_cselect_b32 s39, s18, s4
	s_ashr_i32 s15, s14, 31
	s_lshl_b64 s[0:1], s[14:15], 20
	s_add_u32 s20, s24, s0
	s_addc_u32 s21, s25, s1
	s_and_b64 s[0:1], s[6:7], exec
	s_cselect_b32 s15, s21, s3
	s_cselect_b32 s40, s20, s2
	s_add_u32 s22, s4, 0x80080
	s_addc_u32 s23, s5, 0
	s_add_u32 s41, s2, 0x100
	v_mov_b32_e32 v2, 0
	s_addc_u32 s49, s3, 0
	s_mov_b32 s58, -2
	v_mov_b32_e32 v3, v2
	v_pk_mov_b32 v[4:5], v[2:3], v[2:3] op_sel:[0,1]
	v_pk_mov_b32 v[6:7], v[2:3], v[2:3] op_sel:[0,1]
	v_pk_mov_b32 v[8:9], v[2:3], v[2:3] op_sel:[0,1]
	v_pk_mov_b32 v[18:19], v[2:3], v[2:3] op_sel:[0,1]
	v_pk_mov_b32 v[20:21], v[2:3], v[2:3] op_sel:[0,1]
	v_pk_mov_b32 v[22:23], v[2:3], v[2:3] op_sel:[0,1]
	v_pk_mov_b32 v[24:25], v[2:3], v[2:3] op_sel:[0,1]
	v_pk_mov_b32 v[34:35], v[2:3], v[2:3] op_sel:[0,1]
	v_pk_mov_b32 v[36:37], v[2:3], v[2:3] op_sel:[0,1]
	v_pk_mov_b32 v[38:39], v[2:3], v[2:3] op_sel:[0,1]
	v_pk_mov_b32 v[40:41], v[2:3], v[2:3] op_sel:[0,1]
	v_pk_mov_b32 v[50:51], v[2:3], v[2:3] op_sel:[0,1]
	v_pk_mov_b32 v[52:53], v[2:3], v[2:3] op_sel:[0,1]
	v_pk_mov_b32 v[54:55], v[2:3], v[2:3] op_sel:[0,1]
	v_pk_mov_b32 v[56:57], v[2:3], v[2:3] op_sel:[0,1]
	v_pk_mov_b32 v[10:11], v[2:3], v[2:3] op_sel:[0,1]
	v_pk_mov_b32 v[12:13], v[2:3], v[2:3] op_sel:[0,1]
	v_pk_mov_b32 v[14:15], v[2:3], v[2:3] op_sel:[0,1]
	v_pk_mov_b32 v[16:17], v[2:3], v[2:3] op_sel:[0,1]
	v_pk_mov_b32 v[26:27], v[2:3], v[2:3] op_sel:[0,1]
	v_pk_mov_b32 v[28:29], v[2:3], v[2:3] op_sel:[0,1]
	v_pk_mov_b32 v[30:31], v[2:3], v[2:3] op_sel:[0,1]
	v_pk_mov_b32 v[32:33], v[2:3], v[2:3] op_sel:[0,1]
	v_pk_mov_b32 v[42:43], v[2:3], v[2:3] op_sel:[0,1]
	v_pk_mov_b32 v[44:45], v[2:3], v[2:3] op_sel:[0,1]
	v_pk_mov_b32 v[46:47], v[2:3], v[2:3] op_sel:[0,1]
	v_pk_mov_b32 v[48:49], v[2:3], v[2:3] op_sel:[0,1]
	v_pk_mov_b32 v[58:59], v[2:3], v[2:3] op_sel:[0,1]
	v_pk_mov_b32 v[60:61], v[2:3], v[2:3] op_sel:[0,1]
	v_pk_mov_b32 v[62:63], v[2:3], v[2:3] op_sel:[0,1]
	v_pk_mov_b32 v[64:65], v[2:3], v[2:3] op_sel:[0,1]
	v_pk_mov_b32 v[66:67], v[2:3], v[2:3] op_sel:[0,1]
	v_pk_mov_b32 v[68:69], v[2:3], v[2:3] op_sel:[0,1]
	v_pk_mov_b32 v[70:71], v[2:3], v[2:3] op_sel:[0,1]
	v_pk_mov_b32 v[72:73], v[2:3], v[2:3] op_sel:[0,1]
	v_pk_mov_b32 v[82:83], v[2:3], v[2:3] op_sel:[0,1]
	v_pk_mov_b32 v[84:85], v[2:3], v[2:3] op_sel:[0,1]
	v_pk_mov_b32 v[86:87], v[2:3], v[2:3] op_sel:[0,1]
	v_pk_mov_b32 v[88:89], v[2:3], v[2:3] op_sel:[0,1]
	v_pk_mov_b32 v[98:99], v[2:3], v[2:3] op_sel:[0,1]
	v_pk_mov_b32 v[100:101], v[2:3], v[2:3] op_sel:[0,1]
	v_pk_mov_b32 v[102:103], v[2:3], v[2:3] op_sel:[0,1]
	v_pk_mov_b32 v[104:105], v[2:3], v[2:3] op_sel:[0,1]
	v_pk_mov_b32 v[114:115], v[2:3], v[2:3] op_sel:[0,1]
	v_pk_mov_b32 v[116:117], v[2:3], v[2:3] op_sel:[0,1]
	v_pk_mov_b32 v[118:119], v[2:3], v[2:3] op_sel:[0,1]
	v_pk_mov_b32 v[120:121], v[2:3], v[2:3] op_sel:[0,1]
	v_pk_mov_b32 v[74:75], v[2:3], v[2:3] op_sel:[0,1]
	v_pk_mov_b32 v[76:77], v[2:3], v[2:3] op_sel:[0,1]
	v_pk_mov_b32 v[78:79], v[2:3], v[2:3] op_sel:[0,1]
	v_pk_mov_b32 v[80:81], v[2:3], v[2:3] op_sel:[0,1]
	v_pk_mov_b32 v[90:91], v[2:3], v[2:3] op_sel:[0,1]
	v_pk_mov_b32 v[92:93], v[2:3], v[2:3] op_sel:[0,1]
	v_pk_mov_b32 v[94:95], v[2:3], v[2:3] op_sel:[0,1]
	v_pk_mov_b32 v[96:97], v[2:3], v[2:3] op_sel:[0,1]
	v_pk_mov_b32 v[106:107], v[2:3], v[2:3] op_sel:[0,1]
	v_pk_mov_b32 v[108:109], v[2:3], v[2:3] op_sel:[0,1]
	v_pk_mov_b32 v[110:111], v[2:3], v[2:3] op_sel:[0,1]
	v_pk_mov_b32 v[112:113], v[2:3], v[2:3] op_sel:[0,1]
	v_pk_mov_b32 v[122:123], v[2:3], v[2:3] op_sel:[0,1]
	v_pk_mov_b32 v[124:125], v[2:3], v[2:3] op_sel:[0,1]
	v_pk_mov_b32 v[126:127], v[2:3], v[2:3] op_sel:[0,1]
	v_pk_mov_b32 v[128:129], v[2:3], v[2:3] op_sel:[0,1]
	.p2align 6
.LBB0_1115:
	s_add_u32 s0, s22, 0xfff80080
	s_addc_u32 s1, s23, -1
	s_add_i32 s33, 0, 0x10000
	s_cmp_eq_u32 s58, 28
	s_cselect_b32 s5, s17, s1
	s_cselect_b32 s4, s39, s0
	s_cselect_b32 s3, s15, s49
	s_cselect_b32 s2, s40, s41
	s_add_i32 s55, 0, 0x14000
	ds_read_b128 v[148:151], v145
	ds_read_b128 v[152:155], v145 offset:1024
	ds_read_b128 v[156:159], v145 offset:2048
	ds_read_b128 v[160:163], v145 offset:3072
	ds_read_b128 v[164:167], v145 offset:16384
	ds_read_b128 v[168:171], v145 offset:17408
	ds_read_b128 v[172:175], v145 offset:18432
	ds_read_b128 v[176:179], v145 offset:19456
	s_add_i32 m0, s27, 0xc000
	ds_read_b128 v[180:183], v147
	ds_read_b128 v[184:187], v147 offset:1024
	ds_read_b128 v[188:191], v147 offset:2048
	ds_read_b128 v[192:195], v147 offset:3072
	ds_read_b128 v[196:199], v147 offset:4096
	ds_read_b128 v[208:211], v147 offset:5120
	ds_read_b128 v[212:215], v147 offset:6144
	ds_read_b128 v[216:219], v147 offset:7168
	global_load_lds_dwordx4 v138, s[22:23]
	s_add_i32 m0, s27, 0xe000
	s_nop 0
	global_load_lds_dwordx4 v140, s[22:23]
	.p2align 3
	s_waitcnt vmcnt(8)
	s_waitcnt lgkmcnt(0)
	s_setprio 1
	s_barrier
	v_mfma_f32_16x16x32_bf16 v[126:129], v[148:151], v[180:183], v[126:129]
	v_mfma_f32_16x16x32_bf16 v[122:125], v[156:159], v[180:183], v[122:125]
	v_mfma_f32_16x16x32_bf16 v[110:113], v[148:151], v[188:191], v[110:113]
	v_mfma_f32_16x16x32_bf16 v[106:109], v[156:159], v[188:191], v[106:109]
	v_mfma_f32_16x16x32_bf16 v[94:97], v[148:151], v[196:199], v[94:97]
	v_mfma_f32_16x16x32_bf16 v[90:93], v[156:159], v[196:199], v[90:93]
	v_mfma_f32_16x16x32_bf16 v[78:81], v[148:151], v[212:215], v[78:81]
	v_mfma_f32_16x16x32_bf16 v[74:77], v[156:159], v[212:215], v[74:77]
	v_mfma_f32_16x16x32_bf16 v[126:129], v[152:155], v[184:187], v[126:129]
	v_mfma_f32_16x16x32_bf16 v[122:125], v[160:163], v[184:187], v[122:125]
	v_mfma_f32_16x16x32_bf16 v[110:113], v[152:155], v[192:195], v[110:113]
	v_mfma_f32_16x16x32_bf16 v[106:109], v[160:163], v[192:195], v[106:109]
	v_mfma_f32_16x16x32_bf16 v[94:97], v[152:155], v[208:211], v[94:97]
	v_mfma_f32_16x16x32_bf16 v[90:93], v[160:163], v[208:211], v[90:93]
	v_mfma_f32_16x16x32_bf16 v[78:81], v[152:155], v[216:219], v[78:81]
	v_mfma_f32_16x16x32_bf16 v[74:77], v[160:163], v[216:219], v[74:77]
	v_mfma_f32_16x16x32_bf16 v[118:121], v[164:167], v[180:183], v[118:121]
	v_mfma_f32_16x16x32_bf16 v[114:117], v[172:175], v[180:183], v[114:117]
	v_mfma_f32_16x16x32_bf16 v[102:105], v[164:167], v[188:191], v[102:105]
	v_mfma_f32_16x16x32_bf16 v[98:101], v[172:175], v[188:191], v[98:101]
	v_mfma_f32_16x16x32_bf16 v[86:89], v[164:167], v[196:199], v[86:89]
	v_mfma_f32_16x16x32_bf16 v[82:85], v[172:175], v[196:199], v[82:85]
	v_mfma_f32_16x16x32_bf16 v[70:73], v[164:167], v[212:215], v[70:73]
	v_mfma_f32_16x16x32_bf16 v[66:69], v[172:175], v[212:215], v[66:69]
	v_mfma_f32_16x16x32_bf16 v[118:121], v[168:171], v[184:187], v[118:121]
	v_mfma_f32_16x16x32_bf16 v[114:117], v[176:179], v[184:187], v[114:117]
	v_mfma_f32_16x16x32_bf16 v[102:105], v[168:171], v[192:195], v[102:105]
	v_mfma_f32_16x16x32_bf16 v[98:101], v[176:179], v[192:195], v[98:101]
	v_mfma_f32_16x16x32_bf16 v[86:89], v[168:171], v[208:211], v[86:89]
	v_mfma_f32_16x16x32_bf16 v[82:85], v[176:179], v[208:211], v[82:85]
	v_mfma_f32_16x16x32_bf16 v[70:73], v[168:171], v[216:219], v[70:73]
	v_mfma_f32_16x16x32_bf16 v[66:69], v[176:179], v[216:219], v[66:69]
	s_barrier
	s_setprio 0
	s_add_i32 s0, s33, s26
	s_mov_b32 m0, s0
	ds_read_b128 v[180:183], v147 offset:16384
	ds_read_b128 v[184:187], v147 offset:17408
	ds_read_b128 v[188:191], v147 offset:18432
	ds_read_b128 v[192:195], v147 offset:19456
	ds_read_b128 v[196:199], v147 offset:20480
	ds_read_b128 v[208:211], v147 offset:21504
	ds_read_b128 v[212:215], v147 offset:22528
	ds_read_b128 v[216:219], v147 offset:23552
	global_load_lds_dwordx4 v134, s[2:3]
	s_add_i32 m0, s0, 0x2000
	s_add_u32 s0, s2, 0x80000
	s_addc_u32 s1, s3, 0
	s_add_i32 s33, s55, s26
	global_load_lds_dwordx4 v130, s[2:3]
	s_mov_b32 m0, s33
	s_nop 0
	global_load_lds_dwordx4 v134, s[0:1]
	s_add_i32 m0, s33, 0x2000
	s_nop 0
	global_load_lds_dwordx4 v130, s[0:1]
	s_mov_b32 m0, s27
	s_nop 0
	global_load_lds_dwordx4 v136, s[4:5]
	s_mov_b32 m0, s28
	s_nop 0
	global_load_lds_dwordx4 v132, s[4:5]
	.p2align 3
	s_waitcnt vmcnt(8)
	s_waitcnt lgkmcnt(0)
	s_setprio 1
	s_barrier
	v_mfma_f32_16x16x32_bf16 v[62:65], v[148:151], v[180:183], v[62:65]
	v_mfma_f32_16x16x32_bf16 v[58:61], v[156:159], v[180:183], v[58:61]
	v_mfma_f32_16x16x32_bf16 v[46:49], v[148:151], v[188:191], v[46:49]
	v_mfma_f32_16x16x32_bf16 v[42:45], v[156:159], v[188:191], v[42:45]
	v_mfma_f32_16x16x32_bf16 v[30:33], v[148:151], v[196:199], v[30:33]
	v_mfma_f32_16x16x32_bf16 v[26:29], v[156:159], v[196:199], v[26:29]
	v_mfma_f32_16x16x32_bf16 v[14:17], v[148:151], v[212:215], v[14:17]
	v_mfma_f32_16x16x32_bf16 v[10:13], v[156:159], v[212:215], v[10:13]
	v_mfma_f32_16x16x32_bf16 v[62:65], v[152:155], v[184:187], v[62:65]
	v_mfma_f32_16x16x32_bf16 v[58:61], v[160:163], v[184:187], v[58:61]
	v_mfma_f32_16x16x32_bf16 v[46:49], v[152:155], v[192:195], v[46:49]
	v_mfma_f32_16x16x32_bf16 v[42:45], v[160:163], v[192:195], v[42:45]
	v_mfma_f32_16x16x32_bf16 v[30:33], v[152:155], v[208:211], v[30:33]
	v_mfma_f32_16x16x32_bf16 v[26:29], v[160:163], v[208:211], v[26:29]
	v_mfma_f32_16x16x32_bf16 v[14:17], v[152:155], v[216:219], v[14:17]
	v_mfma_f32_16x16x32_bf16 v[10:13], v[160:163], v[216:219], v[10:13]
	v_mfma_f32_16x16x32_bf16 v[54:57], v[164:167], v[180:183], v[54:57]
	v_mfma_f32_16x16x32_bf16 v[50:53], v[172:175], v[180:183], v[50:53]
	v_mfma_f32_16x16x32_bf16 v[38:41], v[164:167], v[188:191], v[38:41]
	v_mfma_f32_16x16x32_bf16 v[34:37], v[172:175], v[188:191], v[34:37]
	v_mfma_f32_16x16x32_bf16 v[22:25], v[164:167], v[196:199], v[22:25]
	v_mfma_f32_16x16x32_bf16 v[18:21], v[172:175], v[196:199], v[18:21]
	v_mfma_f32_16x16x32_bf16 v[6:9], v[164:167], v[212:215], v[6:9]
	v_mfma_f32_16x16x32_bf16 v[2:5], v[172:175], v[212:215], v[2:5]
	v_mfma_f32_16x16x32_bf16 v[54:57], v[168:171], v[184:187], v[54:57]
	v_mfma_f32_16x16x32_bf16 v[50:53], v[176:179], v[184:187], v[50:53]
	v_mfma_f32_16x16x32_bf16 v[38:41], v[168:171], v[192:195], v[38:41]
	v_mfma_f32_16x16x32_bf16 v[34:37], v[176:179], v[192:195], v[34:37]
	v_mfma_f32_16x16x32_bf16 v[22:25], v[168:171], v[208:211], v[22:25]
	v_mfma_f32_16x16x32_bf16 v[18:21], v[176:179], v[208:211], v[18:21]
	v_mfma_f32_16x16x32_bf16 v[6:9], v[168:171], v[216:219], v[6:9]
	v_mfma_f32_16x16x32_bf16 v[2:5], v[176:179], v[216:219], v[2:5]
	s_barrier
	s_setprio 0
	s_add_i32 s33, 0, 0x18000
	s_add_i32 s55, 0, 0x1c000
	ds_read_b128 v[148:151], v145 offset:32768
	ds_read_b128 v[152:155], v145 offset:33792
	ds_read_b128 v[156:159], v145 offset:34816
	ds_read_b128 v[160:163], v145 offset:35840
	ds_read_b128 v[164:167], v145 offset:49152
	ds_read_b128 v[168:171], v145 offset:50176
	ds_read_b128 v[172:175], v145 offset:51200
	ds_read_b128 v[176:179], v145 offset:52224
	s_add_u32 s0, s4, 0x80000
	s_addc_u32 s1, s5, 0
	s_mov_b32 m0, s29
	ds_read_b128 v[180:183], v147 offset:32768
	ds_read_b128 v[184:187], v147 offset:33792
	ds_read_b128 v[188:191], v147 offset:34816
	ds_read_b128 v[192:195], v147 offset:35840
	ds_read_b128 v[196:199], v147 offset:36864
	ds_read_b128 v[208:211], v147 offset:37888
	ds_read_b128 v[212:215], v147 offset:38912
	ds_read_b128 v[216:219], v147 offset:39936
	global_load_lds_dwordx4 v136, s[0:1]
	s_mov_b32 m0, s30
	s_nop 0
	global_load_lds_dwordx4 v132, s[0:1]
	.p2align 3
	s_waitcnt vmcnt(8)
	s_waitcnt lgkmcnt(0)
	s_setprio 1
	s_barrier
	v_mfma_f32_16x16x32_bf16 v[126:129], v[148:151], v[180:183], v[126:129]
	v_mfma_f32_16x16x32_bf16 v[122:125], v[156:159], v[180:183], v[122:125]
	v_mfma_f32_16x16x32_bf16 v[110:113], v[148:151], v[188:191], v[110:113]
	v_mfma_f32_16x16x32_bf16 v[106:109], v[156:159], v[188:191], v[106:109]
	v_mfma_f32_16x16x32_bf16 v[94:97], v[148:151], v[196:199], v[94:97]
	v_mfma_f32_16x16x32_bf16 v[90:93], v[156:159], v[196:199], v[90:93]
	v_mfma_f32_16x16x32_bf16 v[78:81], v[148:151], v[212:215], v[78:81]
	v_mfma_f32_16x16x32_bf16 v[74:77], v[156:159], v[212:215], v[74:77]
	v_mfma_f32_16x16x32_bf16 v[126:129], v[152:155], v[184:187], v[126:129]
	v_mfma_f32_16x16x32_bf16 v[122:125], v[160:163], v[184:187], v[122:125]
	v_mfma_f32_16x16x32_bf16 v[110:113], v[152:155], v[192:195], v[110:113]
	v_mfma_f32_16x16x32_bf16 v[106:109], v[160:163], v[192:195], v[106:109]
	v_mfma_f32_16x16x32_bf16 v[94:97], v[152:155], v[208:211], v[94:97]
	v_mfma_f32_16x16x32_bf16 v[90:93], v[160:163], v[208:211], v[90:93]
	v_mfma_f32_16x16x32_bf16 v[78:81], v[152:155], v[216:219], v[78:81]
	v_mfma_f32_16x16x32_bf16 v[74:77], v[160:163], v[216:219], v[74:77]
	v_mfma_f32_16x16x32_bf16 v[118:121], v[164:167], v[180:183], v[118:121]
	v_mfma_f32_16x16x32_bf16 v[114:117], v[172:175], v[180:183], v[114:117]
	v_mfma_f32_16x16x32_bf16 v[102:105], v[164:167], v[188:191], v[102:105]
	v_mfma_f32_16x16x32_bf16 v[98:101], v[172:175], v[188:191], v[98:101]
	v_mfma_f32_16x16x32_bf16 v[86:89], v[164:167], v[196:199], v[86:89]
	v_mfma_f32_16x16x32_bf16 v[82:85], v[172:175], v[196:199], v[82:85]
	v_mfma_f32_16x16x32_bf16 v[70:73], v[164:167], v[212:215], v[70:73]
	v_mfma_f32_16x16x32_bf16 v[66:69], v[172:175], v[212:215], v[66:69]
	v_mfma_f32_16x16x32_bf16 v[118:121], v[168:171], v[184:187], v[118:121]
	v_mfma_f32_16x16x32_bf16 v[114:117], v[176:179], v[184:187], v[114:117]
	v_mfma_f32_16x16x32_bf16 v[102:105], v[168:171], v[192:195], v[102:105]
	v_mfma_f32_16x16x32_bf16 v[98:101], v[176:179], v[192:195], v[98:101]
	v_mfma_f32_16x16x32_bf16 v[86:89], v[168:171], v[208:211], v[86:89]
	v_mfma_f32_16x16x32_bf16 v[82:85], v[176:179], v[208:211], v[82:85]
	v_mfma_f32_16x16x32_bf16 v[70:73], v[168:171], v[216:219], v[70:73]
	v_mfma_f32_16x16x32_bf16 v[66:69], v[176:179], v[216:219], v[66:69]
	s_barrier
	s_setprio 0
	s_add_i32 s0, s33, s26
	s_add_u32 s100, s2, 0x80
	s_addc_u32 s101, s3, 0
	s_mov_b32 m0, s0
	ds_read_b128 v[180:183], v147 offset:49152
	ds_read_b128 v[184:187], v147 offset:50176
	ds_read_b128 v[188:191], v147 offset:51200
	ds_read_b128 v[192:195], v147 offset:52224
	ds_read_b128 v[196:199], v147 offset:53248
	ds_read_b128 v[208:211], v147 offset:54272
	ds_read_b128 v[212:215], v147 offset:55296
	ds_read_b128 v[216:219], v147 offset:56320
	global_load_lds_dwordx4 v134, s[100:101]
	s_add_i32 m0, s0, 0x2000
	s_add_u32 s100, s2, 0x80
	s_addc_u32 s101, s3, 0
	s_add_u32 s0, s2, 0x80080
	s_addc_u32 s1, s3, 0
	s_add_i32 s2, s55, s26
	global_load_lds_dwordx4 v130, s[100:101]
	s_mov_b32 m0, s2
	s_nop 0
	global_load_lds_dwordx4 v134, s[0:1]
	s_add_i32 m0, s2, 0x2000
	s_nop 0
	global_load_lds_dwordx4 v130, s[0:1]
	s_add_u32 s100, s4, 0x80
	s_addc_u32 s101, s5, 0
	s_mov_b32 m0, s34
	s_nop 0
	global_load_lds_dwordx4 v136, s[100:101]
	s_add_u32 s100, s4, 0x80
	s_addc_u32 s101, s5, 0
	s_mov_b32 m0, s35
	s_nop 0
	global_load_lds_dwordx4 v132, s[100:101]
	.p2align 3
	s_waitcnt vmcnt(8)
	s_waitcnt lgkmcnt(0)
	s_setprio 1
	s_barrier
	v_mfma_f32_16x16x32_bf16 v[62:65], v[148:151], v[180:183], v[62:65]
	v_mfma_f32_16x16x32_bf16 v[58:61], v[156:159], v[180:183], v[58:61]
	v_mfma_f32_16x16x32_bf16 v[46:49], v[148:151], v[188:191], v[46:49]
	v_mfma_f32_16x16x32_bf16 v[42:45], v[156:159], v[188:191], v[42:45]
	v_mfma_f32_16x16x32_bf16 v[30:33], v[148:151], v[196:199], v[30:33]
	v_mfma_f32_16x16x32_bf16 v[26:29], v[156:159], v[196:199], v[26:29]
	v_mfma_f32_16x16x32_bf16 v[14:17], v[148:151], v[212:215], v[14:17]
	v_mfma_f32_16x16x32_bf16 v[10:13], v[156:159], v[212:215], v[10:13]
	v_mfma_f32_16x16x32_bf16 v[62:65], v[152:155], v[184:187], v[62:65]
	v_mfma_f32_16x16x32_bf16 v[58:61], v[160:163], v[184:187], v[58:61]
	v_mfma_f32_16x16x32_bf16 v[46:49], v[152:155], v[192:195], v[46:49]
	v_mfma_f32_16x16x32_bf16 v[42:45], v[160:163], v[192:195], v[42:45]
	v_mfma_f32_16x16x32_bf16 v[30:33], v[152:155], v[208:211], v[30:33]
	v_mfma_f32_16x16x32_bf16 v[26:29], v[160:163], v[208:211], v[26:29]
	v_mfma_f32_16x16x32_bf16 v[14:17], v[152:155], v[216:219], v[14:17]
	v_mfma_f32_16x16x32_bf16 v[10:13], v[160:163], v[216:219], v[10:13]
	v_mfma_f32_16x16x32_bf16 v[54:57], v[164:167], v[180:183], v[54:57]
	v_mfma_f32_16x16x32_bf16 v[50:53], v[172:175], v[180:183], v[50:53]
	v_mfma_f32_16x16x32_bf16 v[38:41], v[164:167], v[188:191], v[38:41]
	v_mfma_f32_16x16x32_bf16 v[34:37], v[172:175], v[188:191], v[34:37]
	v_mfma_f32_16x16x32_bf16 v[22:25], v[164:167], v[196:199], v[22:25]
	v_mfma_f32_16x16x32_bf16 v[18:21], v[172:175], v[196:199], v[18:21]
	v_mfma_f32_16x16x32_bf16 v[6:9], v[164:167], v[212:215], v[6:9]
	v_mfma_f32_16x16x32_bf16 v[2:5], v[172:175], v[212:215], v[2:5]
	v_mfma_f32_16x16x32_bf16 v[54:57], v[168:171], v[184:187], v[54:57]
	v_mfma_f32_16x16x32_bf16 v[50:53], v[176:179], v[184:187], v[50:53]
	v_mfma_f32_16x16x32_bf16 v[38:41], v[168:171], v[192:195], v[38:41]
	v_mfma_f32_16x16x32_bf16 v[34:37], v[176:179], v[192:195], v[34:37]
	v_mfma_f32_16x16x32_bf16 v[22:25], v[168:171], v[208:211], v[22:25]
	v_mfma_f32_16x16x32_bf16 v[18:21], v[176:179], v[208:211], v[18:21]
	v_mfma_f32_16x16x32_bf16 v[6:9], v[168:171], v[216:219], v[6:9]
	v_mfma_f32_16x16x32_bf16 v[2:5], v[176:179], v[216:219], v[2:5]
	s_barrier
	s_setprio 0
	s_add_i32 s58, s58, 2
	s_add_u32 s22, s22, 0x100
	s_addc_u32 s23, s23, 0
	s_add_u32 s41, s41, 0x100
	s_addc_u32 s49, s49, 0
	s_cmp_gt_u32 s58, 29
	s_cbranch_scc0 .LBB0_1115
	s_and_b64 vcc, exec, s[10:11]
	s_cbranch_vccz .LBB0_1118
	s_barrier

.LBB0_1241:
	s_add_i32 s93, s93, 1
	s_mul_i32 s0, s93, s96
	s_mov_b32 s2, s95
	s_mov_b32 s67, s95
	s_add_i32 s95, s0, s56
	s_cmpk_lt_i32 s95, 0x200
	s_mov_b32 s3, s66
	s_cselect_b64 s[16:17], -1, 0
	s_ashr_i32 s66, s95, 2
	s_and_b64 s[0:1], s[16:17], exec
	s_cselect_b32 s2, s95, s2
	s_cselect_b32 s0, s66, s3
	s_ashr_i32 s3, s2, 31
	s_lshl_b64 s[2:3], s[2:3], 18
	s_mov_b64 s[18:19], s[14:15]
	s_add_u32 s14, s78, s2
	s_addc_u32 s15, s79, s3
	s_and_b64 s[2:3], s[16:17], exec
	s_cselect_b32 s49, s15, s19
	s_cselect_b32 s58, s14, s18
	s_ashr_i32 s1, s0, 31
	s_lshl_b64 s[0:1], s[0:1], 17
	s_mov_b64 s[20:21], s[6:7]
	s_add_u32 s6, s34, s0
	s_addc_u32 s7, s35, s1
	s_and_b64 s[0:1], s[16:17], exec
	v_mov_b32_e32 v2, 0
	s_mov_b32 s72, s56
	s_cselect_b32 s59, s7, s21
	s_cselect_b32 s60, s6, s20
	s_mov_b64 s[4:5], 0
	s_mov_b64 s[22:23], -1
	s_mov_b64 s[2:3], 0
	v_mov_b32_e32 v3, v2
	v_pk_mov_b32 v[4:5], v[2:3], v[2:3] op_sel:[0,1]
	v_pk_mov_b32 v[6:7], v[2:3], v[2:3] op_sel:[0,1]
	v_pk_mov_b32 v[8:9], v[2:3], v[2:3] op_sel:[0,1]
	v_pk_mov_b32 v[10:11], v[2:3], v[2:3] op_sel:[0,1]
	v_pk_mov_b32 v[12:13], v[2:3], v[2:3] op_sel:[0,1]
	v_pk_mov_b32 v[18:19], v[2:3], v[2:3] op_sel:[0,1]
	v_pk_mov_b32 v[20:21], v[2:3], v[2:3] op_sel:[0,1]
	v_pk_mov_b32 v[26:27], v[2:3], v[2:3] op_sel:[0,1]
	v_pk_mov_b32 v[28:29], v[2:3], v[2:3] op_sel:[0,1]
	v_pk_mov_b32 v[34:35], v[2:3], v[2:3] op_sel:[0,1]
	v_pk_mov_b32 v[36:37], v[2:3], v[2:3] op_sel:[0,1]
	v_pk_mov_b32 v[42:43], v[2:3], v[2:3] op_sel:[0,1]
	v_pk_mov_b32 v[44:45], v[2:3], v[2:3] op_sel:[0,1]
	v_pk_mov_b32 v[50:51], v[2:3], v[2:3] op_sel:[0,1]
	v_pk_mov_b32 v[52:53], v[2:3], v[2:3] op_sel:[0,1]
	v_pk_mov_b32 v[14:15], v[2:3], v[2:3] op_sel:[0,1]
	v_pk_mov_b32 v[16:17], v[2:3], v[2:3] op_sel:[0,1]
	v_pk_mov_b32 v[22:23], v[2:3], v[2:3] op_sel:[0,1]
	v_pk_mov_b32 v[24:25], v[2:3], v[2:3] op_sel:[0,1]
	v_pk_mov_b32 v[30:31], v[2:3], v[2:3] op_sel:[0,1]
	v_pk_mov_b32 v[32:33], v[2:3], v[2:3] op_sel:[0,1]
	v_pk_mov_b32 v[38:39], v[2:3], v[2:3] op_sel:[0,1]
	v_pk_mov_b32 v[40:41], v[2:3], v[2:3] op_sel:[0,1]
	v_pk_mov_b32 v[46:47], v[2:3], v[2:3] op_sel:[0,1]
	v_pk_mov_b32 v[48:49], v[2:3], v[2:3] op_sel:[0,1]
	v_pk_mov_b32 v[54:55], v[2:3], v[2:3] op_sel:[0,1]
	v_pk_mov_b32 v[56:57], v[2:3], v[2:3] op_sel:[0,1]
	v_pk_mov_b32 v[58:59], v[2:3], v[2:3] op_sel:[0,1]
	v_pk_mov_b32 v[60:61], v[2:3], v[2:3] op_sel:[0,1]
	v_pk_mov_b32 v[62:63], v[2:3], v[2:3] op_sel:[0,1]
	v_pk_mov_b32 v[64:65], v[2:3], v[2:3] op_sel:[0,1]
	v_pk_mov_b32 v[66:67], v[2:3], v[2:3] op_sel:[0,1]
	v_pk_mov_b32 v[68:69], v[2:3], v[2:3] op_sel:[0,1]
	v_pk_mov_b32 v[70:71], v[2:3], v[2:3] op_sel:[0,1]
	v_pk_mov_b32 v[72:73], v[2:3], v[2:3] op_sel:[0,1]
	v_pk_mov_b32 v[74:75], v[2:3], v[2:3] op_sel:[0,1]
	v_pk_mov_b32 v[76:77], v[2:3], v[2:3] op_sel:[0,1]
	v_pk_mov_b32 v[82:83], v[2:3], v[2:3] op_sel:[0,1]
	v_pk_mov_b32 v[84:85], v[2:3], v[2:3] op_sel:[0,1]
	v_pk_mov_b32 v[90:91], v[2:3], v[2:3] op_sel:[0,1]
	v_pk_mov_b32 v[92:93], v[2:3], v[2:3] op_sel:[0,1]
	v_pk_mov_b32 v[98:99], v[2:3], v[2:3] op_sel:[0,1]
	v_pk_mov_b32 v[100:101], v[2:3], v[2:3] op_sel:[0,1]
	v_pk_mov_b32 v[106:107], v[2:3], v[2:3] op_sel:[0,1]
	v_pk_mov_b32 v[108:109], v[2:3], v[2:3] op_sel:[0,1]
	v_pk_mov_b32 v[114:115], v[2:3], v[2:3] op_sel:[0,1]
	v_pk_mov_b32 v[116:117], v[2:3], v[2:3] op_sel:[0,1]
	v_pk_mov_b32 v[78:79], v[2:3], v[2:3] op_sel:[0,1]
	v_pk_mov_b32 v[80:81], v[2:3], v[2:3] op_sel:[0,1]
	v_pk_mov_b32 v[86:87], v[2:3], v[2:3] op_sel:[0,1]
	v_pk_mov_b32 v[88:89], v[2:3], v[2:3] op_sel:[0,1]
	v_pk_mov_b32 v[94:95], v[2:3], v[2:3] op_sel:[0,1]
	v_pk_mov_b32 v[96:97], v[2:3], v[2:3] op_sel:[0,1]
	v_pk_mov_b32 v[102:103], v[2:3], v[2:3] op_sel:[0,1]
	v_pk_mov_b32 v[104:105], v[2:3], v[2:3] op_sel:[0,1]
	v_pk_mov_b32 v[110:111], v[2:3], v[2:3] op_sel:[0,1]
	v_pk_mov_b32 v[112:113], v[2:3], v[2:3] op_sel:[0,1]
	v_pk_mov_b32 v[118:119], v[2:3], v[2:3] op_sel:[0,1]
	v_pk_mov_b32 v[120:121], v[2:3], v[2:3] op_sel:[0,1]
	v_pk_mov_b32 v[122:123], v[2:3], v[2:3] op_sel:[0,1]
	v_pk_mov_b32 v[124:125], v[2:3], v[2:3] op_sel:[0,1]
	v_pk_mov_b32 v[126:127], v[2:3], v[2:3] op_sel:[0,1]
	v_pk_mov_b32 v[128:129], v[2:3], v[2:3] op_sel:[0,1]
	.p2align 6
.LBB0_1242:
	s_add_u32 s28, s18, s4
	s_addc_u32 s29, s19, s5
	s_add_u32 s24, s28, 0x100
	s_addc_u32 s25, s29, 0
	s_and_b64 s[0:1], s[2:3], exec
	s_cselect_b32 s25, s49, s25
	s_cselect_b32 s24, s58, s24
	s_add_u32 s0, s20, s4
	s_addc_u32 s1, s21, s5
	s_add_u32 s4, s0, 0x100
	s_addc_u32 s5, s1, 0
	s_add_i32 s55, 0, 0x10000
	s_and_b64 s[0:1], s[2:3], exec
	s_cselect_b32 s27, s59, s5
	s_cselect_b32 s26, s60, s4
	s_add_i32 s0, 0, 0x14000
	s_add_u32 s30, s28, 0x20080
	s_addc_u32 s31, s29, 0
	s_add_i32 s57, s55, s36
	s_add_i32 m0, s37, 0xc000
	s_add_i32 s1, s37, 0xe000
	s_add_i32 s63, s57, 0x2000
	v_add_u32_e32 v138, s55, v141
	s_add_u32 s28, s26, 0x10000
	ds_read_b128 v[144:147], v138
	ds_read_b128 v[148:151], v138 offset:1024
	ds_read_b128 v[152:155], v138 offset:2048
	ds_read_b128 v[156:159], v138 offset:3072
	v_add_u32_e32 v138, s0, v141
	s_addc_u32 s29, s27, 0
	s_add_i32 s33, s0, s36
	ds_read_b128 v[160:163], v138
	ds_read_b128 v[164:167], v138 offset:1024
	ds_read_b128 v[168:171], v138 offset:2048
	ds_read_b128 v[172:175], v138 offset:3072
	s_add_i32 s56, s33, 0x2000
	s_add_i32 vcc_lo, 0, 0x18000
	s_add_i32 vcc_hi, 0, 0x1c000
	s_add_u32 s4, s24, 0x20000
	s_addc_u32 s5, s25, 0
	s_add_i32 s61, vcc_lo, s36
	s_add_i32 s62, s61, 0x2000
	s_add_u32 s2, s26, 0x10080
	s_addc_u32 s3, s27, 0
	s_add_i32 s55, vcc_hi, s36
	s_add_i32 s0, s55, 0x2000
	ds_read_b128 v[176:179], v142
	ds_read_b128 v[180:183], v142 offset:1024
	ds_read_b128 v[184:187], v142 offset:2048
	ds_read_b128 v[188:191], v142 offset:3072
	ds_read_b128 v[192:195], v142 offset:4096
	ds_read_b128 v[196:199], v142 offset:5120
	ds_read_b128 v[208:211], v142 offset:6144
	ds_read_b128 v[212:215], v142 offset:7168
	global_load_lds_dwordx4 v134, s[30:31]
	s_mov_b32 m0, s1
	s_nop 0
	global_load_lds_dwordx4 v132, s[30:31]
	.p2align 3
	s_waitcnt vmcnt(8)
	s_waitcnt lgkmcnt(0)
	s_setprio 1
	s_barrier
	v_mfma_f32_16x16x32_bf16 v[126:129], v[144:147], v[176:179], v[126:129]
	v_mfma_f32_16x16x32_bf16 v[122:125], v[152:155], v[176:179], v[122:125]
	v_mfma_f32_16x16x32_bf16 v[118:121], v[144:147], v[184:187], v[118:121]
	v_mfma_f32_16x16x32_bf16 v[110:113], v[152:155], v[184:187], v[110:113]
	v_mfma_f32_16x16x32_bf16 v[102:105], v[144:147], v[192:195], v[102:105]
	v_mfma_f32_16x16x32_bf16 v[94:97], v[152:155], v[192:195], v[94:97]
	v_mfma_f32_16x16x32_bf16 v[86:89], v[144:147], v[208:211], v[86:89]
	v_mfma_f32_16x16x32_bf16 v[78:81], v[152:155], v[208:211], v[78:81]
	v_mfma_f32_16x16x32_bf16 v[126:129], v[148:151], v[180:183], v[126:129]
	v_mfma_f32_16x16x32_bf16 v[122:125], v[156:159], v[180:183], v[122:125]
	v_mfma_f32_16x16x32_bf16 v[118:121], v[148:151], v[188:191], v[118:121]
	v_mfma_f32_16x16x32_bf16 v[110:113], v[156:159], v[188:191], v[110:113]
	v_mfma_f32_16x16x32_bf16 v[102:105], v[148:151], v[196:199], v[102:105]
	v_mfma_f32_16x16x32_bf16 v[94:97], v[156:159], v[196:199], v[94:97]
	v_mfma_f32_16x16x32_bf16 v[86:89], v[148:151], v[212:215], v[86:89]
	v_mfma_f32_16x16x32_bf16 v[78:81], v[156:159], v[212:215], v[78:81]
	v_mfma_f32_16x16x32_bf16 v[114:117], v[160:163], v[176:179], v[114:117]
	v_mfma_f32_16x16x32_bf16 v[106:109], v[168:171], v[176:179], v[106:109]
	v_mfma_f32_16x16x32_bf16 v[98:101], v[160:163], v[184:187], v[98:101]
	v_mfma_f32_16x16x32_bf16 v[90:93], v[168:171], v[184:187], v[90:93]
	v_mfma_f32_16x16x32_bf16 v[82:85], v[160:163], v[192:195], v[82:85]
	v_mfma_f32_16x16x32_bf16 v[74:77], v[168:171], v[192:195], v[74:77]
	v_mfma_f32_16x16x32_bf16 v[70:73], v[160:163], v[208:211], v[70:73]
	v_mfma_f32_16x16x32_bf16 v[66:69], v[168:171], v[208:211], v[66:69]
	v_mfma_f32_16x16x32_bf16 v[114:117], v[164:167], v[180:183], v[114:117]
	v_mfma_f32_16x16x32_bf16 v[106:109], v[172:175], v[180:183], v[106:109]
	v_mfma_f32_16x16x32_bf16 v[98:101], v[164:167], v[188:191], v[98:101]
	v_mfma_f32_16x16x32_bf16 v[90:93], v[172:175], v[188:191], v[90:93]
	v_mfma_f32_16x16x32_bf16 v[82:85], v[164:167], v[196:199], v[82:85]
	v_mfma_f32_16x16x32_bf16 v[74:77], v[172:175], v[196:199], v[74:77]
	v_mfma_f32_16x16x32_bf16 v[70:73], v[164:167], v[212:215], v[70:73]
	v_mfma_f32_16x16x32_bf16 v[66:69], v[172:175], v[212:215], v[66:69]
	s_barrier
	s_setprio 0
	s_mov_b32 m0, s57
	ds_read_b128 v[176:179], v142 offset:16384
	ds_read_b128 v[180:183], v142 offset:17408
	ds_read_b128 v[184:187], v142 offset:18432
	ds_read_b128 v[188:191], v142 offset:19456
	ds_read_b128 v[192:195], v142 offset:20480
	ds_read_b128 v[196:199], v142 offset:21504
	ds_read_b128 v[208:211], v142 offset:22528
	ds_read_b128 v[212:215], v142 offset:23552
	global_load_lds_dwordx4 v202, s[26:27]
	s_mov_b32 m0, s63
	s_nop 0
	global_load_lds_dwordx4 v130, s[26:27]
	s_mov_b32 m0, s33
	s_nop 0
	global_load_lds_dwordx4 v202, s[28:29]
	s_mov_b32 m0, s56
	s_nop 0
	global_load_lds_dwordx4 v130, s[28:29]
	s_mov_b32 m0, s37
	s_nop 0
	global_load_lds_dwordx4 v134, s[24:25]
	s_mov_b32 m0, s38
	s_nop 0
	global_load_lds_dwordx4 v132, s[24:25]
	.p2align 3
	s_waitcnt vmcnt(8)
	s_waitcnt lgkmcnt(0)
	s_setprio 1
	s_barrier
	v_mfma_f32_16x16x32_bf16 v[62:65], v[144:147], v[176:179], v[62:65]
	v_mfma_f32_16x16x32_bf16 v[58:61], v[152:155], v[176:179], v[58:61]
	v_mfma_f32_16x16x32_bf16 v[54:57], v[144:147], v[184:187], v[54:57]
	v_mfma_f32_16x16x32_bf16 v[46:49], v[152:155], v[184:187], v[46:49]
	v_mfma_f32_16x16x32_bf16 v[38:41], v[144:147], v[192:195], v[38:41]
	v_mfma_f32_16x16x32_bf16 v[30:33], v[152:155], v[192:195], v[30:33]
	v_mfma_f32_16x16x32_bf16 v[22:25], v[144:147], v[208:211], v[22:25]
	v_mfma_f32_16x16x32_bf16 v[14:17], v[152:155], v[208:211], v[14:17]
	v_mfma_f32_16x16x32_bf16 v[62:65], v[148:151], v[180:183], v[62:65]
	v_mfma_f32_16x16x32_bf16 v[58:61], v[156:159], v[180:183], v[58:61]
	v_mfma_f32_16x16x32_bf16 v[54:57], v[148:151], v[188:191], v[54:57]
	v_mfma_f32_16x16x32_bf16 v[46:49], v[156:159], v[188:191], v[46:49]
	v_mfma_f32_16x16x32_bf16 v[38:41], v[148:151], v[196:199], v[38:41]
	v_mfma_f32_16x16x32_bf16 v[30:33], v[156:159], v[196:199], v[30:33]
	v_mfma_f32_16x16x32_bf16 v[22:25], v[148:151], v[212:215], v[22:25]
	v_mfma_f32_16x16x32_bf16 v[14:17], v[156:159], v[212:215], v[14:17]
	v_mfma_f32_16x16x32_bf16 v[50:53], v[160:163], v[176:179], v[50:53]
	v_mfma_f32_16x16x32_bf16 v[42:45], v[168:171], v[176:179], v[42:45]
	v_mfma_f32_16x16x32_bf16 v[34:37], v[160:163], v[184:187], v[34:37]
	v_mfma_f32_16x16x32_bf16 v[26:29], v[168:171], v[184:187], v[26:29]
	v_mfma_f32_16x16x32_bf16 v[18:21], v[160:163], v[192:195], v[18:21]
	v_mfma_f32_16x16x32_bf16 v[10:13], v[168:171], v[192:195], v[10:13]
	v_mfma_f32_16x16x32_bf16 v[6:9], v[160:163], v[208:211], v[6:9]
	v_mfma_f32_16x16x32_bf16 v[2:5], v[168:171], v[208:211], v[2:5]
	v_mfma_f32_16x16x32_bf16 v[50:53], v[164:167], v[180:183], v[50:53]
	v_mfma_f32_16x16x32_bf16 v[42:45], v[172:175], v[180:183], v[42:45]
	v_mfma_f32_16x16x32_bf16 v[34:37], v[164:167], v[188:191], v[34:37]
	v_mfma_f32_16x16x32_bf16 v[26:29], v[172:175], v[188:191], v[26:29]
	v_mfma_f32_16x16x32_bf16 v[18:21], v[164:167], v[196:199], v[18:21]
	v_mfma_f32_16x16x32_bf16 v[10:13], v[172:175], v[196:199], v[10:13]
	v_mfma_f32_16x16x32_bf16 v[6:9], v[164:167], v[212:215], v[6:9]
	v_mfma_f32_16x16x32_bf16 v[2:5], v[172:175], v[212:215], v[2:5]
	s_barrier
	s_setprio 0
	v_add_u32_e32 v143, vcc_lo, v141
	ds_read_b128 v[144:147], v143
	ds_read_b128 v[148:151], v143 offset:1024
	ds_read_b128 v[152:155], v143 offset:2048
	ds_read_b128 v[156:159], v143 offset:3072
	v_add_u32_e32 v143, vcc_hi, v141
	ds_read_b128 v[160:163], v143
	ds_read_b128 v[164:167], v143 offset:1024
	ds_read_b128 v[168:171], v143 offset:2048
	ds_read_b128 v[172:175], v143 offset:3072
	s_mov_b32 m0, s39
	ds_read_b128 v[176:179], v142 offset:32768
	ds_read_b128 v[180:183], v142 offset:33792
	ds_read_b128 v[184:187], v142 offset:34816
	ds_read_b128 v[188:191], v142 offset:35840
	ds_read_b128 v[192:195], v142 offset:36864
	ds_read_b128 v[196:199], v142 offset:37888
	ds_read_b128 v[208:211], v142 offset:38912
	ds_read_b128 v[212:215], v142 offset:39936
	global_load_lds_dwordx4 v134, s[4:5]
	s_mov_b32 m0, s40
	s_nop 0
	global_load_lds_dwordx4 v132, s[4:5]
	.p2align 3
	s_waitcnt vmcnt(8)
	s_waitcnt lgkmcnt(0)
	s_setprio 1
	s_barrier
	v_mfma_f32_16x16x32_bf16 v[126:129], v[144:147], v[176:179], v[126:129]
	v_mfma_f32_16x16x32_bf16 v[122:125], v[152:155], v[176:179], v[122:125]
	v_mfma_f32_16x16x32_bf16 v[118:121], v[144:147], v[184:187], v[118:121]
	v_mfma_f32_16x16x32_bf16 v[110:113], v[152:155], v[184:187], v[110:113]
	v_mfma_f32_16x16x32_bf16 v[102:105], v[144:147], v[192:195], v[102:105]
	v_mfma_f32_16x16x32_bf16 v[94:97], v[152:155], v[192:195], v[94:97]
	v_mfma_f32_16x16x32_bf16 v[86:89], v[144:147], v[208:211], v[86:89]
	v_mfma_f32_16x16x32_bf16 v[78:81], v[152:155], v[208:211], v[78:81]
	v_mfma_f32_16x16x32_bf16 v[126:129], v[148:151], v[180:183], v[126:129]
	v_mfma_f32_16x16x32_bf16 v[122:125], v[156:159], v[180:183], v[122:125]
	v_mfma_f32_16x16x32_bf16 v[118:121], v[148:151], v[188:191], v[118:121]
	v_mfma_f32_16x16x32_bf16 v[110:113], v[156:159], v[188:191], v[110:113]
	v_mfma_f32_16x16x32_bf16 v[102:105], v[148:151], v[196:199], v[102:105]
	v_mfma_f32_16x16x32_bf16 v[94:97], v[156:159], v[196:199], v[94:97]
	v_mfma_f32_16x16x32_bf16 v[86:89], v[148:151], v[212:215], v[86:89]
	v_mfma_f32_16x16x32_bf16 v[78:81], v[156:159], v[212:215], v[78:81]
	v_mfma_f32_16x16x32_bf16 v[114:117], v[160:163], v[176:179], v[114:117]
	v_mfma_f32_16x16x32_bf16 v[106:109], v[168:171], v[176:179], v[106:109]
	v_mfma_f32_16x16x32_bf16 v[98:101], v[160:163], v[184:187], v[98:101]
	v_mfma_f32_16x16x32_bf16 v[90:93], v[168:171], v[184:187], v[90:93]
	v_mfma_f32_16x16x32_bf16 v[82:85], v[160:163], v[192:195], v[82:85]
	v_mfma_f32_16x16x32_bf16 v[74:77], v[168:171], v[192:195], v[74:77]
	v_mfma_f32_16x16x32_bf16 v[70:73], v[160:163], v[208:211], v[70:73]
	v_mfma_f32_16x16x32_bf16 v[66:69], v[168:171], v[208:211], v[66:69]
	v_mfma_f32_16x16x32_bf16 v[114:117], v[164:167], v[180:183], v[114:117]
	v_mfma_f32_16x16x32_bf16 v[106:109], v[172:175], v[180:183], v[106:109]
	v_mfma_f32_16x16x32_bf16 v[98:101], v[164:167], v[188:191], v[98:101]
	v_mfma_f32_16x16x32_bf16 v[90:93], v[172:175], v[188:191], v[90:93]
	v_mfma_f32_16x16x32_bf16 v[82:85], v[164:167], v[196:199], v[82:85]
	v_mfma_f32_16x16x32_bf16 v[74:77], v[172:175], v[196:199], v[74:77]
	v_mfma_f32_16x16x32_bf16 v[70:73], v[164:167], v[212:215], v[70:73]
	v_mfma_f32_16x16x32_bf16 v[66:69], v[172:175], v[212:215], v[66:69]
	s_barrier
	s_setprio 0
	s_mov_b32 m0, s61
	s_add_u32 s100, s26, 0x80
	s_addc_u32 s101, s27, 0
	ds_read_b128 v[176:179], v142 offset:49152
	ds_read_b128 v[180:183], v142 offset:50176
	ds_read_b128 v[184:187], v142 offset:51200
	ds_read_b128 v[188:191], v142 offset:52224
	ds_read_b128 v[192:195], v142 offset:53248
	ds_read_b128 v[196:199], v142 offset:54272
	ds_read_b128 v[208:211], v142 offset:55296
	ds_read_b128 v[212:215], v142 offset:56320
	global_load_lds_dwordx4 v202, s[100:101]
	s_add_u32 s100, s26, 0x80
	s_addc_u32 s101, s27, 0
	s_mov_b32 m0, s62
	s_nop 0
	global_load_lds_dwordx4 v130, s[100:101]
	s_mov_b32 m0, s55
	s_nop 0
	global_load_lds_dwordx4 v202, s[2:3]
	s_mov_b32 m0, s0
	s_nop 0
	global_load_lds_dwordx4 v130, s[2:3]
	s_add_u32 s100, s24, 0x80
	s_addc_u32 s101, s25, 0
	s_mov_b32 m0, s41
	s_nop 0
	global_load_lds_dwordx4 v134, s[100:101]
	s_add_u32 s100, s24, 0x80
	s_addc_u32 s101, s25, 0
	s_mov_b32 m0, s86
	s_nop 0
	global_load_lds_dwordx4 v132, s[100:101]
	.p2align 3
	s_waitcnt vmcnt(8)
	s_waitcnt lgkmcnt(0)
	s_setprio 1
	s_barrier
	v_mfma_f32_16x16x32_bf16 v[62:65], v[144:147], v[176:179], v[62:65]
	v_mfma_f32_16x16x32_bf16 v[58:61], v[152:155], v[176:179], v[58:61]
	v_mfma_f32_16x16x32_bf16 v[54:57], v[144:147], v[184:187], v[54:57]
	v_mfma_f32_16x16x32_bf16 v[46:49], v[152:155], v[184:187], v[46:49]
	v_mfma_f32_16x16x32_bf16 v[38:41], v[144:147], v[192:195], v[38:41]
	v_mfma_f32_16x16x32_bf16 v[30:33], v[152:155], v[192:195], v[30:33]
	v_mfma_f32_16x16x32_bf16 v[22:25], v[144:147], v[208:211], v[22:25]
	v_mfma_f32_16x16x32_bf16 v[14:17], v[152:155], v[208:211], v[14:17]
	v_mfma_f32_16x16x32_bf16 v[62:65], v[148:151], v[180:183], v[62:65]
	v_mfma_f32_16x16x32_bf16 v[58:61], v[156:159], v[180:183], v[58:61]
	v_mfma_f32_16x16x32_bf16 v[54:57], v[148:151], v[188:191], v[54:57]
	v_mfma_f32_16x16x32_bf16 v[46:49], v[156:159], v[188:191], v[46:49]
	v_mfma_f32_16x16x32_bf16 v[38:41], v[148:151], v[196:199], v[38:41]
	v_mfma_f32_16x16x32_bf16 v[30:33], v[156:159], v[196:199], v[30:33]
	v_mfma_f32_16x16x32_bf16 v[22:25], v[148:151], v[212:215], v[22:25]
	v_mfma_f32_16x16x32_bf16 v[14:17], v[156:159], v[212:215], v[14:17]
	v_mfma_f32_16x16x32_bf16 v[50:53], v[160:163], v[176:179], v[50:53]
	v_mfma_f32_16x16x32_bf16 v[42:45], v[168:171], v[176:179], v[42:45]
	v_mfma_f32_16x16x32_bf16 v[34:37], v[160:163], v[184:187], v[34:37]
	v_mfma_f32_16x16x32_bf16 v[26:29], v[168:171], v[184:187], v[26:29]
	v_mfma_f32_16x16x32_bf16 v[18:21], v[160:163], v[192:195], v[18:21]
	v_mfma_f32_16x16x32_bf16 v[10:13], v[168:171], v[192:195], v[10:13]
	v_mfma_f32_16x16x32_bf16 v[6:9], v[160:163], v[208:211], v[6:9]
	v_mfma_f32_16x16x32_bf16 v[2:5], v[168:171], v[208:211], v[2:5]
	v_mfma_f32_16x16x32_bf16 v[50:53], v[164:167], v[180:183], v[50:53]
	v_mfma_f32_16x16x32_bf16 v[42:45], v[172:175], v[180:183], v[42:45]
	v_mfma_f32_16x16x32_bf16 v[34:37], v[164:167], v[188:191], v[34:37]
	v_mfma_f32_16x16x32_bf16 v[26:29], v[172:175], v[188:191], v[26:29]
	v_mfma_f32_16x16x32_bf16 v[18:21], v[164:167], v[196:199], v[18:21]
	v_mfma_f32_16x16x32_bf16 v[10:13], v[172:175], v[196:199], v[10:13]
	v_mfma_f32_16x16x32_bf16 v[6:9], v[164:167], v[212:215], v[6:9]
	v_mfma_f32_16x16x32_bf16 v[2:5], v[172:175], v[212:215], v[2:5]
	s_barrier
	s_setprio 0
	s_andn2_b64 vcc, exec, s[22:23]
	s_mov_b64 s[2:3], -1
	s_mov_b64 s[22:23], 0
	s_mov_b64 s[4:5], 0x100
	s_cbranch_vccz .LBB0_1242
	s_and_b64 vcc, exec, s[10:11]
	s_cbranch_vccz .LBB0_1245
	s_barrier

.LBB0_1362:
	s_add_i32 s31, s31, 1
	s_mul_i32 s4, s31, s96
	s_mov_b64 s[2:3], s[8:9]
	s_mov_b32 s8, s34
	s_mov_b32 s37, s34
	s_add_i32 s34, s4, s56
	s_cmpk_lt_i32 s34, 0x200
	s_mov_b32 s9, s35
	s_mov_b32 s36, s35
	s_cselect_b64 s[18:19], -1, 0
	s_ashr_i32 s35, s34, 2
	s_and_b64 s[4:5], s[18:19], exec
	s_cselect_b32 s8, s34, s8
	s_cselect_b32 s4, s35, s9
	s_ashr_i32 s9, s8, 31
	s_lshl_b64 s[8:9], s[8:9], 18
	s_mov_b64 s[0:1], s[16:17]
	s_add_u32 s16, s78, s8
	s_addc_u32 s17, s79, s9
	s_and_b64 s[8:9], s[18:19], exec
	s_cselect_b32 s38, s17, s1
	s_cselect_b32 s39, s16, s0
	s_ashr_i32 s5, s4, 31
	s_lshl_b64 s[4:5], s[4:5], 18
	s_add_u32 s8, s22, s4
	s_addc_u32 s9, s23, s5
	s_and_b64 s[4:5], s[18:19], exec
	s_cselect_b32 s40, s9, s3
	s_cselect_b32 s41, s8, s2
	s_add_u32 s20, s0, 0x20080
	s_addc_u32 s21, s1, 0
	s_add_u32 s49, s2, 0x100
	v_mov_b32_e32 v2, 0
	s_addc_u32 s58, s3, 0
	s_mov_b32 s59, -2
	v_mov_b32_e32 v3, v2
	v_pk_mov_b32 v[4:5], v[2:3], v[2:3] op_sel:[0,1]
	v_pk_mov_b32 v[6:7], v[2:3], v[2:3] op_sel:[0,1]
	v_pk_mov_b32 v[8:9], v[2:3], v[2:3] op_sel:[0,1]
	v_pk_mov_b32 v[18:19], v[2:3], v[2:3] op_sel:[0,1]
	v_pk_mov_b32 v[20:21], v[2:3], v[2:3] op_sel:[0,1]
	v_pk_mov_b32 v[22:23], v[2:3], v[2:3] op_sel:[0,1]
	v_pk_mov_b32 v[24:25], v[2:3], v[2:3] op_sel:[0,1]
	v_pk_mov_b32 v[34:35], v[2:3], v[2:3] op_sel:[0,1]
	v_pk_mov_b32 v[36:37], v[2:3], v[2:3] op_sel:[0,1]
	v_pk_mov_b32 v[38:39], v[2:3], v[2:3] op_sel:[0,1]
	v_pk_mov_b32 v[40:41], v[2:3], v[2:3] op_sel:[0,1]
	v_pk_mov_b32 v[50:51], v[2:3], v[2:3] op_sel:[0,1]
	v_pk_mov_b32 v[52:53], v[2:3], v[2:3] op_sel:[0,1]
	v_pk_mov_b32 v[54:55], v[2:3], v[2:3] op_sel:[0,1]
	v_pk_mov_b32 v[56:57], v[2:3], v[2:3] op_sel:[0,1]
	v_pk_mov_b32 v[10:11], v[2:3], v[2:3] op_sel:[0,1]
	v_pk_mov_b32 v[12:13], v[2:3], v[2:3] op_sel:[0,1]
	v_pk_mov_b32 v[14:15], v[2:3], v[2:3] op_sel:[0,1]
	v_pk_mov_b32 v[16:17], v[2:3], v[2:3] op_sel:[0,1]
	v_pk_mov_b32 v[26:27], v[2:3], v[2:3] op_sel:[0,1]
	v_pk_mov_b32 v[28:29], v[2:3], v[2:3] op_sel:[0,1]
	v_pk_mov_b32 v[30:31], v[2:3], v[2:3] op_sel:[0,1]
	v_pk_mov_b32 v[32:33], v[2:3], v[2:3] op_sel:[0,1]
	v_pk_mov_b32 v[42:43], v[2:3], v[2:3] op_sel:[0,1]
	v_pk_mov_b32 v[44:45], v[2:3], v[2:3] op_sel:[0,1]
	v_pk_mov_b32 v[46:47], v[2:3], v[2:3] op_sel:[0,1]
	v_pk_mov_b32 v[48:49], v[2:3], v[2:3] op_sel:[0,1]
	v_pk_mov_b32 v[58:59], v[2:3], v[2:3] op_sel:[0,1]
	v_pk_mov_b32 v[60:61], v[2:3], v[2:3] op_sel:[0,1]
	v_pk_mov_b32 v[62:63], v[2:3], v[2:3] op_sel:[0,1]
	v_pk_mov_b32 v[64:65], v[2:3], v[2:3] op_sel:[0,1]
	v_pk_mov_b32 v[66:67], v[2:3], v[2:3] op_sel:[0,1]
	v_pk_mov_b32 v[68:69], v[2:3], v[2:3] op_sel:[0,1]
	v_pk_mov_b32 v[70:71], v[2:3], v[2:3] op_sel:[0,1]
	v_pk_mov_b32 v[72:73], v[2:3], v[2:3] op_sel:[0,1]
	v_pk_mov_b32 v[82:83], v[2:3], v[2:3] op_sel:[0,1]
	v_pk_mov_b32 v[84:85], v[2:3], v[2:3] op_sel:[0,1]
	v_pk_mov_b32 v[86:87], v[2:3], v[2:3] op_sel:[0,1]
	v_pk_mov_b32 v[88:89], v[2:3], v[2:3] op_sel:[0,1]
	v_pk_mov_b32 v[98:99], v[2:3], v[2:3] op_sel:[0,1]
	v_pk_mov_b32 v[100:101], v[2:3], v[2:3] op_sel:[0,1]
	v_pk_mov_b32 v[102:103], v[2:3], v[2:3] op_sel:[0,1]
	v_pk_mov_b32 v[104:105], v[2:3], v[2:3] op_sel:[0,1]
	v_pk_mov_b32 v[114:115], v[2:3], v[2:3] op_sel:[0,1]
	v_pk_mov_b32 v[116:117], v[2:3], v[2:3] op_sel:[0,1]
	v_pk_mov_b32 v[118:119], v[2:3], v[2:3] op_sel:[0,1]
	v_pk_mov_b32 v[120:121], v[2:3], v[2:3] op_sel:[0,1]
	v_pk_mov_b32 v[74:75], v[2:3], v[2:3] op_sel:[0,1]
	v_pk_mov_b32 v[76:77], v[2:3], v[2:3] op_sel:[0,1]
	v_pk_mov_b32 v[78:79], v[2:3], v[2:3] op_sel:[0,1]
	v_pk_mov_b32 v[80:81], v[2:3], v[2:3] op_sel:[0,1]
	v_pk_mov_b32 v[90:91], v[2:3], v[2:3] op_sel:[0,1]
	v_pk_mov_b32 v[92:93], v[2:3], v[2:3] op_sel:[0,1]
	v_pk_mov_b32 v[94:95], v[2:3], v[2:3] op_sel:[0,1]
	v_pk_mov_b32 v[96:97], v[2:3], v[2:3] op_sel:[0,1]
	v_pk_mov_b32 v[106:107], v[2:3], v[2:3] op_sel:[0,1]
	v_pk_mov_b32 v[108:109], v[2:3], v[2:3] op_sel:[0,1]
	v_pk_mov_b32 v[110:111], v[2:3], v[2:3] op_sel:[0,1]
	v_pk_mov_b32 v[112:113], v[2:3], v[2:3] op_sel:[0,1]
	v_pk_mov_b32 v[122:123], v[2:3], v[2:3] op_sel:[0,1]
	v_pk_mov_b32 v[124:125], v[2:3], v[2:3] op_sel:[0,1]
	v_pk_mov_b32 v[126:127], v[2:3], v[2:3] op_sel:[0,1]
	v_pk_mov_b32 v[128:129], v[2:3], v[2:3] op_sel:[0,1]
	.p2align 6
.LBB0_1363:
	s_add_u32 s0, s20, 0xfffe0080
	s_addc_u32 s1, s21, -1
	s_add_i32 s33, 0, 0x10000
	s_cmp_eq_u32 s59, 4
	s_cselect_b32 s5, s38, s1
	s_cselect_b32 s4, s39, s0
	s_cselect_b32 s3, s40, s58
	s_cselect_b32 s2, s41, s49
	s_add_i32 s55, 0, 0x14000
	ds_read_b128 v[148:151], v143
	ds_read_b128 v[152:155], v143 offset:1024
	ds_read_b128 v[156:159], v143 offset:2048
	ds_read_b128 v[160:163], v143 offset:3072
	ds_read_b128 v[164:167], v143 offset:16384
	ds_read_b128 v[168:171], v143 offset:17408
	ds_read_b128 v[172:175], v143 offset:18432
	ds_read_b128 v[176:179], v143 offset:19456
	s_add_i32 m0, s25, 0xc000
	ds_read_b128 v[180:183], v146
	ds_read_b128 v[184:187], v146 offset:1024
	ds_read_b128 v[188:191], v146 offset:2048
	ds_read_b128 v[192:195], v146 offset:3072
	ds_read_b128 v[196:199], v146 offset:4096
	ds_read_b128 v[208:211], v146 offset:5120
	ds_read_b128 v[212:215], v146 offset:6144
	ds_read_b128 v[216:219], v146 offset:7168
	global_load_lds_dwordx4 v138, s[20:21]
	s_add_i32 m0, s25, 0xe000
	s_nop 0
	global_load_lds_dwordx4 v140, s[20:21]
	.p2align 3
	s_waitcnt vmcnt(8)
	s_waitcnt lgkmcnt(0)
	s_setprio 1
	s_barrier
	v_mfma_f32_16x16x32_bf16 v[126:129], v[148:151], v[180:183], v[126:129]
	v_mfma_f32_16x16x32_bf16 v[122:125], v[156:159], v[180:183], v[122:125]
	v_mfma_f32_16x16x32_bf16 v[110:113], v[148:151], v[188:191], v[110:113]
	v_mfma_f32_16x16x32_bf16 v[106:109], v[156:159], v[188:191], v[106:109]
	v_mfma_f32_16x16x32_bf16 v[94:97], v[148:151], v[196:199], v[94:97]
	v_mfma_f32_16x16x32_bf16 v[90:93], v[156:159], v[196:199], v[90:93]
	v_mfma_f32_16x16x32_bf16 v[78:81], v[148:151], v[212:215], v[78:81]
	v_mfma_f32_16x16x32_bf16 v[74:77], v[156:159], v[212:215], v[74:77]
	v_mfma_f32_16x16x32_bf16 v[126:129], v[152:155], v[184:187], v[126:129]
	v_mfma_f32_16x16x32_bf16 v[122:125], v[160:163], v[184:187], v[122:125]
	v_mfma_f32_16x16x32_bf16 v[110:113], v[152:155], v[192:195], v[110:113]
	v_mfma_f32_16x16x32_bf16 v[106:109], v[160:163], v[192:195], v[106:109]
	v_mfma_f32_16x16x32_bf16 v[94:97], v[152:155], v[208:211], v[94:97]
	v_mfma_f32_16x16x32_bf16 v[90:93], v[160:163], v[208:211], v[90:93]
	v_mfma_f32_16x16x32_bf16 v[78:81], v[152:155], v[216:219], v[78:81]
	v_mfma_f32_16x16x32_bf16 v[74:77], v[160:163], v[216:219], v[74:77]
	v_mfma_f32_16x16x32_bf16 v[118:121], v[164:167], v[180:183], v[118:121]
	v_mfma_f32_16x16x32_bf16 v[114:117], v[172:175], v[180:183], v[114:117]
	v_mfma_f32_16x16x32_bf16 v[102:105], v[164:167], v[188:191], v[102:105]
	v_mfma_f32_16x16x32_bf16 v[98:101], v[172:175], v[188:191], v[98:101]
	v_mfma_f32_16x16x32_bf16 v[86:89], v[164:167], v[196:199], v[86:89]
	v_mfma_f32_16x16x32_bf16 v[82:85], v[172:175], v[196:199], v[82:85]
	v_mfma_f32_16x16x32_bf16 v[70:73], v[164:167], v[212:215], v[70:73]
	v_mfma_f32_16x16x32_bf16 v[66:69], v[172:175], v[212:215], v[66:69]
	v_mfma_f32_16x16x32_bf16 v[118:121], v[168:171], v[184:187], v[118:121]
	v_mfma_f32_16x16x32_bf16 v[114:117], v[176:179], v[184:187], v[114:117]
	v_mfma_f32_16x16x32_bf16 v[102:105], v[168:171], v[192:195], v[102:105]
	v_mfma_f32_16x16x32_bf16 v[98:101], v[176:179], v[192:195], v[98:101]
	v_mfma_f32_16x16x32_bf16 v[86:89], v[168:171], v[208:211], v[86:89]
	v_mfma_f32_16x16x32_bf16 v[82:85], v[176:179], v[208:211], v[82:85]
	v_mfma_f32_16x16x32_bf16 v[70:73], v[168:171], v[216:219], v[70:73]
	v_mfma_f32_16x16x32_bf16 v[66:69], v[176:179], v[216:219], v[66:69]
	s_barrier
	s_setprio 0
	s_add_i32 s0, s33, s24
	s_mov_b32 m0, s0
	ds_read_b128 v[180:183], v146 offset:16384
	ds_read_b128 v[184:187], v146 offset:17408
	ds_read_b128 v[188:191], v146 offset:18432
	ds_read_b128 v[192:195], v146 offset:19456
	ds_read_b128 v[196:199], v146 offset:20480
	ds_read_b128 v[208:211], v146 offset:21504
	ds_read_b128 v[212:215], v146 offset:22528
	ds_read_b128 v[216:219], v146 offset:23552
	global_load_lds_dwordx4 v134, s[2:3]
	s_add_i32 m0, s0, 0x2000
	s_add_u32 s0, s2, 0x20000
	s_addc_u32 s1, s3, 0
	s_add_i32 s33, s55, s24
	global_load_lds_dwordx4 v130, s[2:3]
	s_mov_b32 m0, s33
	s_nop 0
	global_load_lds_dwordx4 v134, s[0:1]
	s_add_i32 m0, s33, 0x2000
	s_nop 0
	global_load_lds_dwordx4 v130, s[0:1]
	s_mov_b32 m0, s25
	s_nop 0
	global_load_lds_dwordx4 v136, s[4:5]
	s_mov_b32 m0, s26
	s_nop 0
	global_load_lds_dwordx4 v132, s[4:5]
	.p2align 3
	s_waitcnt vmcnt(8)
	s_waitcnt lgkmcnt(0)
	s_setprio 1
	s_barrier
	v_mfma_f32_16x16x32_bf16 v[62:65], v[148:151], v[180:183], v[62:65]
	v_mfma_f32_16x16x32_bf16 v[58:61], v[156:159], v[180:183], v[58:61]
	v_mfma_f32_16x16x32_bf16 v[46:49], v[148:151], v[188:191], v[46:49]
	v_mfma_f32_16x16x32_bf16 v[42:45], v[156:159], v[188:191], v[42:45]
	v_mfma_f32_16x16x32_bf16 v[30:33], v[148:151], v[196:199], v[30:33]
	v_mfma_f32_16x16x32_bf16 v[26:29], v[156:159], v[196:199], v[26:29]
	v_mfma_f32_16x16x32_bf16 v[14:17], v[148:151], v[212:215], v[14:17]
	v_mfma_f32_16x16x32_bf16 v[10:13], v[156:159], v[212:215], v[10:13]
	v_mfma_f32_16x16x32_bf16 v[62:65], v[152:155], v[184:187], v[62:65]
	v_mfma_f32_16x16x32_bf16 v[58:61], v[160:163], v[184:187], v[58:61]
	v_mfma_f32_16x16x32_bf16 v[46:49], v[152:155], v[192:195], v[46:49]
	v_mfma_f32_16x16x32_bf16 v[42:45], v[160:163], v[192:195], v[42:45]
	v_mfma_f32_16x16x32_bf16 v[30:33], v[152:155], v[208:211], v[30:33]
	v_mfma_f32_16x16x32_bf16 v[26:29], v[160:163], v[208:211], v[26:29]
	v_mfma_f32_16x16x32_bf16 v[14:17], v[152:155], v[216:219], v[14:17]
	v_mfma_f32_16x16x32_bf16 v[10:13], v[160:163], v[216:219], v[10:13]
	v_mfma_f32_16x16x32_bf16 v[54:57], v[164:167], v[180:183], v[54:57]
	v_mfma_f32_16x16x32_bf16 v[50:53], v[172:175], v[180:183], v[50:53]
	v_mfma_f32_16x16x32_bf16 v[38:41], v[164:167], v[188:191], v[38:41]
	v_mfma_f32_16x16x32_bf16 v[34:37], v[172:175], v[188:191], v[34:37]
	v_mfma_f32_16x16x32_bf16 v[22:25], v[164:167], v[196:199], v[22:25]
	v_mfma_f32_16x16x32_bf16 v[18:21], v[172:175], v[196:199], v[18:21]
	v_mfma_f32_16x16x32_bf16 v[6:9], v[164:167], v[212:215], v[6:9]
	v_mfma_f32_16x16x32_bf16 v[2:5], v[172:175], v[212:215], v[2:5]
	v_mfma_f32_16x16x32_bf16 v[54:57], v[168:171], v[184:187], v[54:57]
	v_mfma_f32_16x16x32_bf16 v[50:53], v[176:179], v[184:187], v[50:53]
	v_mfma_f32_16x16x32_bf16 v[38:41], v[168:171], v[192:195], v[38:41]
	v_mfma_f32_16x16x32_bf16 v[34:37], v[176:179], v[192:195], v[34:37]
	v_mfma_f32_16x16x32_bf16 v[22:25], v[168:171], v[208:211], v[22:25]
	v_mfma_f32_16x16x32_bf16 v[18:21], v[176:179], v[208:211], v[18:21]
	v_mfma_f32_16x16x32_bf16 v[6:9], v[168:171], v[216:219], v[6:9]
	v_mfma_f32_16x16x32_bf16 v[2:5], v[176:179], v[216:219], v[2:5]
	s_barrier
	s_setprio 0
	s_add_i32 s33, 0, 0x18000
	s_add_i32 s55, 0, 0x1c000
	ds_read_b128 v[148:151], v143 offset:32768
	ds_read_b128 v[152:155], v143 offset:33792
	ds_read_b128 v[156:159], v143 offset:34816
	ds_read_b128 v[160:163], v143 offset:35840
	ds_read_b128 v[164:167], v143 offset:49152
	ds_read_b128 v[168:171], v143 offset:50176
	ds_read_b128 v[172:175], v143 offset:51200
	ds_read_b128 v[176:179], v143 offset:52224
	s_add_u32 s0, s4, 0x20000
	s_addc_u32 s1, s5, 0
	s_mov_b32 m0, s27
	ds_read_b128 v[180:183], v146 offset:32768
	ds_read_b128 v[184:187], v146 offset:33792
	ds_read_b128 v[188:191], v146 offset:34816
	ds_read_b128 v[192:195], v146 offset:35840
	ds_read_b128 v[196:199], v146 offset:36864
	ds_read_b128 v[208:211], v146 offset:37888
	ds_read_b128 v[212:215], v146 offset:38912
	ds_read_b128 v[216:219], v146 offset:39936
	global_load_lds_dwordx4 v136, s[0:1]
	s_mov_b32 m0, s28
	s_nop 0
	global_load_lds_dwordx4 v132, s[0:1]
	.p2align 3
	s_waitcnt vmcnt(8)
	s_waitcnt lgkmcnt(0)
	s_setprio 1
	s_barrier
	v_mfma_f32_16x16x32_bf16 v[126:129], v[148:151], v[180:183], v[126:129]
	v_mfma_f32_16x16x32_bf16 v[122:125], v[156:159], v[180:183], v[122:125]
	v_mfma_f32_16x16x32_bf16 v[110:113], v[148:151], v[188:191], v[110:113]
	v_mfma_f32_16x16x32_bf16 v[106:109], v[156:159], v[188:191], v[106:109]
	v_mfma_f32_16x16x32_bf16 v[94:97], v[148:151], v[196:199], v[94:97]
	v_mfma_f32_16x16x32_bf16 v[90:93], v[156:159], v[196:199], v[90:93]
	v_mfma_f32_16x16x32_bf16 v[78:81], v[148:151], v[212:215], v[78:81]
	v_mfma_f32_16x16x32_bf16 v[74:77], v[156:159], v[212:215], v[74:77]
	v_mfma_f32_16x16x32_bf16 v[126:129], v[152:155], v[184:187], v[126:129]
	v_mfma_f32_16x16x32_bf16 v[122:125], v[160:163], v[184:187], v[122:125]
	v_mfma_f32_16x16x32_bf16 v[110:113], v[152:155], v[192:195], v[110:113]
	v_mfma_f32_16x16x32_bf16 v[106:109], v[160:163], v[192:195], v[106:109]
	v_mfma_f32_16x16x32_bf16 v[94:97], v[152:155], v[208:211], v[94:97]
	v_mfma_f32_16x16x32_bf16 v[90:93], v[160:163], v[208:211], v[90:93]
	v_mfma_f32_16x16x32_bf16 v[78:81], v[152:155], v[216:219], v[78:81]
	v_mfma_f32_16x16x32_bf16 v[74:77], v[160:163], v[216:219], v[74:77]
	v_mfma_f32_16x16x32_bf16 v[118:121], v[164:167], v[180:183], v[118:121]
	v_mfma_f32_16x16x32_bf16 v[114:117], v[172:175], v[180:183], v[114:117]
	v_mfma_f32_16x16x32_bf16 v[102:105], v[164:167], v[188:191], v[102:105]
	v_mfma_f32_16x16x32_bf16 v[98:101], v[172:175], v[188:191], v[98:101]
	v_mfma_f32_16x16x32_bf16 v[86:89], v[164:167], v[196:199], v[86:89]
	v_mfma_f32_16x16x32_bf16 v[82:85], v[172:175], v[196:199], v[82:85]
	v_mfma_f32_16x16x32_bf16 v[70:73], v[164:167], v[212:215], v[70:73]
	v_mfma_f32_16x16x32_bf16 v[66:69], v[172:175], v[212:215], v[66:69]
	v_mfma_f32_16x16x32_bf16 v[118:121], v[168:171], v[184:187], v[118:121]
	v_mfma_f32_16x16x32_bf16 v[114:117], v[176:179], v[184:187], v[114:117]
	v_mfma_f32_16x16x32_bf16 v[102:105], v[168:171], v[192:195], v[102:105]
	v_mfma_f32_16x16x32_bf16 v[98:101], v[176:179], v[192:195], v[98:101]
	v_mfma_f32_16x16x32_bf16 v[86:89], v[168:171], v[208:211], v[86:89]
	v_mfma_f32_16x16x32_bf16 v[82:85], v[176:179], v[208:211], v[82:85]
	v_mfma_f32_16x16x32_bf16 v[70:73], v[168:171], v[216:219], v[70:73]
	v_mfma_f32_16x16x32_bf16 v[66:69], v[176:179], v[216:219], v[66:69]
	s_barrier
	s_setprio 0
	s_add_i32 s0, s33, s24
	s_add_u32 s100, s2, 0x80
	s_addc_u32 s101, s3, 0
	s_mov_b32 m0, s0
	ds_read_b128 v[180:183], v146 offset:49152
	ds_read_b128 v[184:187], v146 offset:50176
	ds_read_b128 v[188:191], v146 offset:51200
	ds_read_b128 v[192:195], v146 offset:52224
	ds_read_b128 v[196:199], v146 offset:53248
	ds_read_b128 v[208:211], v146 offset:54272
	ds_read_b128 v[212:215], v146 offset:55296
	ds_read_b128 v[216:219], v146 offset:56320
	global_load_lds_dwordx4 v134, s[100:101]
	s_add_i32 m0, s0, 0x2000
	s_add_u32 s100, s2, 0x80
	s_addc_u32 s101, s3, 0
	s_add_u32 s0, s2, 0x20080
	s_addc_u32 s1, s3, 0
	s_add_i32 s2, s55, s24
	global_load_lds_dwordx4 v130, s[100:101]
	s_mov_b32 m0, s2
	s_nop 0
	global_load_lds_dwordx4 v134, s[0:1]
	s_add_i32 m0, s2, 0x2000
	s_nop 0
	global_load_lds_dwordx4 v130, s[0:1]
	s_add_u32 s100, s4, 0x80
	s_addc_u32 s101, s5, 0
	s_mov_b32 m0, s29
	s_nop 0
	global_load_lds_dwordx4 v136, s[100:101]
	s_add_u32 s100, s4, 0x80
	s_addc_u32 s101, s5, 0
	s_mov_b32 m0, s30
	s_nop 0
	global_load_lds_dwordx4 v132, s[100:101]
	.p2align 3
	s_waitcnt vmcnt(8)
	s_waitcnt lgkmcnt(0)
	s_setprio 1
	s_barrier
	v_mfma_f32_16x16x32_bf16 v[62:65], v[148:151], v[180:183], v[62:65]
	v_mfma_f32_16x16x32_bf16 v[58:61], v[156:159], v[180:183], v[58:61]
	v_mfma_f32_16x16x32_bf16 v[46:49], v[148:151], v[188:191], v[46:49]
	v_mfma_f32_16x16x32_bf16 v[42:45], v[156:159], v[188:191], v[42:45]
	v_mfma_f32_16x16x32_bf16 v[30:33], v[148:151], v[196:199], v[30:33]
	v_mfma_f32_16x16x32_bf16 v[26:29], v[156:159], v[196:199], v[26:29]
	v_mfma_f32_16x16x32_bf16 v[14:17], v[148:151], v[212:215], v[14:17]
	v_mfma_f32_16x16x32_bf16 v[10:13], v[156:159], v[212:215], v[10:13]
	v_mfma_f32_16x16x32_bf16 v[62:65], v[152:155], v[184:187], v[62:65]
	v_mfma_f32_16x16x32_bf16 v[58:61], v[160:163], v[184:187], v[58:61]
	v_mfma_f32_16x16x32_bf16 v[46:49], v[152:155], v[192:195], v[46:49]
	v_mfma_f32_16x16x32_bf16 v[42:45], v[160:163], v[192:195], v[42:45]
	v_mfma_f32_16x16x32_bf16 v[30:33], v[152:155], v[208:211], v[30:33]
	v_mfma_f32_16x16x32_bf16 v[26:29], v[160:163], v[208:211], v[26:29]
	v_mfma_f32_16x16x32_bf16 v[14:17], v[152:155], v[216:219], v[14:17]
	v_mfma_f32_16x16x32_bf16 v[10:13], v[160:163], v[216:219], v[10:13]
	v_mfma_f32_16x16x32_bf16 v[54:57], v[164:167], v[180:183], v[54:57]
	v_mfma_f32_16x16x32_bf16 v[50:53], v[172:175], v[180:183], v[50:53]
	v_mfma_f32_16x16x32_bf16 v[38:41], v[164:167], v[188:191], v[38:41]
	v_mfma_f32_16x16x32_bf16 v[34:37], v[172:175], v[188:191], v[34:37]
	v_mfma_f32_16x16x32_bf16 v[22:25], v[164:167], v[196:199], v[22:25]
	v_mfma_f32_16x16x32_bf16 v[18:21], v[172:175], v[196:199], v[18:21]
	v_mfma_f32_16x16x32_bf16 v[6:9], v[164:167], v[212:215], v[6:9]
	v_mfma_f32_16x16x32_bf16 v[2:5], v[172:175], v[212:215], v[2:5]
	v_mfma_f32_16x16x32_bf16 v[54:57], v[168:171], v[184:187], v[54:57]
	v_mfma_f32_16x16x32_bf16 v[50:53], v[176:179], v[184:187], v[50:53]
	v_mfma_f32_16x16x32_bf16 v[38:41], v[168:171], v[192:195], v[38:41]
	v_mfma_f32_16x16x32_bf16 v[34:37], v[176:179], v[192:195], v[34:37]
	v_mfma_f32_16x16x32_bf16 v[22:25], v[168:171], v[208:211], v[22:25]
	v_mfma_f32_16x16x32_bf16 v[18:21], v[176:179], v[208:211], v[18:21]
	v_mfma_f32_16x16x32_bf16 v[6:9], v[168:171], v[216:219], v[6:9]
	v_mfma_f32_16x16x32_bf16 v[2:5], v[176:179], v[216:219], v[2:5]
	s_barrier
	s_setprio 0
	s_add_i32 s59, s59, 2
	s_add_u32 s20, s20, 0x100
	s_addc_u32 s21, s21, 0
	s_add_u32 s49, s49, 0x100
	s_addc_u32 s58, s58, 0
	s_cmp_gt_u32 s59, 5
	s_cbranch_scc0 .LBB0_1363
	s_and_b64 vcc, exec, s[14:15]
	s_cbranch_vccz .LBB0_1366
	s_barrier

.LBB0_1427:
	s_ashr_i32 s17, s16, 31
	s_lshl_b64 s[0:1], s[16:17], 20
	s_add_u32 s18, s64, s0
	s_addc_u32 s19, s65, s1
	s_and_b64 s[0:1], s[6:7], exec
	s_cselect_b32 s17, s19, s5
	s_cselect_b32 s49, s18, s4
	s_ashr_i32 s15, s14, 31
	s_lshl_b64 s[0:1], s[14:15], 20
	s_add_u32 s20, s28, s0
	s_addc_u32 s21, s29, s1
	s_and_b64 s[0:1], s[6:7], exec
	s_cselect_b32 s15, s21, s3
	s_cselect_b32 s58, s20, s2
	s_add_u32 s26, s4, 0x80080
	s_addc_u32 s27, s5, 0
	s_add_u32 s59, s2, 0x100
	v_mov_b32_e32 v2, 0
	s_addc_u32 s60, s3, 0
	s_mov_b32 s61, -2
	v_mov_b32_e32 v3, v2
	v_pk_mov_b32 v[4:5], v[2:3], v[2:3] op_sel:[0,1]
	v_pk_mov_b32 v[10:11], v[2:3], v[2:3] op_sel:[0,1]
	v_pk_mov_b32 v[12:13], v[2:3], v[2:3] op_sel:[0,1]
	v_pk_mov_b32 v[18:19], v[2:3], v[2:3] op_sel:[0,1]
	v_pk_mov_b32 v[20:21], v[2:3], v[2:3] op_sel:[0,1]
	v_pk_mov_b32 v[26:27], v[2:3], v[2:3] op_sel:[0,1]
	v_pk_mov_b32 v[28:29], v[2:3], v[2:3] op_sel:[0,1]
	v_pk_mov_b32 v[34:35], v[2:3], v[2:3] op_sel:[0,1]
	v_pk_mov_b32 v[36:37], v[2:3], v[2:3] op_sel:[0,1]
	v_pk_mov_b32 v[42:43], v[2:3], v[2:3] op_sel:[0,1]
	v_pk_mov_b32 v[44:45], v[2:3], v[2:3] op_sel:[0,1]
	v_pk_mov_b32 v[50:51], v[2:3], v[2:3] op_sel:[0,1]
	v_pk_mov_b32 v[52:53], v[2:3], v[2:3] op_sel:[0,1]
	v_pk_mov_b32 v[58:59], v[2:3], v[2:3] op_sel:[0,1]
	v_pk_mov_b32 v[60:61], v[2:3], v[2:3] op_sel:[0,1]
	v_pk_mov_b32 v[6:7], v[2:3], v[2:3] op_sel:[0,1]
	v_pk_mov_b32 v[8:9], v[2:3], v[2:3] op_sel:[0,1]
	v_pk_mov_b32 v[14:15], v[2:3], v[2:3] op_sel:[0,1]
	v_pk_mov_b32 v[16:17], v[2:3], v[2:3] op_sel:[0,1]
	v_pk_mov_b32 v[22:23], v[2:3], v[2:3] op_sel:[0,1]
	v_pk_mov_b32 v[24:25], v[2:3], v[2:3] op_sel:[0,1]
	v_pk_mov_b32 v[30:31], v[2:3], v[2:3] op_sel:[0,1]
	v_pk_mov_b32 v[32:33], v[2:3], v[2:3] op_sel:[0,1]
	v_pk_mov_b32 v[38:39], v[2:3], v[2:3] op_sel:[0,1]
	v_pk_mov_b32 v[40:41], v[2:3], v[2:3] op_sel:[0,1]
	v_pk_mov_b32 v[46:47], v[2:3], v[2:3] op_sel:[0,1]
	v_pk_mov_b32 v[48:49], v[2:3], v[2:3] op_sel:[0,1]
	v_pk_mov_b32 v[54:55], v[2:3], v[2:3] op_sel:[0,1]
	v_pk_mov_b32 v[56:57], v[2:3], v[2:3] op_sel:[0,1]
	v_pk_mov_b32 v[62:63], v[2:3], v[2:3] op_sel:[0,1]
	v_pk_mov_b32 v[64:65], v[2:3], v[2:3] op_sel:[0,1]
	v_pk_mov_b32 v[66:67], v[2:3], v[2:3] op_sel:[0,1]
	v_pk_mov_b32 v[68:69], v[2:3], v[2:3] op_sel:[0,1]
	v_pk_mov_b32 v[74:75], v[2:3], v[2:3] op_sel:[0,1]
	v_pk_mov_b32 v[76:77], v[2:3], v[2:3] op_sel:[0,1]
	v_pk_mov_b32 v[82:83], v[2:3], v[2:3] op_sel:[0,1]
	v_pk_mov_b32 v[84:85], v[2:3], v[2:3] op_sel:[0,1]
	v_pk_mov_b32 v[90:91], v[2:3], v[2:3] op_sel:[0,1]
	v_pk_mov_b32 v[92:93], v[2:3], v[2:3] op_sel:[0,1]
	v_pk_mov_b32 v[98:99], v[2:3], v[2:3] op_sel:[0,1]
	v_pk_mov_b32 v[100:101], v[2:3], v[2:3] op_sel:[0,1]
	v_pk_mov_b32 v[106:107], v[2:3], v[2:3] op_sel:[0,1]
	v_pk_mov_b32 v[108:109], v[2:3], v[2:3] op_sel:[0,1]
	v_pk_mov_b32 v[114:115], v[2:3], v[2:3] op_sel:[0,1]
	v_pk_mov_b32 v[116:117], v[2:3], v[2:3] op_sel:[0,1]
	v_pk_mov_b32 v[122:123], v[2:3], v[2:3] op_sel:[0,1]
	v_pk_mov_b32 v[124:125], v[2:3], v[2:3] op_sel:[0,1]
	v_pk_mov_b32 v[70:71], v[2:3], v[2:3] op_sel:[0,1]
	v_pk_mov_b32 v[72:73], v[2:3], v[2:3] op_sel:[0,1]
	v_pk_mov_b32 v[78:79], v[2:3], v[2:3] op_sel:[0,1]
	v_pk_mov_b32 v[80:81], v[2:3], v[2:3] op_sel:[0,1]
	v_pk_mov_b32 v[86:87], v[2:3], v[2:3] op_sel:[0,1]
	v_pk_mov_b32 v[88:89], v[2:3], v[2:3] op_sel:[0,1]
	v_pk_mov_b32 v[94:95], v[2:3], v[2:3] op_sel:[0,1]
	v_pk_mov_b32 v[96:97], v[2:3], v[2:3] op_sel:[0,1]
	v_pk_mov_b32 v[102:103], v[2:3], v[2:3] op_sel:[0,1]
	v_pk_mov_b32 v[104:105], v[2:3], v[2:3] op_sel:[0,1]
	v_pk_mov_b32 v[110:111], v[2:3], v[2:3] op_sel:[0,1]
	v_pk_mov_b32 v[112:113], v[2:3], v[2:3] op_sel:[0,1]
	v_pk_mov_b32 v[118:119], v[2:3], v[2:3] op_sel:[0,1]
	v_pk_mov_b32 v[120:121], v[2:3], v[2:3] op_sel:[0,1]
	v_pk_mov_b32 v[130:131], v[2:3], v[2:3] op_sel:[0,1]
	v_pk_mov_b32 v[132:133], v[2:3], v[2:3] op_sel:[0,1]
	.p2align 6
.LBB0_1428:
	s_add_u32 s0, s26, 0xfff80080
	s_addc_u32 s1, s27, -1
	s_add_i32 s33, 0, 0x10000
	s_cmp_eq_u32 s61, 28
	s_cselect_b32 s5, s17, s1
	s_cselect_b32 s4, s49, s0
	s_cselect_b32 s3, s15, s60
	s_cselect_b32 s2, s58, s59
	s_add_i32 s55, 0, 0x14000
	ds_read_b128 v[126:129], v187
	ds_read_b128 v[134:137], v187 offset:1024
	ds_read_b128 v[138:141], v187 offset:2048
	ds_read_b128 v[142:145], v187 offset:3072
	ds_read_b128 v[146:149], v187 offset:16384
	ds_read_b128 v[150:153], v187 offset:17408
	ds_read_b128 v[154:157], v187 offset:18432
	ds_read_b128 v[158:161], v187 offset:19456
	s_add_i32 m0, s23, 0xc000
	ds_read_b128 v[172:175], v189
	ds_read_b128 v[176:179], v189 offset:1024
	ds_read_b128 v[180:183], v189 offset:2048
	ds_read_b128 v[190:193], v189 offset:3072
	ds_read_b128 v[194:197], v189 offset:4096
	ds_read_b128 v[198:201], v189 offset:5120
	ds_read_b128 v[208:211], v189 offset:6144
	ds_read_b128 v[212:215], v189 offset:7168
	global_load_lds_dwordx4 v168, s[26:27]
	s_add_i32 m0, s23, 0xe000
	s_nop 0
	global_load_lds_dwordx4 v170, s[26:27]
	.p2align 3
	s_waitcnt vmcnt(8)
	s_waitcnt lgkmcnt(0)
	s_setprio 1
	s_barrier
	v_mfma_f32_16x16x32_bf16 v[130:133], v[126:129], v[172:175], v[130:133]
	v_mfma_f32_16x16x32_bf16 v[118:121], v[138:141], v[172:175], v[118:121]
	v_mfma_f32_16x16x32_bf16 v[110:113], v[126:129], v[180:183], v[110:113]
	v_mfma_f32_16x16x32_bf16 v[102:105], v[138:141], v[180:183], v[102:105]
	v_mfma_f32_16x16x32_bf16 v[94:97], v[126:129], v[194:197], v[94:97]
	v_mfma_f32_16x16x32_bf16 v[86:89], v[138:141], v[194:197], v[86:89]
	v_mfma_f32_16x16x32_bf16 v[78:81], v[126:129], v[208:211], v[78:81]
	v_mfma_f32_16x16x32_bf16 v[70:73], v[138:141], v[208:211], v[70:73]
	v_mfma_f32_16x16x32_bf16 v[130:133], v[134:137], v[176:179], v[130:133]
	v_mfma_f32_16x16x32_bf16 v[118:121], v[142:145], v[176:179], v[118:121]
	v_mfma_f32_16x16x32_bf16 v[110:113], v[134:137], v[190:193], v[110:113]
	v_mfma_f32_16x16x32_bf16 v[102:105], v[142:145], v[190:193], v[102:105]
	v_mfma_f32_16x16x32_bf16 v[94:97], v[134:137], v[198:201], v[94:97]
	v_mfma_f32_16x16x32_bf16 v[86:89], v[142:145], v[198:201], v[86:89]
	v_mfma_f32_16x16x32_bf16 v[78:81], v[134:137], v[212:215], v[78:81]
	v_mfma_f32_16x16x32_bf16 v[70:73], v[142:145], v[212:215], v[70:73]
	v_mfma_f32_16x16x32_bf16 v[122:125], v[146:149], v[172:175], v[122:125]
	v_mfma_f32_16x16x32_bf16 v[114:117], v[154:157], v[172:175], v[114:117]
	v_mfma_f32_16x16x32_bf16 v[106:109], v[146:149], v[180:183], v[106:109]
	v_mfma_f32_16x16x32_bf16 v[98:101], v[154:157], v[180:183], v[98:101]
	v_mfma_f32_16x16x32_bf16 v[90:93], v[146:149], v[194:197], v[90:93]
	v_mfma_f32_16x16x32_bf16 v[82:85], v[154:157], v[194:197], v[82:85]
	v_mfma_f32_16x16x32_bf16 v[74:77], v[146:149], v[208:211], v[74:77]
	v_mfma_f32_16x16x32_bf16 v[66:69], v[154:157], v[208:211], v[66:69]
	v_mfma_f32_16x16x32_bf16 v[122:125], v[150:153], v[176:179], v[122:125]
	v_mfma_f32_16x16x32_bf16 v[114:117], v[158:161], v[176:179], v[114:117]
	v_mfma_f32_16x16x32_bf16 v[106:109], v[150:153], v[190:193], v[106:109]
	v_mfma_f32_16x16x32_bf16 v[98:101], v[158:161], v[190:193], v[98:101]
	v_mfma_f32_16x16x32_bf16 v[90:93], v[150:153], v[198:201], v[90:93]
	v_mfma_f32_16x16x32_bf16 v[82:85], v[158:161], v[198:201], v[82:85]
	v_mfma_f32_16x16x32_bf16 v[74:77], v[150:153], v[212:215], v[74:77]
	v_mfma_f32_16x16x32_bf16 v[66:69], v[158:161], v[212:215], v[66:69]
	s_barrier
	s_setprio 0
	s_add_i32 s0, s33, s34
	s_mov_b32 m0, s0
	ds_read_b128 v[172:175], v189 offset:16384
	ds_read_b128 v[176:179], v189 offset:17408
	ds_read_b128 v[180:183], v189 offset:18432
	ds_read_b128 v[190:193], v189 offset:19456
	ds_read_b128 v[194:197], v189 offset:20480
	ds_read_b128 v[198:201], v189 offset:21504
	ds_read_b128 v[208:211], v189 offset:22528
	ds_read_b128 v[212:215], v189 offset:23552
	global_load_lds_dwordx4 v202, s[2:3]
	s_add_i32 m0, s0, 0x2000
	s_add_u32 s0, s2, 0x80000
	s_addc_u32 s1, s3, 0
	s_add_i32 s33, s55, s34
	global_load_lds_dwordx4 v162, s[2:3]
	s_mov_b32 m0, s33
	s_nop 0
	global_load_lds_dwordx4 v202, s[0:1]
	s_add_i32 m0, s33, 0x2000
	s_nop 0
	global_load_lds_dwordx4 v162, s[0:1]
	s_mov_b32 m0, s23
	s_nop 0
	global_load_lds_dwordx4 v166, s[4:5]
	s_mov_b32 m0, s25
	s_nop 0
	global_load_lds_dwordx4 v164, s[4:5]
	.p2align 3
	s_waitcnt vmcnt(8)
	s_waitcnt lgkmcnt(0)
	s_setprio 1
	s_barrier
	v_mfma_f32_16x16x32_bf16 v[62:65], v[126:129], v[172:175], v[62:65]
	v_mfma_f32_16x16x32_bf16 v[54:57], v[138:141], v[172:175], v[54:57]
	v_mfma_f32_16x16x32_bf16 v[46:49], v[126:129], v[180:183], v[46:49]
	v_mfma_f32_16x16x32_bf16 v[38:41], v[138:141], v[180:183], v[38:41]
	v_mfma_f32_16x16x32_bf16 v[30:33], v[126:129], v[194:197], v[30:33]
	v_mfma_f32_16x16x32_bf16 v[22:25], v[138:141], v[194:197], v[22:25]
	v_mfma_f32_16x16x32_bf16 v[14:17], v[126:129], v[208:211], v[14:17]
	v_mfma_f32_16x16x32_bf16 v[6:9], v[138:141], v[208:211], v[6:9]
	v_mfma_f32_16x16x32_bf16 v[62:65], v[134:137], v[176:179], v[62:65]
	v_mfma_f32_16x16x32_bf16 v[54:57], v[142:145], v[176:179], v[54:57]
	v_mfma_f32_16x16x32_bf16 v[46:49], v[134:137], v[190:193], v[46:49]
	v_mfma_f32_16x16x32_bf16 v[38:41], v[142:145], v[190:193], v[38:41]
	v_mfma_f32_16x16x32_bf16 v[30:33], v[134:137], v[198:201], v[30:33]
	v_mfma_f32_16x16x32_bf16 v[22:25], v[142:145], v[198:201], v[22:25]
	v_mfma_f32_16x16x32_bf16 v[14:17], v[134:137], v[212:215], v[14:17]
	v_mfma_f32_16x16x32_bf16 v[6:9], v[142:145], v[212:215], v[6:9]
	v_mfma_f32_16x16x32_bf16 v[58:61], v[146:149], v[172:175], v[58:61]
	v_mfma_f32_16x16x32_bf16 v[50:53], v[154:157], v[172:175], v[50:53]
	v_mfma_f32_16x16x32_bf16 v[42:45], v[146:149], v[180:183], v[42:45]
	v_mfma_f32_16x16x32_bf16 v[34:37], v[154:157], v[180:183], v[34:37]
	v_mfma_f32_16x16x32_bf16 v[26:29], v[146:149], v[194:197], v[26:29]
	v_mfma_f32_16x16x32_bf16 v[18:21], v[154:157], v[194:197], v[18:21]
	v_mfma_f32_16x16x32_bf16 v[10:13], v[146:149], v[208:211], v[10:13]
	v_mfma_f32_16x16x32_bf16 v[2:5], v[154:157], v[208:211], v[2:5]
	v_mfma_f32_16x16x32_bf16 v[58:61], v[150:153], v[176:179], v[58:61]
	v_mfma_f32_16x16x32_bf16 v[50:53], v[158:161], v[176:179], v[50:53]
	v_mfma_f32_16x16x32_bf16 v[42:45], v[150:153], v[190:193], v[42:45]
	v_mfma_f32_16x16x32_bf16 v[34:37], v[158:161], v[190:193], v[34:37]
	v_mfma_f32_16x16x32_bf16 v[26:29], v[150:153], v[198:201], v[26:29]
	v_mfma_f32_16x16x32_bf16 v[18:21], v[158:161], v[198:201], v[18:21]
	v_mfma_f32_16x16x32_bf16 v[10:13], v[150:153], v[212:215], v[10:13]
	v_mfma_f32_16x16x32_bf16 v[2:5], v[158:161], v[212:215], v[2:5]
	s_barrier
	s_setprio 0
	s_add_i32 s33, 0, 0x18000
	s_add_i32 s55, 0, 0x1c000
	ds_read_b128 v[126:129], v187 offset:32768
	ds_read_b128 v[134:137], v187 offset:33792
	ds_read_b128 v[138:141], v187 offset:34816
	ds_read_b128 v[142:145], v187 offset:35840
	ds_read_b128 v[146:149], v187 offset:49152
	ds_read_b128 v[150:153], v187 offset:50176
	ds_read_b128 v[154:157], v187 offset:51200
	ds_read_b128 v[158:161], v187 offset:52224
	s_add_u32 s0, s4, 0x80000
	s_addc_u32 s1, s5, 0
	s_mov_b32 m0, s35
	ds_read_b128 v[172:175], v189 offset:32768
	ds_read_b128 v[176:179], v189 offset:33792
	ds_read_b128 v[180:183], v189 offset:34816
	ds_read_b128 v[190:193], v189 offset:35840
	ds_read_b128 v[194:197], v189 offset:36864
	ds_read_b128 v[198:201], v189 offset:37888
	ds_read_b128 v[208:211], v189 offset:38912
	ds_read_b128 v[212:215], v189 offset:39936
	global_load_lds_dwordx4 v166, s[0:1]
	s_mov_b32 m0, s36
	s_nop 0
	global_load_lds_dwordx4 v164, s[0:1]
	.p2align 3
	s_waitcnt vmcnt(8)
	s_waitcnt lgkmcnt(0)
	s_setprio 1
	s_barrier
	v_mfma_f32_16x16x32_bf16 v[130:133], v[126:129], v[172:175], v[130:133]
	v_mfma_f32_16x16x32_bf16 v[118:121], v[138:141], v[172:175], v[118:121]
	v_mfma_f32_16x16x32_bf16 v[110:113], v[126:129], v[180:183], v[110:113]
	v_mfma_f32_16x16x32_bf16 v[102:105], v[138:141], v[180:183], v[102:105]
	v_mfma_f32_16x16x32_bf16 v[94:97], v[126:129], v[194:197], v[94:97]
	v_mfma_f32_16x16x32_bf16 v[86:89], v[138:141], v[194:197], v[86:89]
	v_mfma_f32_16x16x32_bf16 v[78:81], v[126:129], v[208:211], v[78:81]
	v_mfma_f32_16x16x32_bf16 v[70:73], v[138:141], v[208:211], v[70:73]
	v_mfma_f32_16x16x32_bf16 v[130:133], v[134:137], v[176:179], v[130:133]
	v_mfma_f32_16x16x32_bf16 v[118:121], v[142:145], v[176:179], v[118:121]
	v_mfma_f32_16x16x32_bf16 v[110:113], v[134:137], v[190:193], v[110:113]
	v_mfma_f32_16x16x32_bf16 v[102:105], v[142:145], v[190:193], v[102:105]
	v_mfma_f32_16x16x32_bf16 v[94:97], v[134:137], v[198:201], v[94:97]
	v_mfma_f32_16x16x32_bf16 v[86:89], v[142:145], v[198:201], v[86:89]
	v_mfma_f32_16x16x32_bf16 v[78:81], v[134:137], v[212:215], v[78:81]
	v_mfma_f32_16x16x32_bf16 v[70:73], v[142:145], v[212:215], v[70:73]
	v_mfma_f32_16x16x32_bf16 v[122:125], v[146:149], v[172:175], v[122:125]
	v_mfma_f32_16x16x32_bf16 v[114:117], v[154:157], v[172:175], v[114:117]
	v_mfma_f32_16x16x32_bf16 v[106:109], v[146:149], v[180:183], v[106:109]
	v_mfma_f32_16x16x32_bf16 v[98:101], v[154:157], v[180:183], v[98:101]
	v_mfma_f32_16x16x32_bf16 v[90:93], v[146:149], v[194:197], v[90:93]
	v_mfma_f32_16x16x32_bf16 v[82:85], v[154:157], v[194:197], v[82:85]
	v_mfma_f32_16x16x32_bf16 v[74:77], v[146:149], v[208:211], v[74:77]
	v_mfma_f32_16x16x32_bf16 v[66:69], v[154:157], v[208:211], v[66:69]
	v_mfma_f32_16x16x32_bf16 v[122:125], v[150:153], v[176:179], v[122:125]
	v_mfma_f32_16x16x32_bf16 v[114:117], v[158:161], v[176:179], v[114:117]
	v_mfma_f32_16x16x32_bf16 v[106:109], v[150:153], v[190:193], v[106:109]
	v_mfma_f32_16x16x32_bf16 v[98:101], v[158:161], v[190:193], v[98:101]
	v_mfma_f32_16x16x32_bf16 v[90:93], v[150:153], v[198:201], v[90:93]
	v_mfma_f32_16x16x32_bf16 v[82:85], v[158:161], v[198:201], v[82:85]
	v_mfma_f32_16x16x32_bf16 v[74:77], v[150:153], v[212:215], v[74:77]
	v_mfma_f32_16x16x32_bf16 v[66:69], v[158:161], v[212:215], v[66:69]
	s_barrier
	s_setprio 0
	s_add_i32 s0, s33, s34
	s_add_u32 s100, s2, 0x80
	s_addc_u32 s101, s3, 0
	s_mov_b32 m0, s0
	ds_read_b128 v[172:175], v189 offset:49152
	ds_read_b128 v[176:179], v189 offset:50176
	ds_read_b128 v[180:183], v189 offset:51200
	ds_read_b128 v[190:193], v189 offset:52224
	ds_read_b128 v[194:197], v189 offset:53248
	ds_read_b128 v[198:201], v189 offset:54272
	ds_read_b128 v[208:211], v189 offset:55296
	ds_read_b128 v[212:215], v189 offset:56320
	global_load_lds_dwordx4 v202, s[100:101]
	s_add_i32 m0, s0, 0x2000
	s_add_u32 s100, s2, 0x80
	s_addc_u32 s101, s3, 0
	s_add_u32 s0, s2, 0x80080
	s_addc_u32 s1, s3, 0
	s_add_i32 s2, s55, s34
	global_load_lds_dwordx4 v162, s[100:101]
	s_mov_b32 m0, s2
	s_nop 0
	global_load_lds_dwordx4 v202, s[0:1]
	s_add_i32 m0, s2, 0x2000
	s_nop 0
	global_load_lds_dwordx4 v162, s[0:1]
	s_add_u32 s100, s4, 0x80
	s_addc_u32 s101, s5, 0
	s_mov_b32 m0, s39
	s_nop 0
	global_load_lds_dwordx4 v166, s[100:101]
	s_add_u32 s100, s4, 0x80
	s_addc_u32 s101, s5, 0
	s_mov_b32 m0, s40
	s_nop 0
	global_load_lds_dwordx4 v164, s[100:101]
	.p2align 3
	s_waitcnt vmcnt(8)
	s_waitcnt lgkmcnt(0)
	s_setprio 1
	s_barrier
	v_mfma_f32_16x16x32_bf16 v[62:65], v[126:129], v[172:175], v[62:65]
	v_mfma_f32_16x16x32_bf16 v[54:57], v[138:141], v[172:175], v[54:57]
	v_mfma_f32_16x16x32_bf16 v[46:49], v[126:129], v[180:183], v[46:49]
	v_mfma_f32_16x16x32_bf16 v[38:41], v[138:141], v[180:183], v[38:41]
	v_mfma_f32_16x16x32_bf16 v[30:33], v[126:129], v[194:197], v[30:33]
	v_mfma_f32_16x16x32_bf16 v[22:25], v[138:141], v[194:197], v[22:25]
	v_mfma_f32_16x16x32_bf16 v[14:17], v[126:129], v[208:211], v[14:17]
	v_mfma_f32_16x16x32_bf16 v[6:9], v[138:141], v[208:211], v[6:9]
	v_mfma_f32_16x16x32_bf16 v[62:65], v[134:137], v[176:179], v[62:65]
	v_mfma_f32_16x16x32_bf16 v[54:57], v[142:145], v[176:179], v[54:57]
	v_mfma_f32_16x16x32_bf16 v[46:49], v[134:137], v[190:193], v[46:49]
	v_mfma_f32_16x16x32_bf16 v[38:41], v[142:145], v[190:193], v[38:41]
	v_mfma_f32_16x16x32_bf16 v[30:33], v[134:137], v[198:201], v[30:33]
	v_mfma_f32_16x16x32_bf16 v[22:25], v[142:145], v[198:201], v[22:25]
	v_mfma_f32_16x16x32_bf16 v[14:17], v[134:137], v[212:215], v[14:17]
	v_mfma_f32_16x16x32_bf16 v[6:9], v[142:145], v[212:215], v[6:9]
	v_mfma_f32_16x16x32_bf16 v[58:61], v[146:149], v[172:175], v[58:61]
	v_mfma_f32_16x16x32_bf16 v[50:53], v[154:157], v[172:175], v[50:53]
	v_mfma_f32_16x16x32_bf16 v[42:45], v[146:149], v[180:183], v[42:45]
	v_mfma_f32_16x16x32_bf16 v[34:37], v[154:157], v[180:183], v[34:37]
	v_mfma_f32_16x16x32_bf16 v[26:29], v[146:149], v[194:197], v[26:29]
	v_mfma_f32_16x16x32_bf16 v[18:21], v[154:157], v[194:197], v[18:21]
	v_mfma_f32_16x16x32_bf16 v[10:13], v[146:149], v[208:211], v[10:13]
	v_mfma_f32_16x16x32_bf16 v[2:5], v[154:157], v[208:211], v[2:5]
	v_mfma_f32_16x16x32_bf16 v[58:61], v[150:153], v[176:179], v[58:61]
	v_mfma_f32_16x16x32_bf16 v[50:53], v[158:161], v[176:179], v[50:53]
	v_mfma_f32_16x16x32_bf16 v[42:45], v[150:153], v[190:193], v[42:45]
	v_mfma_f32_16x16x32_bf16 v[34:37], v[158:161], v[190:193], v[34:37]
	v_mfma_f32_16x16x32_bf16 v[26:29], v[150:153], v[198:201], v[26:29]
	v_mfma_f32_16x16x32_bf16 v[18:21], v[158:161], v[198:201], v[18:21]
	v_mfma_f32_16x16x32_bf16 v[10:13], v[150:153], v[212:215], v[10:13]
	v_mfma_f32_16x16x32_bf16 v[2:5], v[158:161], v[212:215], v[2:5]
	s_barrier
	s_setprio 0
	s_add_i32 s61, s61, 2
	s_add_u32 s26, s26, 0x100
	s_addc_u32 s27, s27, 0
	s_add_u32 s59, s59, 0x100
	s_addc_u32 s60, s60, 0
	s_cmp_gt_u32 s61, 29
	s_cbranch_scc0 .LBB0_1428
	s_and_b64 vcc, exec, s[10:11]
	s_cbranch_vccz .LBB0_1431
	s_barrier

.LBB0_1593:
	s_ashr_i32 s19, s18, 31
	s_lshl_b64 s[0:1], s[18:19], 20
	s_add_u32 s20, s42, s0
	s_addc_u32 s21, s43, s1
	s_and_b64 s[0:1], s[8:9], exec
	s_cselect_b32 s19, s21, s5
	s_cselect_b32 s49, s20, s4
	s_ashr_i32 s17, s16, 31
	s_lshl_b64 s[0:1], s[16:17], 20
	s_add_u32 s22, s30, s0
	s_addc_u32 s23, s31, s1
	s_and_b64 s[0:1], s[8:9], exec
	s_cselect_b32 s17, s23, s3
	s_cselect_b32 s58, s22, s2
	s_add_u32 s28, s4, 0x80080
	s_addc_u32 s29, s5, 0
	s_add_u32 s59, s2, 0x100
	v_mov_b32_e32 v2, 0
	s_addc_u32 s60, s3, 0
	s_mov_b32 s61, -2
	v_mov_b32_e32 v3, v2
	v_pk_mov_b32 v[4:5], v[2:3], v[2:3] op_sel:[0,1]
	v_pk_mov_b32 v[10:11], v[2:3], v[2:3] op_sel:[0,1]
	v_pk_mov_b32 v[12:13], v[2:3], v[2:3] op_sel:[0,1]
	v_pk_mov_b32 v[18:19], v[2:3], v[2:3] op_sel:[0,1]
	v_pk_mov_b32 v[20:21], v[2:3], v[2:3] op_sel:[0,1]
	v_pk_mov_b32 v[26:27], v[2:3], v[2:3] op_sel:[0,1]
	v_pk_mov_b32 v[28:29], v[2:3], v[2:3] op_sel:[0,1]
	v_pk_mov_b32 v[34:35], v[2:3], v[2:3] op_sel:[0,1]
	v_pk_mov_b32 v[36:37], v[2:3], v[2:3] op_sel:[0,1]
	v_pk_mov_b32 v[42:43], v[2:3], v[2:3] op_sel:[0,1]
	v_pk_mov_b32 v[44:45], v[2:3], v[2:3] op_sel:[0,1]
	v_pk_mov_b32 v[50:51], v[2:3], v[2:3] op_sel:[0,1]
	v_pk_mov_b32 v[52:53], v[2:3], v[2:3] op_sel:[0,1]
	v_pk_mov_b32 v[58:59], v[2:3], v[2:3] op_sel:[0,1]
	v_pk_mov_b32 v[60:61], v[2:3], v[2:3] op_sel:[0,1]
	v_pk_mov_b32 v[6:7], v[2:3], v[2:3] op_sel:[0,1]
	v_pk_mov_b32 v[8:9], v[2:3], v[2:3] op_sel:[0,1]
	v_pk_mov_b32 v[14:15], v[2:3], v[2:3] op_sel:[0,1]
	v_pk_mov_b32 v[16:17], v[2:3], v[2:3] op_sel:[0,1]
	v_pk_mov_b32 v[22:23], v[2:3], v[2:3] op_sel:[0,1]
	v_pk_mov_b32 v[24:25], v[2:3], v[2:3] op_sel:[0,1]
	v_pk_mov_b32 v[30:31], v[2:3], v[2:3] op_sel:[0,1]
	v_pk_mov_b32 v[32:33], v[2:3], v[2:3] op_sel:[0,1]
	v_pk_mov_b32 v[38:39], v[2:3], v[2:3] op_sel:[0,1]
	v_pk_mov_b32 v[40:41], v[2:3], v[2:3] op_sel:[0,1]
	v_pk_mov_b32 v[46:47], v[2:3], v[2:3] op_sel:[0,1]
	v_pk_mov_b32 v[48:49], v[2:3], v[2:3] op_sel:[0,1]
	v_pk_mov_b32 v[54:55], v[2:3], v[2:3] op_sel:[0,1]
	v_pk_mov_b32 v[56:57], v[2:3], v[2:3] op_sel:[0,1]
	v_pk_mov_b32 v[62:63], v[2:3], v[2:3] op_sel:[0,1]
	v_pk_mov_b32 v[64:65], v[2:3], v[2:3] op_sel:[0,1]
	v_pk_mov_b32 v[66:67], v[2:3], v[2:3] op_sel:[0,1]
	v_pk_mov_b32 v[68:69], v[2:3], v[2:3] op_sel:[0,1]
	v_pk_mov_b32 v[74:75], v[2:3], v[2:3] op_sel:[0,1]
	v_pk_mov_b32 v[76:77], v[2:3], v[2:3] op_sel:[0,1]
	v_pk_mov_b32 v[82:83], v[2:3], v[2:3] op_sel:[0,1]
	v_pk_mov_b32 v[84:85], v[2:3], v[2:3] op_sel:[0,1]
	v_pk_mov_b32 v[90:91], v[2:3], v[2:3] op_sel:[0,1]
	v_pk_mov_b32 v[92:93], v[2:3], v[2:3] op_sel:[0,1]
	v_pk_mov_b32 v[98:99], v[2:3], v[2:3] op_sel:[0,1]
	v_pk_mov_b32 v[100:101], v[2:3], v[2:3] op_sel:[0,1]
	v_pk_mov_b32 v[106:107], v[2:3], v[2:3] op_sel:[0,1]
	v_pk_mov_b32 v[108:109], v[2:3], v[2:3] op_sel:[0,1]
	v_pk_mov_b32 v[114:115], v[2:3], v[2:3] op_sel:[0,1]
	v_pk_mov_b32 v[116:117], v[2:3], v[2:3] op_sel:[0,1]
	v_pk_mov_b32 v[122:123], v[2:3], v[2:3] op_sel:[0,1]
	v_pk_mov_b32 v[124:125], v[2:3], v[2:3] op_sel:[0,1]
	v_pk_mov_b32 v[70:71], v[2:3], v[2:3] op_sel:[0,1]
	v_pk_mov_b32 v[72:73], v[2:3], v[2:3] op_sel:[0,1]
	v_pk_mov_b32 v[78:79], v[2:3], v[2:3] op_sel:[0,1]
	v_pk_mov_b32 v[80:81], v[2:3], v[2:3] op_sel:[0,1]
	v_pk_mov_b32 v[86:87], v[2:3], v[2:3] op_sel:[0,1]
	v_pk_mov_b32 v[88:89], v[2:3], v[2:3] op_sel:[0,1]
	v_pk_mov_b32 v[94:95], v[2:3], v[2:3] op_sel:[0,1]
	v_pk_mov_b32 v[96:97], v[2:3], v[2:3] op_sel:[0,1]
	v_pk_mov_b32 v[102:103], v[2:3], v[2:3] op_sel:[0,1]
	v_pk_mov_b32 v[104:105], v[2:3], v[2:3] op_sel:[0,1]
	v_pk_mov_b32 v[110:111], v[2:3], v[2:3] op_sel:[0,1]
	v_pk_mov_b32 v[112:113], v[2:3], v[2:3] op_sel:[0,1]
	v_pk_mov_b32 v[118:119], v[2:3], v[2:3] op_sel:[0,1]
	v_pk_mov_b32 v[120:121], v[2:3], v[2:3] op_sel:[0,1]
	v_pk_mov_b32 v[126:127], v[2:3], v[2:3] op_sel:[0,1]
	v_pk_mov_b32 v[128:129], v[2:3], v[2:3] op_sel:[0,1]
	.p2align 6
.LBB0_1594:
	s_add_u32 s0, s28, 0xfff80080
	s_addc_u32 s1, s29, -1
	s_add_i32 s33, 0, 0x10000
	s_cmp_eq_u32 s61, 28
	s_cselect_b32 s5, s19, s1
	s_cselect_b32 s4, s49, s0
	s_cselect_b32 s3, s17, s60
	s_cselect_b32 s2, s58, s59
	s_add_i32 s55, 0, 0x14000
	ds_read_b128 v[146:149], v143
	ds_read_b128 v[150:153], v143 offset:1024
	ds_read_b128 v[154:157], v143 offset:2048
	ds_read_b128 v[158:161], v143 offset:3072
	ds_read_b128 v[162:165], v143 offset:16384
	ds_read_b128 v[166:169], v143 offset:17408
	ds_read_b128 v[170:173], v143 offset:18432
	ds_read_b128 v[174:177], v143 offset:19456
	s_add_i32 m0, s25, 0xc000
	ds_read_b128 v[178:181], v145
	ds_read_b128 v[182:185], v145 offset:1024
	ds_read_b128 v[186:189], v145 offset:2048
	ds_read_b128 v[190:193], v145 offset:3072
	ds_read_b128 v[194:197], v145 offset:4096
	ds_read_b128 v[198:201], v145 offset:5120
	ds_read_b128 v[208:211], v145 offset:6144
	ds_read_b128 v[212:215], v145 offset:7168
	global_load_lds_dwordx4 v136, s[28:29]
	s_add_i32 m0, s25, 0xe000
	s_nop 0
	global_load_lds_dwordx4 v138, s[28:29]
	.p2align 3
	s_waitcnt vmcnt(8)
	s_waitcnt lgkmcnt(0)
	s_setprio 1
	s_barrier
	v_mfma_f32_16x16x32_bf16 v[126:129], v[146:149], v[178:181], v[126:129]
	v_mfma_f32_16x16x32_bf16 v[118:121], v[154:157], v[178:181], v[118:121]
	v_mfma_f32_16x16x32_bf16 v[110:113], v[146:149], v[186:189], v[110:113]
	v_mfma_f32_16x16x32_bf16 v[102:105], v[154:157], v[186:189], v[102:105]
	v_mfma_f32_16x16x32_bf16 v[94:97], v[146:149], v[194:197], v[94:97]
	v_mfma_f32_16x16x32_bf16 v[86:89], v[154:157], v[194:197], v[86:89]
	v_mfma_f32_16x16x32_bf16 v[78:81], v[146:149], v[208:211], v[78:81]
	v_mfma_f32_16x16x32_bf16 v[70:73], v[154:157], v[208:211], v[70:73]
	v_mfma_f32_16x16x32_bf16 v[126:129], v[150:153], v[182:185], v[126:129]
	v_mfma_f32_16x16x32_bf16 v[118:121], v[158:161], v[182:185], v[118:121]
	v_mfma_f32_16x16x32_bf16 v[110:113], v[150:153], v[190:193], v[110:113]
	v_mfma_f32_16x16x32_bf16 v[102:105], v[158:161], v[190:193], v[102:105]
	v_mfma_f32_16x16x32_bf16 v[94:97], v[150:153], v[198:201], v[94:97]
	v_mfma_f32_16x16x32_bf16 v[86:89], v[158:161], v[198:201], v[86:89]
	v_mfma_f32_16x16x32_bf16 v[78:81], v[150:153], v[212:215], v[78:81]
	v_mfma_f32_16x16x32_bf16 v[70:73], v[158:161], v[212:215], v[70:73]
	v_mfma_f32_16x16x32_bf16 v[122:125], v[162:165], v[178:181], v[122:125]
	v_mfma_f32_16x16x32_bf16 v[114:117], v[170:173], v[178:181], v[114:117]
	v_mfma_f32_16x16x32_bf16 v[106:109], v[162:165], v[186:189], v[106:109]
	v_mfma_f32_16x16x32_bf16 v[98:101], v[170:173], v[186:189], v[98:101]
	v_mfma_f32_16x16x32_bf16 v[90:93], v[162:165], v[194:197], v[90:93]
	v_mfma_f32_16x16x32_bf16 v[82:85], v[170:173], v[194:197], v[82:85]
	v_mfma_f32_16x16x32_bf16 v[74:77], v[162:165], v[208:211], v[74:77]
	v_mfma_f32_16x16x32_bf16 v[66:69], v[170:173], v[208:211], v[66:69]
	v_mfma_f32_16x16x32_bf16 v[122:125], v[166:169], v[182:185], v[122:125]
	v_mfma_f32_16x16x32_bf16 v[114:117], v[174:177], v[182:185], v[114:117]
	v_mfma_f32_16x16x32_bf16 v[106:109], v[166:169], v[190:193], v[106:109]
	v_mfma_f32_16x16x32_bf16 v[98:101], v[174:177], v[190:193], v[98:101]
	v_mfma_f32_16x16x32_bf16 v[90:93], v[166:169], v[198:201], v[90:93]
	v_mfma_f32_16x16x32_bf16 v[82:85], v[174:177], v[198:201], v[82:85]
	v_mfma_f32_16x16x32_bf16 v[74:77], v[166:169], v[212:215], v[74:77]
	v_mfma_f32_16x16x32_bf16 v[66:69], v[174:177], v[212:215], v[66:69]
	s_barrier
	s_setprio 0
	s_add_i32 s0, s33, s36
	s_mov_b32 m0, s0
	ds_read_b128 v[178:181], v145 offset:16384
	ds_read_b128 v[182:185], v145 offset:17408
	ds_read_b128 v[186:189], v145 offset:18432
	ds_read_b128 v[190:193], v145 offset:19456
	ds_read_b128 v[194:197], v145 offset:20480
	ds_read_b128 v[198:201], v145 offset:21504
	ds_read_b128 v[208:211], v145 offset:22528
	ds_read_b128 v[212:215], v145 offset:23552
	global_load_lds_dwordx4 v202, s[2:3]
	s_add_i32 m0, s0, 0x2000
	s_add_u32 s0, s2, 0x80000
	s_addc_u32 s1, s3, 0
	s_add_i32 s33, s55, s36
	global_load_lds_dwordx4 v130, s[2:3]
	s_mov_b32 m0, s33
	s_nop 0
	global_load_lds_dwordx4 v202, s[0:1]
	s_add_i32 m0, s33, 0x2000
	s_nop 0
	global_load_lds_dwordx4 v130, s[0:1]
	s_mov_b32 m0, s25
	s_nop 0
	global_load_lds_dwordx4 v134, s[4:5]
	s_mov_b32 m0, s27
	s_nop 0
	global_load_lds_dwordx4 v132, s[4:5]
	.p2align 3
	s_waitcnt vmcnt(8)
	s_waitcnt lgkmcnt(0)
	s_setprio 1
	s_barrier
	v_mfma_f32_16x16x32_bf16 v[62:65], v[146:149], v[178:181], v[62:65]
	v_mfma_f32_16x16x32_bf16 v[54:57], v[154:157], v[178:181], v[54:57]
	v_mfma_f32_16x16x32_bf16 v[46:49], v[146:149], v[186:189], v[46:49]
	v_mfma_f32_16x16x32_bf16 v[38:41], v[154:157], v[186:189], v[38:41]
	v_mfma_f32_16x16x32_bf16 v[30:33], v[146:149], v[194:197], v[30:33]
	v_mfma_f32_16x16x32_bf16 v[22:25], v[154:157], v[194:197], v[22:25]
	v_mfma_f32_16x16x32_bf16 v[14:17], v[146:149], v[208:211], v[14:17]
	v_mfma_f32_16x16x32_bf16 v[6:9], v[154:157], v[208:211], v[6:9]
	v_mfma_f32_16x16x32_bf16 v[62:65], v[150:153], v[182:185], v[62:65]
	v_mfma_f32_16x16x32_bf16 v[54:57], v[158:161], v[182:185], v[54:57]
	v_mfma_f32_16x16x32_bf16 v[46:49], v[150:153], v[190:193], v[46:49]
	v_mfma_f32_16x16x32_bf16 v[38:41], v[158:161], v[190:193], v[38:41]
	v_mfma_f32_16x16x32_bf16 v[30:33], v[150:153], v[198:201], v[30:33]
	v_mfma_f32_16x16x32_bf16 v[22:25], v[158:161], v[198:201], v[22:25]
	v_mfma_f32_16x16x32_bf16 v[14:17], v[150:153], v[212:215], v[14:17]
	v_mfma_f32_16x16x32_bf16 v[6:9], v[158:161], v[212:215], v[6:9]
	v_mfma_f32_16x16x32_bf16 v[58:61], v[162:165], v[178:181], v[58:61]
	v_mfma_f32_16x16x32_bf16 v[50:53], v[170:173], v[178:181], v[50:53]
	v_mfma_f32_16x16x32_bf16 v[42:45], v[162:165], v[186:189], v[42:45]
	v_mfma_f32_16x16x32_bf16 v[34:37], v[170:173], v[186:189], v[34:37]
	v_mfma_f32_16x16x32_bf16 v[26:29], v[162:165], v[194:197], v[26:29]
	v_mfma_f32_16x16x32_bf16 v[18:21], v[170:173], v[194:197], v[18:21]
	v_mfma_f32_16x16x32_bf16 v[10:13], v[162:165], v[208:211], v[10:13]
	v_mfma_f32_16x16x32_bf16 v[2:5], v[170:173], v[208:211], v[2:5]
	v_mfma_f32_16x16x32_bf16 v[58:61], v[166:169], v[182:185], v[58:61]
	v_mfma_f32_16x16x32_bf16 v[50:53], v[174:177], v[182:185], v[50:53]
	v_mfma_f32_16x16x32_bf16 v[42:45], v[166:169], v[190:193], v[42:45]
	v_mfma_f32_16x16x32_bf16 v[34:37], v[174:177], v[190:193], v[34:37]
	v_mfma_f32_16x16x32_bf16 v[26:29], v[166:169], v[198:201], v[26:29]
	v_mfma_f32_16x16x32_bf16 v[18:21], v[174:177], v[198:201], v[18:21]
	v_mfma_f32_16x16x32_bf16 v[10:13], v[166:169], v[212:215], v[10:13]
	v_mfma_f32_16x16x32_bf16 v[2:5], v[174:177], v[212:215], v[2:5]
	s_barrier
	s_setprio 0
	s_add_i32 s33, 0, 0x18000
	s_add_i32 s55, 0, 0x1c000
	ds_read_b128 v[146:149], v143 offset:32768
	ds_read_b128 v[150:153], v143 offset:33792
	ds_read_b128 v[154:157], v143 offset:34816
	ds_read_b128 v[158:161], v143 offset:35840
	ds_read_b128 v[162:165], v143 offset:49152
	ds_read_b128 v[166:169], v143 offset:50176
	ds_read_b128 v[170:173], v143 offset:51200
	ds_read_b128 v[174:177], v143 offset:52224
	s_add_u32 s0, s4, 0x80000
	s_addc_u32 s1, s5, 0
	s_mov_b32 m0, s37
	ds_read_b128 v[178:181], v145 offset:32768
	ds_read_b128 v[182:185], v145 offset:33792
	ds_read_b128 v[186:189], v145 offset:34816
	ds_read_b128 v[190:193], v145 offset:35840
	ds_read_b128 v[194:197], v145 offset:36864
	ds_read_b128 v[198:201], v145 offset:37888
	ds_read_b128 v[208:211], v145 offset:38912
	ds_read_b128 v[212:215], v145 offset:39936
	global_load_lds_dwordx4 v134, s[0:1]
	s_mov_b32 m0, s38
	s_nop 0
	global_load_lds_dwordx4 v132, s[0:1]
	.p2align 3
	s_waitcnt vmcnt(8)
	s_waitcnt lgkmcnt(0)
	s_setprio 1
	s_barrier
	v_mfma_f32_16x16x32_bf16 v[126:129], v[146:149], v[178:181], v[126:129]
	v_mfma_f32_16x16x32_bf16 v[118:121], v[154:157], v[178:181], v[118:121]
	v_mfma_f32_16x16x32_bf16 v[110:113], v[146:149], v[186:189], v[110:113]
	v_mfma_f32_16x16x32_bf16 v[102:105], v[154:157], v[186:189], v[102:105]
	v_mfma_f32_16x16x32_bf16 v[94:97], v[146:149], v[194:197], v[94:97]
	v_mfma_f32_16x16x32_bf16 v[86:89], v[154:157], v[194:197], v[86:89]
	v_mfma_f32_16x16x32_bf16 v[78:81], v[146:149], v[208:211], v[78:81]
	v_mfma_f32_16x16x32_bf16 v[70:73], v[154:157], v[208:211], v[70:73]
	v_mfma_f32_16x16x32_bf16 v[126:129], v[150:153], v[182:185], v[126:129]
	v_mfma_f32_16x16x32_bf16 v[118:121], v[158:161], v[182:185], v[118:121]
	v_mfma_f32_16x16x32_bf16 v[110:113], v[150:153], v[190:193], v[110:113]
	v_mfma_f32_16x16x32_bf16 v[102:105], v[158:161], v[190:193], v[102:105]
	v_mfma_f32_16x16x32_bf16 v[94:97], v[150:153], v[198:201], v[94:97]
	v_mfma_f32_16x16x32_bf16 v[86:89], v[158:161], v[198:201], v[86:89]
	v_mfma_f32_16x16x32_bf16 v[78:81], v[150:153], v[212:215], v[78:81]
	v_mfma_f32_16x16x32_bf16 v[70:73], v[158:161], v[212:215], v[70:73]
	v_mfma_f32_16x16x32_bf16 v[122:125], v[162:165], v[178:181], v[122:125]
	v_mfma_f32_16x16x32_bf16 v[114:117], v[170:173], v[178:181], v[114:117]
	v_mfma_f32_16x16x32_bf16 v[106:109], v[162:165], v[186:189], v[106:109]
	v_mfma_f32_16x16x32_bf16 v[98:101], v[170:173], v[186:189], v[98:101]
	v_mfma_f32_16x16x32_bf16 v[90:93], v[162:165], v[194:197], v[90:93]
	v_mfma_f32_16x16x32_bf16 v[82:85], v[170:173], v[194:197], v[82:85]
	v_mfma_f32_16x16x32_bf16 v[74:77], v[162:165], v[208:211], v[74:77]
	v_mfma_f32_16x16x32_bf16 v[66:69], v[170:173], v[208:211], v[66:69]
	v_mfma_f32_16x16x32_bf16 v[122:125], v[166:169], v[182:185], v[122:125]
	v_mfma_f32_16x16x32_bf16 v[114:117], v[174:177], v[182:185], v[114:117]
	v_mfma_f32_16x16x32_bf16 v[106:109], v[166:169], v[190:193], v[106:109]
	v_mfma_f32_16x16x32_bf16 v[98:101], v[174:177], v[190:193], v[98:101]
	v_mfma_f32_16x16x32_bf16 v[90:93], v[166:169], v[198:201], v[90:93]
	v_mfma_f32_16x16x32_bf16 v[82:85], v[174:177], v[198:201], v[82:85]
	v_mfma_f32_16x16x32_bf16 v[74:77], v[166:169], v[212:215], v[74:77]
	v_mfma_f32_16x16x32_bf16 v[66:69], v[174:177], v[212:215], v[66:69]
	s_barrier
	s_setprio 0
	s_add_i32 s0, s33, s36
	s_add_u32 s100, s2, 0x80
	s_addc_u32 s101, s3, 0
	s_mov_b32 m0, s0
	ds_read_b128 v[178:181], v145 offset:49152
	ds_read_b128 v[182:185], v145 offset:50176
	ds_read_b128 v[186:189], v145 offset:51200
	ds_read_b128 v[190:193], v145 offset:52224
	ds_read_b128 v[194:197], v145 offset:53248
	ds_read_b128 v[198:201], v145 offset:54272
	ds_read_b128 v[208:211], v145 offset:55296
	ds_read_b128 v[212:215], v145 offset:56320
	global_load_lds_dwordx4 v202, s[100:101]
	s_add_i32 m0, s0, 0x2000
	s_add_u32 s100, s2, 0x80
	s_addc_u32 s101, s3, 0
	s_add_u32 s0, s2, 0x80080
	s_addc_u32 s1, s3, 0
	s_add_i32 s2, s55, s36
	global_load_lds_dwordx4 v130, s[100:101]
	s_mov_b32 m0, s2
	s_nop 0
	global_load_lds_dwordx4 v202, s[0:1]
	s_add_i32 m0, s2, 0x2000
	s_nop 0
	global_load_lds_dwordx4 v130, s[0:1]
	s_add_u32 s100, s4, 0x80
	s_addc_u32 s101, s5, 0
	s_mov_b32 m0, s39
	s_nop 0
	global_load_lds_dwordx4 v134, s[100:101]
	s_add_u32 s100, s4, 0x80
	s_addc_u32 s101, s5, 0
	s_mov_b32 m0, s40
	s_nop 0
	global_load_lds_dwordx4 v132, s[100:101]
	.p2align 3
	s_waitcnt vmcnt(8)
	s_waitcnt lgkmcnt(0)
	s_setprio 1
	s_barrier
	v_mfma_f32_16x16x32_bf16 v[62:65], v[146:149], v[178:181], v[62:65]
	v_mfma_f32_16x16x32_bf16 v[54:57], v[154:157], v[178:181], v[54:57]
	v_mfma_f32_16x16x32_bf16 v[46:49], v[146:149], v[186:189], v[46:49]
	v_mfma_f32_16x16x32_bf16 v[38:41], v[154:157], v[186:189], v[38:41]
	v_mfma_f32_16x16x32_bf16 v[30:33], v[146:149], v[194:197], v[30:33]
	v_mfma_f32_16x16x32_bf16 v[22:25], v[154:157], v[194:197], v[22:25]
	v_mfma_f32_16x16x32_bf16 v[14:17], v[146:149], v[208:211], v[14:17]
	v_mfma_f32_16x16x32_bf16 v[6:9], v[154:157], v[208:211], v[6:9]
	v_mfma_f32_16x16x32_bf16 v[62:65], v[150:153], v[182:185], v[62:65]
	v_mfma_f32_16x16x32_bf16 v[54:57], v[158:161], v[182:185], v[54:57]
	v_mfma_f32_16x16x32_bf16 v[46:49], v[150:153], v[190:193], v[46:49]
	v_mfma_f32_16x16x32_bf16 v[38:41], v[158:161], v[190:193], v[38:41]
	v_mfma_f32_16x16x32_bf16 v[30:33], v[150:153], v[198:201], v[30:33]
	v_mfma_f32_16x16x32_bf16 v[22:25], v[158:161], v[198:201], v[22:25]
	v_mfma_f32_16x16x32_bf16 v[14:17], v[150:153], v[212:215], v[14:17]
	v_mfma_f32_16x16x32_bf16 v[6:9], v[158:161], v[212:215], v[6:9]
	v_mfma_f32_16x16x32_bf16 v[58:61], v[162:165], v[178:181], v[58:61]
	v_mfma_f32_16x16x32_bf16 v[50:53], v[170:173], v[178:181], v[50:53]
	v_mfma_f32_16x16x32_bf16 v[42:45], v[162:165], v[186:189], v[42:45]
	v_mfma_f32_16x16x32_bf16 v[34:37], v[170:173], v[186:189], v[34:37]
	v_mfma_f32_16x16x32_bf16 v[26:29], v[162:165], v[194:197], v[26:29]
	v_mfma_f32_16x16x32_bf16 v[18:21], v[170:173], v[194:197], v[18:21]
	v_mfma_f32_16x16x32_bf16 v[10:13], v[162:165], v[208:211], v[10:13]
	v_mfma_f32_16x16x32_bf16 v[2:5], v[170:173], v[208:211], v[2:5]
	v_mfma_f32_16x16x32_bf16 v[58:61], v[166:169], v[182:185], v[58:61]
	v_mfma_f32_16x16x32_bf16 v[50:53], v[174:177], v[182:185], v[50:53]
	v_mfma_f32_16x16x32_bf16 v[42:45], v[166:169], v[190:193], v[42:45]
	v_mfma_f32_16x16x32_bf16 v[34:37], v[174:177], v[190:193], v[34:37]
	v_mfma_f32_16x16x32_bf16 v[26:29], v[166:169], v[198:201], v[26:29]
	v_mfma_f32_16x16x32_bf16 v[18:21], v[174:177], v[198:201], v[18:21]
	v_mfma_f32_16x16x32_bf16 v[10:13], v[166:169], v[212:215], v[10:13]
	v_mfma_f32_16x16x32_bf16 v[2:5], v[174:177], v[212:215], v[2:5]
	s_barrier
	s_setprio 0
	s_add_i32 s61, s61, 2
	s_add_u32 s28, s28, 0x100
	s_addc_u32 s29, s29, 0
	s_add_u32 s59, s59, 0x100
	s_addc_u32 s60, s60, 0
	s_cmp_gt_u32 s61, 29
	s_cbranch_scc0 .LBB0_1594
	s_and_b64 vcc, exec, s[14:15]
	s_cbranch_vccz .LBB0_1597
	s_barrier

.LBB0_1717:
	s_add_u32 s49, s18, 0x100
	v_mov_b32_e32 v2, 0
	s_addc_u32 s58, s19, 0
	s_mov_b32 s59, -2
	v_mov_b32_e32 v3, v2
	v_pk_mov_b32 v[4:5], v[2:3], v[2:3] op_sel:[0,1]
	v_pk_mov_b32 v[6:7], v[2:3], v[2:3] op_sel:[0,1]
	v_pk_mov_b32 v[8:9], v[2:3], v[2:3] op_sel:[0,1]
	v_pk_mov_b32 v[18:19], v[2:3], v[2:3] op_sel:[0,1]
	v_pk_mov_b32 v[20:21], v[2:3], v[2:3] op_sel:[0,1]
	v_pk_mov_b32 v[22:23], v[2:3], v[2:3] op_sel:[0,1]
	v_pk_mov_b32 v[24:25], v[2:3], v[2:3] op_sel:[0,1]
	v_pk_mov_b32 v[34:35], v[2:3], v[2:3] op_sel:[0,1]
	v_pk_mov_b32 v[36:37], v[2:3], v[2:3] op_sel:[0,1]
	v_pk_mov_b32 v[38:39], v[2:3], v[2:3] op_sel:[0,1]
	v_pk_mov_b32 v[40:41], v[2:3], v[2:3] op_sel:[0,1]
	v_pk_mov_b32 v[50:51], v[2:3], v[2:3] op_sel:[0,1]
	v_pk_mov_b32 v[52:53], v[2:3], v[2:3] op_sel:[0,1]
	v_pk_mov_b32 v[54:55], v[2:3], v[2:3] op_sel:[0,1]
	v_pk_mov_b32 v[56:57], v[2:3], v[2:3] op_sel:[0,1]
	v_pk_mov_b32 v[10:11], v[2:3], v[2:3] op_sel:[0,1]
	v_pk_mov_b32 v[12:13], v[2:3], v[2:3] op_sel:[0,1]
	v_pk_mov_b32 v[14:15], v[2:3], v[2:3] op_sel:[0,1]
	v_pk_mov_b32 v[16:17], v[2:3], v[2:3] op_sel:[0,1]
	v_pk_mov_b32 v[26:27], v[2:3], v[2:3] op_sel:[0,1]
	v_pk_mov_b32 v[28:29], v[2:3], v[2:3] op_sel:[0,1]
	v_pk_mov_b32 v[30:31], v[2:3], v[2:3] op_sel:[0,1]
	v_pk_mov_b32 v[32:33], v[2:3], v[2:3] op_sel:[0,1]
	v_pk_mov_b32 v[42:43], v[2:3], v[2:3] op_sel:[0,1]
	v_pk_mov_b32 v[44:45], v[2:3], v[2:3] op_sel:[0,1]
	v_pk_mov_b32 v[46:47], v[2:3], v[2:3] op_sel:[0,1]
	v_pk_mov_b32 v[48:49], v[2:3], v[2:3] op_sel:[0,1]
	v_pk_mov_b32 v[58:59], v[2:3], v[2:3] op_sel:[0,1]
	v_pk_mov_b32 v[60:61], v[2:3], v[2:3] op_sel:[0,1]
	v_pk_mov_b32 v[62:63], v[2:3], v[2:3] op_sel:[0,1]
	v_pk_mov_b32 v[64:65], v[2:3], v[2:3] op_sel:[0,1]
	v_pk_mov_b32 v[66:67], v[2:3], v[2:3] op_sel:[0,1]
	v_pk_mov_b32 v[68:69], v[2:3], v[2:3] op_sel:[0,1]
	v_pk_mov_b32 v[70:71], v[2:3], v[2:3] op_sel:[0,1]
	v_pk_mov_b32 v[72:73], v[2:3], v[2:3] op_sel:[0,1]
	v_pk_mov_b32 v[90:91], v[2:3], v[2:3] op_sel:[0,1]
	v_pk_mov_b32 v[92:93], v[2:3], v[2:3] op_sel:[0,1]
	v_pk_mov_b32 v[102:103], v[2:3], v[2:3] op_sel:[0,1]
	v_pk_mov_b32 v[104:105], v[2:3], v[2:3] op_sel:[0,1]
	v_pk_mov_b32 v[122:123], v[2:3], v[2:3] op_sel:[0,1]
	v_pk_mov_b32 v[124:125], v[2:3], v[2:3] op_sel:[0,1]
	v_pk_mov_b32 v[130:131], v[2:3], v[2:3] op_sel:[0,1]
	v_pk_mov_b32 v[132:133], v[2:3], v[2:3] op_sel:[0,1]
	v_pk_mov_b32 v[150:151], v[2:3], v[2:3] op_sel:[0,1]
	v_pk_mov_b32 v[152:153], v[2:3], v[2:3] op_sel:[0,1]
	v_pk_mov_b32 v[154:155], v[2:3], v[2:3] op_sel:[0,1]
	v_pk_mov_b32 v[156:157], v[2:3], v[2:3] op_sel:[0,1]
	v_pk_mov_b32 v[74:75], v[2:3], v[2:3] op_sel:[0,1]
	v_pk_mov_b32 v[76:77], v[2:3], v[2:3] op_sel:[0,1]
	v_pk_mov_b32 v[86:87], v[2:3], v[2:3] op_sel:[0,1]
	v_pk_mov_b32 v[88:89], v[2:3], v[2:3] op_sel:[0,1]
	v_pk_mov_b32 v[114:115], v[2:3], v[2:3] op_sel:[0,1]
	v_pk_mov_b32 v[116:117], v[2:3], v[2:3] op_sel:[0,1]
	v_pk_mov_b32 v[118:119], v[2:3], v[2:3] op_sel:[0,1]
	v_pk_mov_b32 v[120:121], v[2:3], v[2:3] op_sel:[0,1]
	v_pk_mov_b32 v[138:139], v[2:3], v[2:3] op_sel:[0,1]
	v_pk_mov_b32 v[140:141], v[2:3], v[2:3] op_sel:[0,1]
	v_pk_mov_b32 v[142:143], v[2:3], v[2:3] op_sel:[0,1]
	v_pk_mov_b32 v[144:145], v[2:3], v[2:3] op_sel:[0,1]
	v_pk_mov_b32 v[162:163], v[2:3], v[2:3] op_sel:[0,1]
	v_pk_mov_b32 v[164:165], v[2:3], v[2:3] op_sel:[0,1]
	v_pk_mov_b32 v[170:171], v[2:3], v[2:3] op_sel:[0,1]
	v_pk_mov_b32 v[172:173], v[2:3], v[2:3] op_sel:[0,1]
	.p2align 6
.LBB0_1718:
	s_add_u32 s18, s4, 0x100
	s_addc_u32 s19, s5, 0
	s_add_i32 s0, 0, 0x10000
	s_cmpk_eq_i32 s59, 0x54
	s_cselect_b32 s23, s9, s19
	s_cselect_b32 s22, s8, s18
	s_cselect_b32 s21, s17, s58
	s_cselect_b32 s20, s16, s49
	s_add_i32 s33, 0, 0x14000
	ds_read_b128 v[78:81], v205
	ds_read_b128 v[82:85], v205 offset:1024
	ds_read_b128 v[94:97], v205 offset:2048
	ds_read_b128 v[98:101], v205 offset:3072
	ds_read_b128 v[106:109], v205 offset:16384
	ds_read_b128 v[110:113], v205 offset:17408
	ds_read_b128 v[126:129], v205 offset:18432
	ds_read_b128 v[134:137], v205 offset:19456
	s_add_i32 m0, s27, 0xc000
	ds_read_b128 v[146:149], v239
	ds_read_b128 v[158:161], v239 offset:1024
	ds_read_b128 v[166:169], v239 offset:2048
	ds_read_b128 v[174:177], v239 offset:3072
	ds_read_b128 v[178:181], v239 offset:4096
	ds_read_b128 v[182:185], v239 offset:5120
	ds_read_b128 v[186:189], v239 offset:6144
	ds_read_b128 v[190:193], v239 offset:7168
	global_load_lds_dwordx4 v214, s[4:5]
	s_add_i32 m0, s27, 0xe000
	s_nop 0
	global_load_lds_dwordx4 v216, s[4:5]
	.p2align 3
	s_waitcnt vmcnt(8)
	s_waitcnt lgkmcnt(0)
	s_setprio 1
	s_barrier
	v_mfma_f32_16x16x32_bf16 v[170:173], v[78:81], v[146:149], v[170:173]
	v_mfma_f32_16x16x32_bf16 v[162:165], v[94:97], v[146:149], v[162:165]
	v_mfma_f32_16x16x32_bf16 v[142:145], v[78:81], v[166:169], v[142:145]
	v_mfma_f32_16x16x32_bf16 v[138:141], v[94:97], v[166:169], v[138:141]
	v_mfma_f32_16x16x32_bf16 v[118:121], v[78:81], v[178:181], v[118:121]
	v_mfma_f32_16x16x32_bf16 v[114:117], v[94:97], v[178:181], v[114:117]
	v_mfma_f32_16x16x32_bf16 v[86:89], v[78:81], v[186:189], v[86:89]
	v_mfma_f32_16x16x32_bf16 v[74:77], v[94:97], v[186:189], v[74:77]
	v_mfma_f32_16x16x32_bf16 v[170:173], v[82:85], v[158:161], v[170:173]
	v_mfma_f32_16x16x32_bf16 v[162:165], v[98:101], v[158:161], v[162:165]
	v_mfma_f32_16x16x32_bf16 v[142:145], v[82:85], v[174:177], v[142:145]
	v_mfma_f32_16x16x32_bf16 v[138:141], v[98:101], v[174:177], v[138:141]
	v_mfma_f32_16x16x32_bf16 v[118:121], v[82:85], v[182:185], v[118:121]
	v_mfma_f32_16x16x32_bf16 v[114:117], v[98:101], v[182:185], v[114:117]
	v_mfma_f32_16x16x32_bf16 v[86:89], v[82:85], v[190:193], v[86:89]
	v_mfma_f32_16x16x32_bf16 v[74:77], v[98:101], v[190:193], v[74:77]
	v_mfma_f32_16x16x32_bf16 v[154:157], v[106:109], v[146:149], v[154:157]
	v_mfma_f32_16x16x32_bf16 v[130:133], v[106:109], v[166:169], v[130:133]
	v_mfma_f32_16x16x32_bf16 v[122:125], v[126:129], v[166:169], v[122:125]
	v_mfma_f32_16x16x32_bf16 v[102:105], v[106:109], v[178:181], v[102:105]
	v_mfma_f32_16x16x32_bf16 v[90:93], v[126:129], v[178:181], v[90:93]
	v_mfma_f32_16x16x32_bf16 v[70:73], v[106:109], v[186:189], v[70:73]
	v_mfma_f32_16x16x32_bf16 v[66:69], v[126:129], v[186:189], v[66:69]
	v_mfma_f32_16x16x32_bf16 v[154:157], v[110:113], v[158:161], v[154:157]
	v_mfma_f32_16x16x32_bf16 v[146:149], v[126:129], v[146:149], v[150:153]
	v_mfma_f32_16x16x32_bf16 v[130:133], v[110:113], v[174:177], v[130:133]
	v_mfma_f32_16x16x32_bf16 v[122:125], v[134:137], v[174:177], v[122:125]
	v_mfma_f32_16x16x32_bf16 v[102:105], v[110:113], v[182:185], v[102:105]
	v_mfma_f32_16x16x32_bf16 v[90:93], v[134:137], v[182:185], v[90:93]
	v_mfma_f32_16x16x32_bf16 v[70:73], v[110:113], v[190:193], v[70:73]
	v_mfma_f32_16x16x32_bf16 v[66:69], v[134:137], v[190:193], v[66:69]
	v_mfma_f32_16x16x32_bf16 v[146:149], v[134:137], v[158:161], v[146:149]
	s_barrier
	s_setprio 0
	s_add_i32 s0, s0, s26
	s_mov_b32 m0, s0
	ds_read_b128 v[150:153], v239 offset:16384
	ds_read_b128 v[158:161], v239 offset:17408
	ds_read_b128 v[166:169], v239 offset:18432
	ds_read_b128 v[174:177], v239 offset:19456
	ds_read_b128 v[178:181], v239 offset:20480
	ds_read_b128 v[182:185], v239 offset:21504
	ds_read_b128 v[186:189], v239 offset:22528
	ds_read_b128 v[190:193], v239 offset:23552
	global_load_lds_dwordx4 v202, s[20:21]
	s_add_i32 m0, s0, 0x2000
	s_add_u32 s0, s20, 0x160000
	s_addc_u32 s1, s21, 0
	s_add_i32 s4, s33, s26
	global_load_lds_dwordx4 v208, s[20:21]
	s_mov_b32 m0, s4
	s_nop 0
	global_load_lds_dwordx4 v202, s[0:1]
	s_add_i32 m0, s4, 0x2000
	s_nop 0
	global_load_lds_dwordx4 v208, s[0:1]
	s_mov_b32 m0, s27
	s_nop 0
	global_load_lds_dwordx4 v212, s[22:23]
	s_mov_b32 m0, s28
	s_nop 0
	global_load_lds_dwordx4 v210, s[22:23]
	.p2align 3
	s_waitcnt vmcnt(8)
	s_waitcnt lgkmcnt(0)
	s_setprio 1
	s_barrier
	v_mfma_f32_16x16x32_bf16 v[62:65], v[78:81], v[150:153], v[62:65]
	v_mfma_f32_16x16x32_bf16 v[58:61], v[94:97], v[150:153], v[58:61]
	v_mfma_f32_16x16x32_bf16 v[46:49], v[78:81], v[166:169], v[46:49]
	v_mfma_f32_16x16x32_bf16 v[42:45], v[94:97], v[166:169], v[42:45]
	v_mfma_f32_16x16x32_bf16 v[30:33], v[78:81], v[178:181], v[30:33]
	v_mfma_f32_16x16x32_bf16 v[26:29], v[94:97], v[178:181], v[26:29]
	v_mfma_f32_16x16x32_bf16 v[14:17], v[78:81], v[186:189], v[14:17]
	v_mfma_f32_16x16x32_bf16 v[10:13], v[94:97], v[186:189], v[10:13]
	v_mfma_f32_16x16x32_bf16 v[62:65], v[82:85], v[158:161], v[62:65]
	v_mfma_f32_16x16x32_bf16 v[58:61], v[98:101], v[158:161], v[58:61]
	v_mfma_f32_16x16x32_bf16 v[46:49], v[82:85], v[174:177], v[46:49]
	v_mfma_f32_16x16x32_bf16 v[42:45], v[98:101], v[174:177], v[42:45]
	v_mfma_f32_16x16x32_bf16 v[30:33], v[82:85], v[182:185], v[30:33]
	v_mfma_f32_16x16x32_bf16 v[26:29], v[98:101], v[182:185], v[26:29]
	v_mfma_f32_16x16x32_bf16 v[14:17], v[82:85], v[190:193], v[14:17]
	v_mfma_f32_16x16x32_bf16 v[10:13], v[98:101], v[190:193], v[10:13]
	v_mfma_f32_16x16x32_bf16 v[54:57], v[106:109], v[150:153], v[54:57]
	v_mfma_f32_16x16x32_bf16 v[50:53], v[126:129], v[150:153], v[50:53]
	v_mfma_f32_16x16x32_bf16 v[38:41], v[106:109], v[166:169], v[38:41]
	v_mfma_f32_16x16x32_bf16 v[34:37], v[126:129], v[166:169], v[34:37]
	v_mfma_f32_16x16x32_bf16 v[22:25], v[106:109], v[178:181], v[22:25]
	v_mfma_f32_16x16x32_bf16 v[18:21], v[126:129], v[178:181], v[18:21]
	v_mfma_f32_16x16x32_bf16 v[6:9], v[106:109], v[186:189], v[6:9]
	v_mfma_f32_16x16x32_bf16 v[2:5], v[126:129], v[186:189], v[2:5]
	v_mfma_f32_16x16x32_bf16 v[54:57], v[110:113], v[158:161], v[54:57]
	v_mfma_f32_16x16x32_bf16 v[50:53], v[134:137], v[158:161], v[50:53]
	v_mfma_f32_16x16x32_bf16 v[38:41], v[110:113], v[174:177], v[38:41]
	v_mfma_f32_16x16x32_bf16 v[34:37], v[134:137], v[174:177], v[34:37]
	v_mfma_f32_16x16x32_bf16 v[22:25], v[110:113], v[182:185], v[22:25]
	v_mfma_f32_16x16x32_bf16 v[18:21], v[134:137], v[182:185], v[18:21]
	v_mfma_f32_16x16x32_bf16 v[6:9], v[110:113], v[190:193], v[6:9]
	v_mfma_f32_16x16x32_bf16 v[2:5], v[134:137], v[190:193], v[2:5]
	s_barrier
	s_setprio 0
	s_add_i32 s4, 0, 0x18000
	s_add_i32 s5, 0, 0x1c000
	ds_read_b128 v[78:81], v205 offset:32768
	ds_read_b128 v[82:85], v205 offset:33792
	ds_read_b128 v[94:97], v205 offset:34816
	ds_read_b128 v[98:101], v205 offset:35840
	ds_read_b128 v[106:109], v205 offset:49152
	ds_read_b128 v[110:113], v205 offset:50176
	ds_read_b128 v[126:129], v205 offset:51200
	ds_read_b128 v[134:137], v205 offset:52224
	s_add_u32 s0, s22, 0x160000
	s_addc_u32 s1, s23, 0
	s_mov_b32 m0, s29
	ds_read_b128 v[150:153], v239 offset:32768
	ds_read_b128 v[158:161], v239 offset:33792
	ds_read_b128 v[166:169], v239 offset:34816
	ds_read_b128 v[174:177], v239 offset:35840
	ds_read_b128 v[178:181], v239 offset:36864
	ds_read_b128 v[182:185], v239 offset:37888
	ds_read_b128 v[186:189], v239 offset:38912
	ds_read_b128 v[190:193], v239 offset:39936
	global_load_lds_dwordx4 v212, s[0:1]
	s_mov_b32 m0, s30
	s_nop 0
	global_load_lds_dwordx4 v210, s[0:1]
	.p2align 3
	s_waitcnt vmcnt(8)
	s_waitcnt lgkmcnt(0)
	s_setprio 1
	s_barrier
	v_mfma_f32_16x16x32_bf16 v[170:173], v[78:81], v[150:153], v[170:173]
	v_mfma_f32_16x16x32_bf16 v[162:165], v[94:97], v[150:153], v[162:165]
	v_mfma_f32_16x16x32_bf16 v[142:145], v[78:81], v[166:169], v[142:145]
	v_mfma_f32_16x16x32_bf16 v[138:141], v[94:97], v[166:169], v[138:141]
	v_mfma_f32_16x16x32_bf16 v[118:121], v[78:81], v[178:181], v[118:121]
	v_mfma_f32_16x16x32_bf16 v[114:117], v[94:97], v[178:181], v[114:117]
	v_mfma_f32_16x16x32_bf16 v[86:89], v[78:81], v[186:189], v[86:89]
	v_mfma_f32_16x16x32_bf16 v[74:77], v[94:97], v[186:189], v[74:77]
	v_mfma_f32_16x16x32_bf16 v[170:173], v[82:85], v[158:161], v[170:173]
	v_mfma_f32_16x16x32_bf16 v[162:165], v[98:101], v[158:161], v[162:165]
	v_mfma_f32_16x16x32_bf16 v[142:145], v[82:85], v[174:177], v[142:145]
	v_mfma_f32_16x16x32_bf16 v[138:141], v[98:101], v[174:177], v[138:141]
	v_mfma_f32_16x16x32_bf16 v[118:121], v[82:85], v[182:185], v[118:121]
	v_mfma_f32_16x16x32_bf16 v[114:117], v[98:101], v[182:185], v[114:117]
	v_mfma_f32_16x16x32_bf16 v[86:89], v[82:85], v[190:193], v[86:89]
	v_mfma_f32_16x16x32_bf16 v[74:77], v[98:101], v[190:193], v[74:77]
	v_mfma_f32_16x16x32_bf16 v[154:157], v[106:109], v[150:153], v[154:157]
	v_mfma_f32_16x16x32_bf16 v[146:149], v[126:129], v[150:153], v[146:149]
	v_mfma_f32_16x16x32_bf16 v[130:133], v[106:109], v[166:169], v[130:133]
	v_mfma_f32_16x16x32_bf16 v[122:125], v[126:129], v[166:169], v[122:125]
	v_mfma_f32_16x16x32_bf16 v[102:105], v[106:109], v[178:181], v[102:105]
	v_mfma_f32_16x16x32_bf16 v[90:93], v[126:129], v[178:181], v[90:93]
	v_mfma_f32_16x16x32_bf16 v[70:73], v[106:109], v[186:189], v[70:73]
	v_mfma_f32_16x16x32_bf16 v[66:69], v[126:129], v[186:189], v[66:69]
	v_mfma_f32_16x16x32_bf16 v[154:157], v[110:113], v[158:161], v[154:157]
	v_mfma_f32_16x16x32_bf16 v[150:153], v[134:137], v[158:161], v[146:149]
	v_mfma_f32_16x16x32_bf16 v[130:133], v[110:113], v[174:177], v[130:133]
	v_mfma_f32_16x16x32_bf16 v[122:125], v[134:137], v[174:177], v[122:125]
	v_mfma_f32_16x16x32_bf16 v[102:105], v[110:113], v[182:185], v[102:105]
	v_mfma_f32_16x16x32_bf16 v[90:93], v[134:137], v[182:185], v[90:93]
	v_mfma_f32_16x16x32_bf16 v[70:73], v[110:113], v[190:193], v[70:73]
	v_mfma_f32_16x16x32_bf16 v[66:69], v[134:137], v[190:193], v[66:69]
	s_barrier
	s_setprio 0
	s_add_i32 s0, s4, s26
	s_add_u32 s100, s20, 0x80
	s_addc_u32 s101, s21, 0
	s_mov_b32 m0, s0
	ds_read_b128 v[146:149], v239 offset:49152
	ds_read_b128 v[158:161], v239 offset:50176
	ds_read_b128 v[166:169], v239 offset:51200
	ds_read_b128 v[174:177], v239 offset:52224
	ds_read_b128 v[178:181], v239 offset:53248
	ds_read_b128 v[182:185], v239 offset:54272
	ds_read_b128 v[186:189], v239 offset:55296
	ds_read_b128 v[190:193], v239 offset:56320
	global_load_lds_dwordx4 v202, s[100:101]
	s_add_i32 m0, s0, 0x2000
	s_add_u32 s100, s20, 0x80
	s_addc_u32 s101, s21, 0
	s_add_u32 s0, s20, 0x160080
	s_addc_u32 s1, s21, 0
	s_add_i32 s4, s5, s26
	global_load_lds_dwordx4 v208, s[100:101]
	s_mov_b32 m0, s4
	s_nop 0
	global_load_lds_dwordx4 v202, s[0:1]
	s_add_i32 m0, s4, 0x2000
	s_nop 0
	global_load_lds_dwordx4 v208, s[0:1]
	s_add_u32 s100, s22, 0x80
	s_addc_u32 s101, s23, 0
	s_mov_b32 m0, s35
	s_nop 0
	global_load_lds_dwordx4 v212, s[100:101]
	s_add_u32 s100, s22, 0x80
	s_addc_u32 s101, s23, 0
	s_mov_b32 m0, s36
	s_nop 0
	global_load_lds_dwordx4 v210, s[100:101]
	.p2align 3
	s_waitcnt vmcnt(8)
	s_waitcnt lgkmcnt(0)
	s_setprio 1
	s_barrier
	v_mfma_f32_16x16x32_bf16 v[62:65], v[78:81], v[146:149], v[62:65]
	v_mfma_f32_16x16x32_bf16 v[58:61], v[94:97], v[146:149], v[58:61]
	v_mfma_f32_16x16x32_bf16 v[46:49], v[78:81], v[166:169], v[46:49]
	v_mfma_f32_16x16x32_bf16 v[42:45], v[94:97], v[166:169], v[42:45]
	v_mfma_f32_16x16x32_bf16 v[30:33], v[78:81], v[178:181], v[30:33]
	v_mfma_f32_16x16x32_bf16 v[26:29], v[94:97], v[178:181], v[26:29]
	v_mfma_f32_16x16x32_bf16 v[14:17], v[78:81], v[186:189], v[14:17]
	v_mfma_f32_16x16x32_bf16 v[10:13], v[94:97], v[186:189], v[10:13]
	v_mfma_f32_16x16x32_bf16 v[62:65], v[82:85], v[158:161], v[62:65]
	v_mfma_f32_16x16x32_bf16 v[58:61], v[98:101], v[158:161], v[58:61]
	v_mfma_f32_16x16x32_bf16 v[46:49], v[82:85], v[174:177], v[46:49]
	v_mfma_f32_16x16x32_bf16 v[42:45], v[98:101], v[174:177], v[42:45]
	v_mfma_f32_16x16x32_bf16 v[30:33], v[82:85], v[182:185], v[30:33]
	v_mfma_f32_16x16x32_bf16 v[26:29], v[98:101], v[182:185], v[26:29]
	v_mfma_f32_16x16x32_bf16 v[14:17], v[82:85], v[190:193], v[14:17]
	v_mfma_f32_16x16x32_bf16 v[10:13], v[98:101], v[190:193], v[10:13]
	v_mfma_f32_16x16x32_bf16 v[54:57], v[106:109], v[146:149], v[54:57]
	v_mfma_f32_16x16x32_bf16 v[50:53], v[126:129], v[146:149], v[50:53]
	v_mfma_f32_16x16x32_bf16 v[38:41], v[106:109], v[166:169], v[38:41]
	v_mfma_f32_16x16x32_bf16 v[34:37], v[126:129], v[166:169], v[34:37]
	v_mfma_f32_16x16x32_bf16 v[22:25], v[106:109], v[178:181], v[22:25]
	v_mfma_f32_16x16x32_bf16 v[18:21], v[126:129], v[178:181], v[18:21]
	v_mfma_f32_16x16x32_bf16 v[6:9], v[106:109], v[186:189], v[6:9]
	v_mfma_f32_16x16x32_bf16 v[2:5], v[126:129], v[186:189], v[2:5]
	v_mfma_f32_16x16x32_bf16 v[54:57], v[110:113], v[158:161], v[54:57]
	v_mfma_f32_16x16x32_bf16 v[50:53], v[134:137], v[158:161], v[50:53]
	v_mfma_f32_16x16x32_bf16 v[38:41], v[110:113], v[174:177], v[38:41]
	v_mfma_f32_16x16x32_bf16 v[34:37], v[134:137], v[174:177], v[34:37]
	v_mfma_f32_16x16x32_bf16 v[22:25], v[110:113], v[182:185], v[22:25]
	v_mfma_f32_16x16x32_bf16 v[18:21], v[134:137], v[182:185], v[18:21]
	v_mfma_f32_16x16x32_bf16 v[6:9], v[110:113], v[190:193], v[6:9]
	v_mfma_f32_16x16x32_bf16 v[2:5], v[134:137], v[190:193], v[2:5]
	s_barrier
	s_setprio 0
	s_add_i32 s59, s59, 2
	s_add_u32 s49, s49, 0x100
	s_addc_u32 s58, s58, 0
	s_cmpk_gt_u32 s59, 0x55
	s_mov_b64 s[4:5], s[18:19]
	s_cbranch_scc0 .LBB0_1718
	s_and_b64 vcc, exec, s[14:15]
	s_cbranch_vccz .LBB0_1721
	s_barrier

.LBB0_1738:
	s_add_u32 s40, s16, 0x100
	v_mov_b32_e32 v2, 0
	s_addc_u32 s41, s17, 0
	s_mov_b32 s49, -2
	v_mov_b32_e32 v3, v2
	v_pk_mov_b32 v[4:5], v[2:3], v[2:3] op_sel:[0,1]
	v_pk_mov_b32 v[6:7], v[2:3], v[2:3] op_sel:[0,1]
	v_pk_mov_b32 v[8:9], v[2:3], v[2:3] op_sel:[0,1]
	v_pk_mov_b32 v[10:11], v[2:3], v[2:3] op_sel:[0,1]
	v_pk_mov_b32 v[12:13], v[2:3], v[2:3] op_sel:[0,1]
	v_pk_mov_b32 v[14:15], v[2:3], v[2:3] op_sel:[0,1]
	v_pk_mov_b32 v[16:17], v[2:3], v[2:3] op_sel:[0,1]
	v_pk_mov_b32 v[26:27], v[2:3], v[2:3] op_sel:[0,1]
	v_pk_mov_b32 v[28:29], v[2:3], v[2:3] op_sel:[0,1]
	v_pk_mov_b32 v[30:31], v[2:3], v[2:3] op_sel:[0,1]
	v_pk_mov_b32 v[32:33], v[2:3], v[2:3] op_sel:[0,1]
	v_pk_mov_b32 v[42:43], v[2:3], v[2:3] op_sel:[0,1]
	v_pk_mov_b32 v[44:45], v[2:3], v[2:3] op_sel:[0,1]
	v_pk_mov_b32 v[46:47], v[2:3], v[2:3] op_sel:[0,1]
	v_pk_mov_b32 v[48:49], v[2:3], v[2:3] op_sel:[0,1]
	v_pk_mov_b32 v[18:19], v[2:3], v[2:3] op_sel:[0,1]
	v_pk_mov_b32 v[20:21], v[2:3], v[2:3] op_sel:[0,1]
	v_pk_mov_b32 v[22:23], v[2:3], v[2:3] op_sel:[0,1]
	v_pk_mov_b32 v[24:25], v[2:3], v[2:3] op_sel:[0,1]
	v_pk_mov_b32 v[34:35], v[2:3], v[2:3] op_sel:[0,1]
	v_pk_mov_b32 v[36:37], v[2:3], v[2:3] op_sel:[0,1]
	v_pk_mov_b32 v[38:39], v[2:3], v[2:3] op_sel:[0,1]
	v_pk_mov_b32 v[40:41], v[2:3], v[2:3] op_sel:[0,1]
	v_pk_mov_b32 v[50:51], v[2:3], v[2:3] op_sel:[0,1]
	v_pk_mov_b32 v[52:53], v[2:3], v[2:3] op_sel:[0,1]
	v_pk_mov_b32 v[54:55], v[2:3], v[2:3] op_sel:[0,1]
	v_pk_mov_b32 v[56:57], v[2:3], v[2:3] op_sel:[0,1]
	v_pk_mov_b32 v[58:59], v[2:3], v[2:3] op_sel:[0,1]
	v_pk_mov_b32 v[60:61], v[2:3], v[2:3] op_sel:[0,1]
	v_pk_mov_b32 v[62:63], v[2:3], v[2:3] op_sel:[0,1]
	v_pk_mov_b32 v[64:65], v[2:3], v[2:3] op_sel:[0,1]
	v_pk_mov_b32 v[66:67], v[2:3], v[2:3] op_sel:[0,1]
	v_pk_mov_b32 v[68:69], v[2:3], v[2:3] op_sel:[0,1]
	v_pk_mov_b32 v[70:71], v[2:3], v[2:3] op_sel:[0,1]
	v_pk_mov_b32 v[72:73], v[2:3], v[2:3] op_sel:[0,1]
	v_pk_mov_b32 v[74:75], v[2:3], v[2:3] op_sel:[0,1]
	v_pk_mov_b32 v[76:77], v[2:3], v[2:3] op_sel:[0,1]
	v_pk_mov_b32 v[78:79], v[2:3], v[2:3] op_sel:[0,1]
	v_pk_mov_b32 v[80:81], v[2:3], v[2:3] op_sel:[0,1]
	v_pk_mov_b32 v[86:87], v[2:3], v[2:3] op_sel:[0,1]
	v_pk_mov_b32 v[88:89], v[2:3], v[2:3] op_sel:[0,1]
	v_pk_mov_b32 v[94:95], v[2:3], v[2:3] op_sel:[0,1]
	v_pk_mov_b32 v[96:97], v[2:3], v[2:3] op_sel:[0,1]
	v_pk_mov_b32 v[102:103], v[2:3], v[2:3] op_sel:[0,1]
	v_pk_mov_b32 v[104:105], v[2:3], v[2:3] op_sel:[0,1]
	v_pk_mov_b32 v[110:111], v[2:3], v[2:3] op_sel:[0,1]
	v_pk_mov_b32 v[112:113], v[2:3], v[2:3] op_sel:[0,1]
	v_pk_mov_b32 v[82:83], v[2:3], v[2:3] op_sel:[0,1]
	v_pk_mov_b32 v[84:85], v[2:3], v[2:3] op_sel:[0,1]
	v_pk_mov_b32 v[90:91], v[2:3], v[2:3] op_sel:[0,1]
	v_pk_mov_b32 v[92:93], v[2:3], v[2:3] op_sel:[0,1]
	v_pk_mov_b32 v[98:99], v[2:3], v[2:3] op_sel:[0,1]
	v_pk_mov_b32 v[100:101], v[2:3], v[2:3] op_sel:[0,1]
	v_pk_mov_b32 v[106:107], v[2:3], v[2:3] op_sel:[0,1]
	v_pk_mov_b32 v[108:109], v[2:3], v[2:3] op_sel:[0,1]
	v_pk_mov_b32 v[114:115], v[2:3], v[2:3] op_sel:[0,1]
	v_pk_mov_b32 v[116:117], v[2:3], v[2:3] op_sel:[0,1]
	v_pk_mov_b32 v[118:119], v[2:3], v[2:3] op_sel:[0,1]
	v_pk_mov_b32 v[120:121], v[2:3], v[2:3] op_sel:[0,1]
	v_pk_mov_b32 v[122:123], v[2:3], v[2:3] op_sel:[0,1]
	v_pk_mov_b32 v[124:125], v[2:3], v[2:3] op_sel:[0,1]
	v_pk_mov_b32 v[126:127], v[2:3], v[2:3] op_sel:[0,1]
	v_pk_mov_b32 v[128:129], v[2:3], v[2:3] op_sel:[0,1]
	.p2align 6
.LBB0_1739:
	s_add_u32 s16, s14, 0x100
	s_addc_u32 s17, s15, 0
	s_add_i32 s0, 0, 0x10000
	s_cmp_eq_u32 s49, 4
	s_cselect_b32 s21, s9, s17
	s_cselect_b32 s20, s8, s16
	s_cselect_b32 s19, s11, s41
	s_cselect_b32 s18, s10, s40
	s_add_i32 s33, 0, 0x14000
	ds_read_b128 v[140:143], v136
	ds_read_b128 v[144:147], v136 offset:1024
	ds_read_b128 v[148:151], v136 offset:2048
	ds_read_b128 v[152:155], v136 offset:3072
	ds_read_b128 v[156:159], v136 offset:16384
	ds_read_b128 v[160:163], v136 offset:17408
	ds_read_b128 v[164:167], v136 offset:18432
	ds_read_b128 v[168:171], v136 offset:19456
	s_add_i32 m0, s23, 0xc000
	ds_read_b128 v[172:175], v139
	ds_read_b128 v[176:179], v139 offset:1024
	ds_read_b128 v[180:183], v139 offset:2048
	ds_read_b128 v[184:187], v139 offset:3072
	ds_read_b128 v[188:191], v139 offset:4096
	ds_read_b128 v[192:195], v139 offset:5120
	ds_read_b128 v[196:199], v139 offset:6144
	ds_read_b128 v[208:211], v139 offset:7168
	global_load_lds_dwordx4 v132, s[14:15]
	s_add_i32 m0, s23, 0xe000
	s_nop 0
	global_load_lds_dwordx4 v134, s[14:15]
	.p2align 3
	s_waitcnt vmcnt(8)
	s_waitcnt lgkmcnt(0)
	s_setprio 1
	s_barrier
	v_mfma_f32_16x16x32_bf16 v[126:129], v[140:143], v[172:175], v[126:129]
	v_mfma_f32_16x16x32_bf16 v[122:125], v[148:151], v[172:175], v[122:125]
	v_mfma_f32_16x16x32_bf16 v[118:121], v[140:143], v[180:183], v[118:121]
	v_mfma_f32_16x16x32_bf16 v[114:117], v[148:151], v[180:183], v[114:117]
	v_mfma_f32_16x16x32_bf16 v[106:109], v[140:143], v[188:191], v[106:109]
	v_mfma_f32_16x16x32_bf16 v[98:101], v[148:151], v[188:191], v[98:101]
	v_mfma_f32_16x16x32_bf16 v[90:93], v[140:143], v[196:199], v[90:93]
	v_mfma_f32_16x16x32_bf16 v[82:85], v[148:151], v[196:199], v[82:85]
	v_mfma_f32_16x16x32_bf16 v[126:129], v[144:147], v[176:179], v[126:129]
	v_mfma_f32_16x16x32_bf16 v[122:125], v[152:155], v[176:179], v[122:125]
	v_mfma_f32_16x16x32_bf16 v[118:121], v[144:147], v[184:187], v[118:121]
	v_mfma_f32_16x16x32_bf16 v[114:117], v[152:155], v[184:187], v[114:117]
	v_mfma_f32_16x16x32_bf16 v[106:109], v[144:147], v[192:195], v[106:109]
	v_mfma_f32_16x16x32_bf16 v[98:101], v[152:155], v[192:195], v[98:101]
	v_mfma_f32_16x16x32_bf16 v[90:93], v[144:147], v[208:211], v[90:93]
	v_mfma_f32_16x16x32_bf16 v[82:85], v[152:155], v[208:211], v[82:85]
	v_mfma_f32_16x16x32_bf16 v[110:113], v[156:159], v[172:175], v[110:113]
	v_mfma_f32_16x16x32_bf16 v[102:105], v[164:167], v[172:175], v[102:105]
	v_mfma_f32_16x16x32_bf16 v[94:97], v[156:159], v[180:183], v[94:97]
	v_mfma_f32_16x16x32_bf16 v[86:89], v[164:167], v[180:183], v[86:89]
	v_mfma_f32_16x16x32_bf16 v[78:81], v[156:159], v[188:191], v[78:81]
	v_mfma_f32_16x16x32_bf16 v[74:77], v[164:167], v[188:191], v[74:77]
	v_mfma_f32_16x16x32_bf16 v[70:73], v[156:159], v[196:199], v[70:73]
	v_mfma_f32_16x16x32_bf16 v[66:69], v[164:167], v[196:199], v[66:69]
	v_mfma_f32_16x16x32_bf16 v[110:113], v[160:163], v[176:179], v[110:113]
	v_mfma_f32_16x16x32_bf16 v[102:105], v[168:171], v[176:179], v[102:105]
	v_mfma_f32_16x16x32_bf16 v[94:97], v[160:163], v[184:187], v[94:97]
	v_mfma_f32_16x16x32_bf16 v[86:89], v[168:171], v[184:187], v[86:89]
	v_mfma_f32_16x16x32_bf16 v[78:81], v[160:163], v[192:195], v[78:81]
	v_mfma_f32_16x16x32_bf16 v[74:77], v[168:171], v[192:195], v[74:77]
	v_mfma_f32_16x16x32_bf16 v[70:73], v[160:163], v[208:211], v[70:73]
	v_mfma_f32_16x16x32_bf16 v[66:69], v[168:171], v[208:211], v[66:69]
	s_barrier
	s_setprio 0
	s_add_i32 s0, s0, s22
	s_mov_b32 m0, s0
	ds_read_b128 v[172:175], v139 offset:16384
	ds_read_b128 v[176:179], v139 offset:17408
	ds_read_b128 v[180:183], v139 offset:18432
	ds_read_b128 v[184:187], v139 offset:19456
	ds_read_b128 v[188:191], v139 offset:20480
	ds_read_b128 v[192:195], v139 offset:21504
	ds_read_b128 v[196:199], v139 offset:22528
	ds_read_b128 v[208:211], v139 offset:23552
	global_load_lds_dwordx4 v202, s[18:19]
	s_add_i32 m0, s0, 0x2000
	s_add_u32 s0, s18, 0x160000
	s_addc_u32 s1, s19, 0
	s_add_i32 s14, s33, s22
	global_load_lds_dwordx4 v130, s[18:19]
	s_mov_b32 m0, s14
	s_nop 0
	global_load_lds_dwordx4 v202, s[0:1]
	s_add_i32 m0, s14, 0x2000
	s_nop 0
	global_load_lds_dwordx4 v130, s[0:1]
	s_mov_b32 m0, s23
	s_nop 0
	global_load_lds_dwordx4 v202, s[20:21]
	s_mov_b32 m0, s26
	s_nop 0
	global_load_lds_dwordx4 v130, s[20:21]
	.p2align 3
	s_waitcnt vmcnt(8)
	s_waitcnt lgkmcnt(0)
	s_setprio 1
	s_barrier
	v_mfma_f32_16x16x32_bf16 v[62:65], v[140:143], v[172:175], v[62:65]
	v_mfma_f32_16x16x32_bf16 v[58:61], v[148:151], v[172:175], v[58:61]
	v_mfma_f32_16x16x32_bf16 v[54:57], v[140:143], v[180:183], v[54:57]
	v_mfma_f32_16x16x32_bf16 v[50:53], v[148:151], v[180:183], v[50:53]
	v_mfma_f32_16x16x32_bf16 v[38:41], v[140:143], v[188:191], v[38:41]
	v_mfma_f32_16x16x32_bf16 v[34:37], v[148:151], v[188:191], v[34:37]
	v_mfma_f32_16x16x32_bf16 v[22:25], v[140:143], v[196:199], v[22:25]
	v_mfma_f32_16x16x32_bf16 v[18:21], v[148:151], v[196:199], v[18:21]
	v_mfma_f32_16x16x32_bf16 v[62:65], v[144:147], v[176:179], v[62:65]
	v_mfma_f32_16x16x32_bf16 v[58:61], v[152:155], v[176:179], v[58:61]
	v_mfma_f32_16x16x32_bf16 v[54:57], v[144:147], v[184:187], v[54:57]
	v_mfma_f32_16x16x32_bf16 v[50:53], v[152:155], v[184:187], v[50:53]
	v_mfma_f32_16x16x32_bf16 v[38:41], v[144:147], v[192:195], v[38:41]
	v_mfma_f32_16x16x32_bf16 v[34:37], v[152:155], v[192:195], v[34:37]
	v_mfma_f32_16x16x32_bf16 v[22:25], v[144:147], v[208:211], v[22:25]
	v_mfma_f32_16x16x32_bf16 v[18:21], v[152:155], v[208:211], v[18:21]
	v_mfma_f32_16x16x32_bf16 v[46:49], v[156:159], v[172:175], v[46:49]
	v_mfma_f32_16x16x32_bf16 v[42:45], v[164:167], v[172:175], v[42:45]
	v_mfma_f32_16x16x32_bf16 v[30:33], v[156:159], v[180:183], v[30:33]
	v_mfma_f32_16x16x32_bf16 v[26:29], v[164:167], v[180:183], v[26:29]
	v_mfma_f32_16x16x32_bf16 v[14:17], v[156:159], v[188:191], v[14:17]
	v_mfma_f32_16x16x32_bf16 v[10:13], v[164:167], v[188:191], v[10:13]
	v_mfma_f32_16x16x32_bf16 v[6:9], v[156:159], v[196:199], v[6:9]
	v_mfma_f32_16x16x32_bf16 v[2:5], v[164:167], v[196:199], v[2:5]
	v_mfma_f32_16x16x32_bf16 v[46:49], v[160:163], v[176:179], v[46:49]
	v_mfma_f32_16x16x32_bf16 v[42:45], v[168:171], v[176:179], v[42:45]
	v_mfma_f32_16x16x32_bf16 v[30:33], v[160:163], v[184:187], v[30:33]
	v_mfma_f32_16x16x32_bf16 v[26:29], v[168:171], v[184:187], v[26:29]
	v_mfma_f32_16x16x32_bf16 v[14:17], v[160:163], v[192:195], v[14:17]
	v_mfma_f32_16x16x32_bf16 v[10:13], v[168:171], v[192:195], v[10:13]
	v_mfma_f32_16x16x32_bf16 v[6:9], v[160:163], v[208:211], v[6:9]
	v_mfma_f32_16x16x32_bf16 v[2:5], v[168:171], v[208:211], v[2:5]
	s_barrier
	s_setprio 0
	s_add_i32 s14, 0, 0x18000
	s_add_i32 s15, 0, 0x1c000
	ds_read_b128 v[140:143], v136 offset:32768
	ds_read_b128 v[144:147], v136 offset:33792
	ds_read_b128 v[148:151], v136 offset:34816
	ds_read_b128 v[152:155], v136 offset:35840
	ds_read_b128 v[156:159], v136 offset:49152
	ds_read_b128 v[160:163], v136 offset:50176
	ds_read_b128 v[164:167], v136 offset:51200
	ds_read_b128 v[168:171], v136 offset:52224
	s_add_u32 s0, s20, 0x160000
	s_addc_u32 s1, s21, 0
	s_mov_b32 m0, s27
	ds_read_b128 v[172:175], v139 offset:32768
	ds_read_b128 v[176:179], v139 offset:33792
	ds_read_b128 v[180:183], v139 offset:34816
	ds_read_b128 v[184:187], v139 offset:35840
	ds_read_b128 v[188:191], v139 offset:36864
	ds_read_b128 v[192:195], v139 offset:37888
	ds_read_b128 v[196:199], v139 offset:38912
	ds_read_b128 v[208:211], v139 offset:39936
	global_load_lds_dwordx4 v202, s[0:1]
	s_mov_b32 m0, s28
	s_nop 0
	global_load_lds_dwordx4 v130, s[0:1]
	.p2align 3
	s_waitcnt vmcnt(8)
	s_waitcnt lgkmcnt(0)
	s_setprio 1
	s_barrier
	v_mfma_f32_16x16x32_bf16 v[126:129], v[140:143], v[172:175], v[126:129]
	v_mfma_f32_16x16x32_bf16 v[122:125], v[148:151], v[172:175], v[122:125]
	v_mfma_f32_16x16x32_bf16 v[118:121], v[140:143], v[180:183], v[118:121]
	v_mfma_f32_16x16x32_bf16 v[114:117], v[148:151], v[180:183], v[114:117]
	v_mfma_f32_16x16x32_bf16 v[106:109], v[140:143], v[188:191], v[106:109]
	v_mfma_f32_16x16x32_bf16 v[98:101], v[148:151], v[188:191], v[98:101]
	v_mfma_f32_16x16x32_bf16 v[90:93], v[140:143], v[196:199], v[90:93]
	v_mfma_f32_16x16x32_bf16 v[82:85], v[148:151], v[196:199], v[82:85]
	v_mfma_f32_16x16x32_bf16 v[126:129], v[144:147], v[176:179], v[126:129]
	v_mfma_f32_16x16x32_bf16 v[122:125], v[152:155], v[176:179], v[122:125]
	v_mfma_f32_16x16x32_bf16 v[118:121], v[144:147], v[184:187], v[118:121]
	v_mfma_f32_16x16x32_bf16 v[114:117], v[152:155], v[184:187], v[114:117]
	v_mfma_f32_16x16x32_bf16 v[106:109], v[144:147], v[192:195], v[106:109]
	v_mfma_f32_16x16x32_bf16 v[98:101], v[152:155], v[192:195], v[98:101]
	v_mfma_f32_16x16x32_bf16 v[90:93], v[144:147], v[208:211], v[90:93]
	v_mfma_f32_16x16x32_bf16 v[82:85], v[152:155], v[208:211], v[82:85]
	v_mfma_f32_16x16x32_bf16 v[110:113], v[156:159], v[172:175], v[110:113]
	v_mfma_f32_16x16x32_bf16 v[102:105], v[164:167], v[172:175], v[102:105]
	v_mfma_f32_16x16x32_bf16 v[94:97], v[156:159], v[180:183], v[94:97]
	v_mfma_f32_16x16x32_bf16 v[86:89], v[164:167], v[180:183], v[86:89]
	v_mfma_f32_16x16x32_bf16 v[78:81], v[156:159], v[188:191], v[78:81]
	v_mfma_f32_16x16x32_bf16 v[74:77], v[164:167], v[188:191], v[74:77]
	v_mfma_f32_16x16x32_bf16 v[70:73], v[156:159], v[196:199], v[70:73]
	v_mfma_f32_16x16x32_bf16 v[66:69], v[164:167], v[196:199], v[66:69]
	v_mfma_f32_16x16x32_bf16 v[110:113], v[160:163], v[176:179], v[110:113]
	v_mfma_f32_16x16x32_bf16 v[102:105], v[168:171], v[176:179], v[102:105]
	v_mfma_f32_16x16x32_bf16 v[94:97], v[160:163], v[184:187], v[94:97]
	v_mfma_f32_16x16x32_bf16 v[86:89], v[168:171], v[184:187], v[86:89]
	v_mfma_f32_16x16x32_bf16 v[78:81], v[160:163], v[192:195], v[78:81]
	v_mfma_f32_16x16x32_bf16 v[74:77], v[168:171], v[192:195], v[74:77]
	v_mfma_f32_16x16x32_bf16 v[70:73], v[160:163], v[208:211], v[70:73]
	v_mfma_f32_16x16x32_bf16 v[66:69], v[168:171], v[208:211], v[66:69]
	s_barrier
	s_setprio 0
	s_add_i32 s0, s14, s22
	s_add_u32 s100, s18, 0x80
	s_addc_u32 s101, s19, 0
	s_mov_b32 m0, s0
	ds_read_b128 v[172:175], v139 offset:49152
	ds_read_b128 v[176:179], v139 offset:50176
	ds_read_b128 v[180:183], v139 offset:51200
	ds_read_b128 v[184:187], v139 offset:52224
	ds_read_b128 v[188:191], v139 offset:53248
	ds_read_b128 v[192:195], v139 offset:54272
	ds_read_b128 v[196:199], v139 offset:55296
	ds_read_b128 v[208:211], v139 offset:56320
	global_load_lds_dwordx4 v202, s[100:101]
	s_add_i32 m0, s0, 0x2000
	s_add_u32 s100, s18, 0x80
	s_addc_u32 s101, s19, 0
	s_add_u32 s0, s18, 0x160080
	s_addc_u32 s1, s19, 0
	s_add_i32 s14, s15, s22
	global_load_lds_dwordx4 v130, s[100:101]
	s_mov_b32 m0, s14
	s_nop 0
	global_load_lds_dwordx4 v202, s[0:1]
	s_add_i32 m0, s14, 0x2000
	s_nop 0
	global_load_lds_dwordx4 v130, s[0:1]
	s_add_u32 s100, s20, 0x80
	s_addc_u32 s101, s21, 0
	s_mov_b32 m0, s29
	s_nop 0
	global_load_lds_dwordx4 v202, s[100:101]
	s_add_u32 s100, s20, 0x80
	s_addc_u32 s101, s21, 0
	s_mov_b32 m0, s30
	s_nop 0
	global_load_lds_dwordx4 v130, s[100:101]
	.p2align 3
	s_waitcnt vmcnt(8)
	s_waitcnt lgkmcnt(0)
	s_setprio 1
	s_barrier
	v_mfma_f32_16x16x32_bf16 v[62:65], v[140:143], v[172:175], v[62:65]
	v_mfma_f32_16x16x32_bf16 v[58:61], v[148:151], v[172:175], v[58:61]
	v_mfma_f32_16x16x32_bf16 v[54:57], v[140:143], v[180:183], v[54:57]
	v_mfma_f32_16x16x32_bf16 v[50:53], v[148:151], v[180:183], v[50:53]
	v_mfma_f32_16x16x32_bf16 v[38:41], v[140:143], v[188:191], v[38:41]
	v_mfma_f32_16x16x32_bf16 v[34:37], v[148:151], v[188:191], v[34:37]
	v_mfma_f32_16x16x32_bf16 v[22:25], v[140:143], v[196:199], v[22:25]
	v_mfma_f32_16x16x32_bf16 v[18:21], v[148:151], v[196:199], v[18:21]
	v_mfma_f32_16x16x32_bf16 v[62:65], v[144:147], v[176:179], v[62:65]
	v_mfma_f32_16x16x32_bf16 v[58:61], v[152:155], v[176:179], v[58:61]
	v_mfma_f32_16x16x32_bf16 v[54:57], v[144:147], v[184:187], v[54:57]
	v_mfma_f32_16x16x32_bf16 v[50:53], v[152:155], v[184:187], v[50:53]
	v_mfma_f32_16x16x32_bf16 v[38:41], v[144:147], v[192:195], v[38:41]
	v_mfma_f32_16x16x32_bf16 v[34:37], v[152:155], v[192:195], v[34:37]
	v_mfma_f32_16x16x32_bf16 v[22:25], v[144:147], v[208:211], v[22:25]
	v_mfma_f32_16x16x32_bf16 v[18:21], v[152:155], v[208:211], v[18:21]
	v_mfma_f32_16x16x32_bf16 v[46:49], v[156:159], v[172:175], v[46:49]
	v_mfma_f32_16x16x32_bf16 v[42:45], v[164:167], v[172:175], v[42:45]
	v_mfma_f32_16x16x32_bf16 v[30:33], v[156:159], v[180:183], v[30:33]
	v_mfma_f32_16x16x32_bf16 v[26:29], v[164:167], v[180:183], v[26:29]
	v_mfma_f32_16x16x32_bf16 v[14:17], v[156:159], v[188:191], v[14:17]
	v_mfma_f32_16x16x32_bf16 v[10:13], v[164:167], v[188:191], v[10:13]
	v_mfma_f32_16x16x32_bf16 v[6:9], v[156:159], v[196:199], v[6:9]
	v_mfma_f32_16x16x32_bf16 v[2:5], v[164:167], v[196:199], v[2:5]
	v_mfma_f32_16x16x32_bf16 v[46:49], v[160:163], v[176:179], v[46:49]
	v_mfma_f32_16x16x32_bf16 v[42:45], v[168:171], v[176:179], v[42:45]
	v_mfma_f32_16x16x32_bf16 v[30:33], v[160:163], v[184:187], v[30:33]
	v_mfma_f32_16x16x32_bf16 v[26:29], v[168:171], v[184:187], v[26:29]
	v_mfma_f32_16x16x32_bf16 v[14:17], v[160:163], v[192:195], v[14:17]
	v_mfma_f32_16x16x32_bf16 v[10:13], v[168:171], v[192:195], v[10:13]
	v_mfma_f32_16x16x32_bf16 v[6:9], v[160:163], v[208:211], v[6:9]
	v_mfma_f32_16x16x32_bf16 v[2:5], v[168:171], v[208:211], v[2:5]
	s_barrier
	s_setprio 0
	s_add_i32 s49, s49, 2
	s_add_u32 s40, s40, 0x100
	s_addc_u32 s41, s41, 0
	s_cmp_gt_u32 s49, 5
	s_mov_b64 s[14:15], s[16:17]
	s_cbranch_scc0 .LBB0_1739
	s_and_b64 vcc, exec, s[6:7]
	s_cbranch_vccz .LBB0_1742
	s_barrier
